# prep+final phases: wave sums via DPP/permlane swaps (bit-identical) instead of ds_bpermute butterflies; GEMM K-loop: drop mid-block setprio pair, setprio before barrier, merged waits
# baseline (speedup 1.0000x reference)
; #define PG8_STAGE(bufoff, gbase, voff) do { _Pragma("unroll") for (int _i = 0; _i < 2; ++_i) \
;         asm volatile("s_mov_b32 m0, %0\n\ts_nop 0\n\tglobal_load_lds_dwordx4 %1, %2" :: "s"(ldsb + (unsigned)((bufoff) + _i * 8192)), "v"((voff)[_i]), "s"(gbase) : "m0", "memory"); } while (0)
; #define PG8_LDA(dst, b, h) do { _Pragma("unroll") for (int m = 0; m < 4; ++m) _Pragma("unroll") for (int k = 0; k < 2; ++k) dst[m][k] = *(const PG8_LAS bf16x8*)(lds + PG8_SA(b, h) + aoff + m * 2048 + k * 1024); } while (0)
; #define PG8_LDB(dst, b, h) do { _Pragma("unroll") for (int n = 0; n < 2; ++n) _Pragma("unroll") for (int k = 0; k < 2; ++k) dst[n][k] = *(const PG8_LAS bf16x8*)(lds + PG8_SB(b, h) + boff + n * 2048 + k * 1024); } while (0)
; #define PG8_MMA(ai, bj, At, Bt) do { __builtin_amdgcn_s_setprio(1); _Pragma("unroll") for (int m = 0; m < 4; ++m) _Pragma("unroll") for (int n = 0; n < 2; ++n) _Pragma("unroll") for (int k = 0; k < 2; ++k) \
;         acc[ai][bj][m][n] = __builtin_amdgcn_mfma_f32_16x16x32_bf16(Bt[n][k], At[m][k], acc[ai][bj][m][n], 0, 0, 0); __builtin_amdgcn_s_setprio(0); } while (0)
; #define PG8_WAIT_V(n) asm volatile("s_waitcnt vmcnt(" #n ")" ::: "memory")
; #define PG8_WAIT_L(n) asm volatile("s_waitcnt lgkmcnt(" #n ")" ::: "memory")
; #define PG8_BAR __builtin_amdgcn_s_barrier()
; #define PG8_SCHED __builtin_amdgcn_sched_barrier(0)
; template <class Epi, class Sched, bool ALIGN_EPI = false, bool SP2 = false>
; __device__ __forceinline__ void gemm_phase(PG8_LAS unsigned char* lds, const Gemm g, const Sched& S, const Epi& E, const int wv) {
;     ...
;             PG8_LDB(B0, 0, 0); PG8_LDB(B1, 0, 1); PG8_SCHED; PG8_LDA(At, 0, 0); PG8_STAGE(PG8_SA(1, 1), a1 + hstepA, voffA);
;             PG8_WAIT_V(8); PG8_WAIT_L(0); PG8_BAR; PG8_MMA(0, 0, At, B0); PG8_MMA(0, 1, At, B1); PG8_BAR; PG8_SCHED;
;             PG8_LDA(At, 0, 1); PG8_STAGE(PG8_SB(0, 0), b2, voffB); PG8_STAGE(PG8_SB(0, 1), b2 + hstepB, voffB); PG8_STAGE(PG8_SA(0, 0), a2, voffA);
;             PG8_WAIT_V(8); PG8_WAIT_L(0); PG8_BAR; PG8_MMA(1, 0, At, B0); PG8_MMA(1, 1, At, B1); PG8_BAR; PG8_SCHED;
.LBB0_268:
	ds_read_b128 v[80:83], v161
	ds_read_b128 v[84:87], v161 offset:1024
	ds_read_b128 v[88:91], v161 offset:2048
	ds_read_b128 v[92:95], v161 offset:3072
	ds_read_b128 v[166:169], v162
	ds_read_b128 v[170:173], v162 offset:1024
	ds_read_b128 v[174:177], v162 offset:2048
	ds_read_b128 v[178:181], v162 offset:3072
	s_add_i32 s84, s18, 2
	s_cmp_eq_u32 s71, s18
	s_cselect_b32 s22, s12, s72
	s_cselect_b32 s23, s13, s77
	s_cselect_b32 s20, s65, s79
	s_cselect_b32 s21, s62, s83
	s_add_u32 s18, s22, 0x80
	s_addc_u32 s19, s23, 0
	ds_read_b128 v[182:185], v163
	ds_read_b128 v[186:189], v163 offset:1024
	ds_read_b128 v[194:197], v163 offset:2048
	ds_read_b128 v[198:201], v163 offset:3072
	ds_read_b128 v[202:205], v163 offset:4096
	ds_read_b128 v[206:209], v163 offset:5120
	ds_read_b128 v[210:213], v163 offset:6144
	ds_read_b128 v[214:217], v163 offset:7168
	s_add_u32 s86, s72, 0x83f80
	s_addc_u32 s87, s77, 0
	s_mov_b32 m0, s51
	s_nop 0
	global_load_lds_dwordx4 v147, s[86:87]
	s_nop 0
	s_mov_b32 m0, s52
	s_nop 0
	global_load_lds_dwordx4 v151, s[86:87]
	s_waitcnt vmcnt(8) lgkmcnt(0)
	s_setprio 1
	s_barrier
	v_mfma_f32_16x16x32_bf16 v[140:143], v[80:83], v[182:185], v[140:143]
	v_mfma_f32_16x16x32_bf16 v[136:139], v[88:91], v[182:185], v[136:139]
	v_mfma_f32_16x16x32_bf16 v[124:127], v[80:83], v[194:197], v[124:127]
	v_mfma_f32_16x16x32_bf16 v[120:123], v[88:91], v[194:197], v[120:123]
	v_mfma_f32_16x16x32_bf16 v[108:111], v[80:83], v[202:205], v[108:111]
	v_mfma_f32_16x16x32_bf16 v[104:107], v[88:91], v[202:205], v[104:107]
	v_mfma_f32_16x16x32_bf16 v[76:79], v[80:83], v[210:213], v[76:79]
	v_mfma_f32_16x16x32_bf16 v[72:75], v[88:91], v[210:213], v[72:75]
	v_mfma_f32_16x16x32_bf16 v[140:143], v[84:87], v[186:189], v[140:143]
	v_mfma_f32_16x16x32_bf16 v[136:139], v[92:95], v[186:189], v[136:139]
	v_mfma_f32_16x16x32_bf16 v[124:127], v[84:87], v[198:201], v[124:127]
	v_mfma_f32_16x16x32_bf16 v[120:123], v[92:95], v[198:201], v[120:123]
	v_mfma_f32_16x16x32_bf16 v[108:111], v[84:87], v[206:209], v[108:111]
	v_mfma_f32_16x16x32_bf16 v[104:107], v[92:95], v[206:209], v[104:107]
	v_mfma_f32_16x16x32_bf16 v[76:79], v[84:87], v[214:217], v[76:79]
	v_mfma_f32_16x16x32_bf16 v[72:75], v[92:95], v[214:217], v[72:75]
	v_mfma_f32_16x16x32_bf16 v[132:135], v[166:169], v[182:185], v[132:135]
	v_mfma_f32_16x16x32_bf16 v[128:131], v[174:177], v[182:185], v[128:131]
	v_mfma_f32_16x16x32_bf16 v[116:119], v[166:169], v[194:197], v[116:119]
	v_mfma_f32_16x16x32_bf16 v[112:115], v[174:177], v[194:197], v[112:115]
	v_mfma_f32_16x16x32_bf16 v[100:103], v[166:169], v[202:205], v[100:103]
	v_mfma_f32_16x16x32_bf16 v[96:99], v[174:177], v[202:205], v[96:99]
	v_mfma_f32_16x16x32_bf16 v[68:71], v[166:169], v[210:213], v[68:71]
	v_mfma_f32_16x16x32_bf16 v[64:67], v[174:177], v[210:213], v[64:67]
	v_mfma_f32_16x16x32_bf16 v[132:135], v[170:173], v[186:189], v[132:135]
	v_mfma_f32_16x16x32_bf16 v[128:131], v[178:181], v[186:189], v[128:131]
	v_mfma_f32_16x16x32_bf16 v[116:119], v[170:173], v[198:201], v[116:119]
	v_mfma_f32_16x16x32_bf16 v[112:115], v[178:181], v[198:201], v[112:115]
	v_mfma_f32_16x16x32_bf16 v[100:103], v[170:173], v[206:209], v[100:103]
	v_mfma_f32_16x16x32_bf16 v[96:99], v[178:181], v[206:209], v[96:99]
	v_mfma_f32_16x16x32_bf16 v[68:71], v[170:173], v[214:217], v[68:71]
	v_mfma_f32_16x16x32_bf16 v[64:67], v[178:181], v[214:217], v[64:67]
	s_setprio 0
	s_barrier
	ds_read_b128 v[182:185], v163 offset:16384
	ds_read_b128 v[186:189], v163 offset:17408
	ds_read_b128 v[194:197], v163 offset:18432
	ds_read_b128 v[198:201], v163 offset:19456
	ds_read_b128 v[202:205], v163 offset:20480
	ds_read_b128 v[206:209], v163 offset:21504
	ds_read_b128 v[210:213], v163 offset:22528
	ds_read_b128 v[214:217], v163 offset:23552
	s_mov_b32 m0, s29
	s_nop 0
	global_load_lds_dwordx4 v149, s[20:21]
	s_add_u32 s86, s20, 0x80000
	s_mov_b32 m0, s30
	s_nop 0
	global_load_lds_dwordx4 v153, s[20:21]
	s_addc_u32 s87, s21, 0
	s_mov_b32 m0, s31
	s_nop 0
	global_load_lds_dwordx4 v149, s[86:87]
	s_nop 0
	s_mov_b32 m0, s33
	s_nop 0
	global_load_lds_dwordx4 v153, s[86:87]
	s_nop 0
	s_mov_b32 m0, s28
	s_nop 0
	global_load_lds_dwordx4 v147, s[22:23]
	s_nop 0
	s_mov_b32 m0, s34
	s_nop 0
	global_load_lds_dwordx4 v151, s[22:23]
	s_waitcnt vmcnt(8) lgkmcnt(0)
	s_setprio 1
	s_barrier
	v_mfma_f32_16x16x32_bf16 v[60:63], v[80:83], v[182:185], v[60:63]
	v_mfma_f32_16x16x32_bf16 v[56:59], v[88:91], v[182:185], v[56:59]
	v_mfma_f32_16x16x32_bf16 v[44:47], v[80:83], v[194:197], v[44:47]
	v_mfma_f32_16x16x32_bf16 v[40:43], v[88:91], v[194:197], v[40:43]
	v_mfma_f32_16x16x32_bf16 v[28:31], v[80:83], v[202:205], v[28:31]
	v_mfma_f32_16x16x32_bf16 v[24:27], v[88:91], v[202:205], v[24:27]
	v_mfma_f32_16x16x32_bf16 v[12:15], v[80:83], v[210:213], v[12:15]
	v_mfma_f32_16x16x32_bf16 v[8:11], v[88:91], v[210:213], v[8:11]
	v_mfma_f32_16x16x32_bf16 v[60:63], v[84:87], v[186:189], v[60:63]
	v_mfma_f32_16x16x32_bf16 v[56:59], v[92:95], v[186:189], v[56:59]
	v_mfma_f32_16x16x32_bf16 v[44:47], v[84:87], v[198:201], v[44:47]
	v_mfma_f32_16x16x32_bf16 v[40:43], v[92:95], v[198:201], v[40:43]
	v_mfma_f32_16x16x32_bf16 v[28:31], v[84:87], v[206:209], v[28:31]
	v_mfma_f32_16x16x32_bf16 v[24:27], v[92:95], v[206:209], v[24:27]
	v_mfma_f32_16x16x32_bf16 v[12:15], v[84:87], v[214:217], v[12:15]
	v_mfma_f32_16x16x32_bf16 v[8:11], v[92:95], v[214:217], v[8:11]
	v_mfma_f32_16x16x32_bf16 v[52:55], v[166:169], v[182:185], v[52:55]
	v_mfma_f32_16x16x32_bf16 v[48:51], v[174:177], v[182:185], v[48:51]
	v_mfma_f32_16x16x32_bf16 v[36:39], v[166:169], v[194:197], v[36:39]
	v_mfma_f32_16x16x32_bf16 v[32:35], v[174:177], v[194:197], v[32:35]
	v_mfma_f32_16x16x32_bf16 v[20:23], v[166:169], v[202:205], v[20:23]
	v_mfma_f32_16x16x32_bf16 v[16:19], v[174:177], v[202:205], v[16:19]
	v_mfma_f32_16x16x32_bf16 v[4:7], v[166:169], v[210:213], v[4:7]
	v_mfma_f32_16x16x32_bf16 v[0:3], v[174:177], v[210:213], v[0:3]
	v_mfma_f32_16x16x32_bf16 v[52:55], v[170:173], v[186:189], v[52:55]
	v_mfma_f32_16x16x32_bf16 v[48:51], v[178:181], v[186:189], v[48:51]
	v_mfma_f32_16x16x32_bf16 v[36:39], v[170:173], v[198:201], v[36:39]
	v_mfma_f32_16x16x32_bf16 v[32:35], v[178:181], v[198:201], v[32:35]
	v_mfma_f32_16x16x32_bf16 v[20:23], v[170:173], v[206:209], v[20:23]
	v_mfma_f32_16x16x32_bf16 v[16:19], v[178:181], v[206:209], v[16:19]
	v_mfma_f32_16x16x32_bf16 v[4:7], v[170:173], v[214:217], v[4:7]
	v_mfma_f32_16x16x32_bf16 v[0:3], v[178:181], v[214:217], v[0:3]
	s_setprio 0
	s_barrier
; #define PG8_STAGE(bufoff, gbase, voff) do { _Pragma("unroll") for (int _i = 0; _i < 2; ++_i) \
;         asm volatile("s_mov_b32 m0, %0\n\ts_nop 0\n\tglobal_load_lds_dwordx4 %1, %2" :: "s"(ldsb + (unsigned)((bufoff) + _i * 8192)), "v"((voff)[_i]), "s"(gbase) : "m0", "memory"); } while (0)
; #define PG8_LDA(dst, b, h) do { _Pragma("unroll") for (int m = 0; m < 4; ++m) _Pragma("unroll") for (int k = 0; k < 2; ++k) dst[m][k] = *(const PG8_LAS bf16x8*)(lds + PG8_SA(b, h) + aoff + m * 2048 + k * 1024); } while (0)
; #define PG8_LDB(dst, b, h) do { _Pragma("unroll") for (int n = 0; n < 2; ++n) _Pragma("unroll") for (int k = 0; k < 2; ++k) dst[n][k] = *(const PG8_LAS bf16x8*)(lds + PG8_SB(b, h) + boff + n * 2048 + k * 1024); } while (0)
; #define PG8_MMA(ai, bj, At, Bt) do { __builtin_amdgcn_s_setprio(1); _Pragma("unroll") for (int m = 0; m < 4; ++m) _Pragma("unroll") for (int n = 0; n < 2; ++n) _Pragma("unroll") for (int k = 0; k < 2; ++k) \
;         acc[ai][bj][m][n] = __builtin_amdgcn_mfma_f32_16x16x32_bf16(Bt[n][k], At[m][k], acc[ai][bj][m][n], 0, 0, 0); __builtin_amdgcn_s_setprio(0); } while (0)
; #define PG8_WAIT_V(n) asm volatile("s_waitcnt vmcnt(" #n ")" ::: "memory")
; #define PG8_WAIT_L(n) asm volatile("s_waitcnt lgkmcnt(" #n ")" ::: "memory")
; #define PG8_BAR __builtin_amdgcn_s_barrier()
; template <class Epi, class Sched, bool ALIGN_EPI = false, bool SP2 = false>
; __device__ __forceinline__ void gemm_phase(PG8_LAS unsigned char* lds, const Gemm g, const Sched& S, const Epi& E, const int wv) {
;     ...
;         for (int t = 0; t < nt; t += 2) {
;             const bool last = (t == nt - 2);
;             const char* a1 = cA + (size_t)(t + 1) * kstep;
;             const char* a2 = last ? nA : cA + (size_t)(t + 2) * kstep; const char* b2 = last ? nB : cB + (size_t)(t + 2) * kstep;
;             const char* a3 = a2 + kstep; const char* b3 = b2 + kstep;
;     ...
;             PG8_LDB(B0, 1, 0); PG8_LDB(B1, 1, 1); PG8_SCHED; PG8_LDA(At, 1, 0); PG8_STAGE(PG8_SA(0, 1), a2 + hstepA, voffA);
;             PG8_WAIT_V(8); PG8_WAIT_L(0); PG8_BAR; PG8_MMA(0, 0, At, B0); PG8_MMA(0, 1, At, B1); PG8_BAR; PG8_SCHED;
;             PG8_LDA(At, 1, 1); PG8_STAGE(PG8_SB(1, 0), b3, voffB); PG8_STAGE(PG8_SB(1, 1), b3 + hstepB, voffB); PG8_STAGE(PG8_SA(1, 0), a3, voffA);
;             PG8_WAIT_V(8); PG8_WAIT_L(0); PG8_BAR; PG8_MMA(1, 0, At, B0); PG8_MMA(1, 1, At, B1); PG8_BAR; PG8_SCHED;
	v_add_u32_e32 v92, 0x18000, v160
	v_add_u32_e32 v144, 0x1c000, v160
	ds_read_b128 v[80:83], v92
	ds_read_b128 v[84:87], v92 offset:1024
	ds_read_b128 v[88:91], v92 offset:2048
	ds_read_b128 v[92:95], v92 offset:3072
	ds_read_b128 v[166:169], v144
	ds_read_b128 v[170:173], v144 offset:1024
	ds_read_b128 v[174:177], v144 offset:2048
	ds_read_b128 v[178:181], v144 offset:3072
	ds_read_b128 v[182:185], v163 offset:32768
	ds_read_b128 v[186:189], v163 offset:33792
	ds_read_b128 v[194:197], v163 offset:34816
	ds_read_b128 v[198:201], v163 offset:35840
	ds_read_b128 v[202:205], v163 offset:36864
	ds_read_b128 v[206:209], v163 offset:37888
	ds_read_b128 v[210:213], v163 offset:38912
	ds_read_b128 v[214:217], v163 offset:39936
	s_add_u32 s22, s22, 0x84000
	s_addc_u32 s23, s23, 0
	s_mov_b32 m0, s35
	s_nop 0
	global_load_lds_dwordx4 v147, s[22:23]
	s_nop 0
	s_mov_b32 m0, s36
	s_nop 0
	global_load_lds_dwordx4 v151, s[22:23]
	s_waitcnt vmcnt(8) lgkmcnt(0)
	s_setprio 1
	s_barrier
	v_mfma_f32_16x16x32_bf16 v[140:143], v[80:83], v[182:185], v[140:143]
	v_mfma_f32_16x16x32_bf16 v[136:139], v[88:91], v[182:185], v[136:139]
	v_mfma_f32_16x16x32_bf16 v[124:127], v[80:83], v[194:197], v[124:127]
	v_mfma_f32_16x16x32_bf16 v[120:123], v[88:91], v[194:197], v[120:123]
	v_mfma_f32_16x16x32_bf16 v[108:111], v[80:83], v[202:205], v[108:111]
	v_mfma_f32_16x16x32_bf16 v[104:107], v[88:91], v[202:205], v[104:107]
	v_mfma_f32_16x16x32_bf16 v[76:79], v[80:83], v[210:213], v[76:79]
	v_mfma_f32_16x16x32_bf16 v[72:75], v[88:91], v[210:213], v[72:75]
	v_mfma_f32_16x16x32_bf16 v[140:143], v[84:87], v[186:189], v[140:143]
	v_mfma_f32_16x16x32_bf16 v[136:139], v[92:95], v[186:189], v[136:139]
	v_mfma_f32_16x16x32_bf16 v[124:127], v[84:87], v[198:201], v[124:127]
	v_mfma_f32_16x16x32_bf16 v[120:123], v[92:95], v[198:201], v[120:123]
	v_mfma_f32_16x16x32_bf16 v[108:111], v[84:87], v[206:209], v[108:111]
	v_mfma_f32_16x16x32_bf16 v[104:107], v[92:95], v[206:209], v[104:107]
	v_mfma_f32_16x16x32_bf16 v[76:79], v[84:87], v[214:217], v[76:79]
	v_mfma_f32_16x16x32_bf16 v[72:75], v[92:95], v[214:217], v[72:75]
	v_mfma_f32_16x16x32_bf16 v[132:135], v[166:169], v[182:185], v[132:135]
	v_mfma_f32_16x16x32_bf16 v[128:131], v[174:177], v[182:185], v[128:131]
	v_mfma_f32_16x16x32_bf16 v[116:119], v[166:169], v[194:197], v[116:119]
	v_mfma_f32_16x16x32_bf16 v[112:115], v[174:177], v[194:197], v[112:115]
	v_mfma_f32_16x16x32_bf16 v[100:103], v[166:169], v[202:205], v[100:103]
	v_mfma_f32_16x16x32_bf16 v[96:99], v[174:177], v[202:205], v[96:99]
	v_mfma_f32_16x16x32_bf16 v[68:71], v[166:169], v[210:213], v[68:71]
	v_mfma_f32_16x16x32_bf16 v[64:67], v[174:177], v[210:213], v[64:67]
	v_mfma_f32_16x16x32_bf16 v[132:135], v[170:173], v[186:189], v[132:135]
	v_mfma_f32_16x16x32_bf16 v[128:131], v[178:181], v[186:189], v[128:131]
	v_mfma_f32_16x16x32_bf16 v[116:119], v[170:173], v[198:201], v[116:119]
	v_mfma_f32_16x16x32_bf16 v[112:115], v[178:181], v[198:201], v[112:115]
	v_mfma_f32_16x16x32_bf16 v[100:103], v[170:173], v[206:209], v[100:103]
	v_mfma_f32_16x16x32_bf16 v[96:99], v[178:181], v[206:209], v[96:99]
	v_mfma_f32_16x16x32_bf16 v[68:71], v[170:173], v[214:217], v[68:71]
	v_mfma_f32_16x16x32_bf16 v[64:67], v[178:181], v[214:217], v[64:67]
	s_setprio 0
	s_barrier
	ds_read_b128 v[182:185], v163 offset:49152
	ds_read_b128 v[186:189], v163 offset:50176
	ds_read_b128 v[194:197], v163 offset:51200
	ds_read_b128 v[198:201], v163 offset:52224
	ds_read_b128 v[202:205], v163 offset:53248
	ds_read_b128 v[206:209], v163 offset:54272
	ds_read_b128 v[210:213], v163 offset:55296
	ds_read_b128 v[214:217], v163 offset:56320
	s_add_u32 s22, s20, 0x80
	s_addc_u32 s23, s21, 0
	s_mov_b32 m0, s45
	s_nop 0
	global_load_lds_dwordx4 v149, s[22:23]
	s_add_u32 s20, s20, 0x80080
	s_mov_b32 m0, s46
	s_nop 0
	global_load_lds_dwordx4 v153, s[22:23]
	s_addc_u32 s21, s21, 0
	s_mov_b32 m0, s49
	s_nop 0
	global_load_lds_dwordx4 v149, s[20:21]
	s_nop 0
	s_mov_b32 m0, s50
	s_nop 0
	global_load_lds_dwordx4 v153, s[20:21]
	s_nop 0
	s_mov_b32 m0, s47
	s_nop 0
	global_load_lds_dwordx4 v147, s[18:19]
	s_nop 0
	s_mov_b32 m0, s48
	s_nop 0
	global_load_lds_dwordx4 v151, s[18:19]
	s_waitcnt vmcnt(8) lgkmcnt(0)
	s_setprio 1
	s_barrier
	v_mfma_f32_16x16x32_bf16 v[60:63], v[80:83], v[182:185], v[60:63]
	v_mfma_f32_16x16x32_bf16 v[56:59], v[88:91], v[182:185], v[56:59]
	v_mfma_f32_16x16x32_bf16 v[44:47], v[80:83], v[194:197], v[44:47]
	v_mfma_f32_16x16x32_bf16 v[40:43], v[88:91], v[194:197], v[40:43]
	v_mfma_f32_16x16x32_bf16 v[28:31], v[80:83], v[202:205], v[28:31]
	v_mfma_f32_16x16x32_bf16 v[24:27], v[88:91], v[202:205], v[24:27]
	v_mfma_f32_16x16x32_bf16 v[12:15], v[80:83], v[210:213], v[12:15]
	v_mfma_f32_16x16x32_bf16 v[8:11], v[88:91], v[210:213], v[8:11]
	v_mfma_f32_16x16x32_bf16 v[60:63], v[84:87], v[186:189], v[60:63]
	v_mfma_f32_16x16x32_bf16 v[56:59], v[92:95], v[186:189], v[56:59]
	v_mfma_f32_16x16x32_bf16 v[44:47], v[84:87], v[198:201], v[44:47]
	v_mfma_f32_16x16x32_bf16 v[40:43], v[92:95], v[198:201], v[40:43]
	v_mfma_f32_16x16x32_bf16 v[28:31], v[84:87], v[206:209], v[28:31]
	v_mfma_f32_16x16x32_bf16 v[24:27], v[92:95], v[206:209], v[24:27]
	v_mfma_f32_16x16x32_bf16 v[12:15], v[84:87], v[214:217], v[12:15]
	v_mfma_f32_16x16x32_bf16 v[8:11], v[92:95], v[214:217], v[8:11]
	v_mfma_f32_16x16x32_bf16 v[52:55], v[166:169], v[182:185], v[52:55]
	v_mfma_f32_16x16x32_bf16 v[48:51], v[174:177], v[182:185], v[48:51]
	v_mfma_f32_16x16x32_bf16 v[36:39], v[166:169], v[194:197], v[36:39]
	v_mfma_f32_16x16x32_bf16 v[32:35], v[174:177], v[194:197], v[32:35]
	v_mfma_f32_16x16x32_bf16 v[20:23], v[166:169], v[202:205], v[20:23]
	v_mfma_f32_16x16x32_bf16 v[16:19], v[174:177], v[202:205], v[16:19]
	v_mfma_f32_16x16x32_bf16 v[4:7], v[166:169], v[210:213], v[4:7]
	v_mfma_f32_16x16x32_bf16 v[0:3], v[174:177], v[210:213], v[0:3]
	v_mfma_f32_16x16x32_bf16 v[52:55], v[170:173], v[186:189], v[52:55]
	v_mfma_f32_16x16x32_bf16 v[48:51], v[178:181], v[186:189], v[48:51]
	v_mfma_f32_16x16x32_bf16 v[36:39], v[170:173], v[198:201], v[36:39]
	v_mfma_f32_16x16x32_bf16 v[32:35], v[178:181], v[198:201], v[32:35]
	v_mfma_f32_16x16x32_bf16 v[20:23], v[170:173], v[206:209], v[20:23]
	v_mfma_f32_16x16x32_bf16 v[16:19], v[178:181], v[206:209], v[16:19]
	v_mfma_f32_16x16x32_bf16 v[4:7], v[170:173], v[214:217], v[4:7]
	v_mfma_f32_16x16x32_bf16 v[0:3], v[178:181], v[214:217], v[0:3]
	s_setprio 0
	s_barrier
	s_add_u32 s72, s72, 0x100
	s_addc_u32 s77, s77, 0
	s_add_u32 s79, s79, 0x100
	s_addc_u32 s83, s83, 0
	s_cmp_ge_i32 s84, s40
	s_mov_b32 s18, s84
	s_cbranch_scc0 .LBB0_268
	s_mov_b32 s79, 0xc00000
	s_and_b64 vcc, exec, s[10:11]
	s_cbranch_vccz .LBB0_271

; #define PG8_STAGE(bufoff, gbase, voff) do { _Pragma("unroll") for (int _i = 0; _i < 2; ++_i) \
;         asm volatile("s_mov_b32 m0, %0\n\ts_nop 0\n\tglobal_load_lds_dwordx4 %1, %2" :: "s"(ldsb + (unsigned)((bufoff) + _i * 8192)), "v"((voff)[_i]), "s"(gbase) : "m0", "memory"); } while (0)
; #define PG8_LDA(dst, b, h) do { _Pragma("unroll") for (int m = 0; m < 4; ++m) _Pragma("unroll") for (int k = 0; k < 2; ++k) dst[m][k] = *(const PG8_LAS bf16x8*)(lds + PG8_SA(b, h) + aoff + m * 2048 + k * 1024); } while (0)
; #define PG8_LDB(dst, b, h) do { _Pragma("unroll") for (int n = 0; n < 2; ++n) _Pragma("unroll") for (int k = 0; k < 2; ++k) dst[n][k] = *(const PG8_LAS bf16x8*)(lds + PG8_SB(b, h) + boff + n * 2048 + k * 1024); } while (0)
; #define PG8_MMA(ai, bj, At, Bt) do { __builtin_amdgcn_s_setprio(1); _Pragma("unroll") for (int m = 0; m < 4; ++m) _Pragma("unroll") for (int n = 0; n < 2; ++n) _Pragma("unroll") for (int k = 0; k < 2; ++k) \
;         acc[ai][bj][m][n] = __builtin_amdgcn_mfma_f32_16x16x32_bf16(Bt[n][k], At[m][k], acc[ai][bj][m][n], 0, 0, 0); __builtin_amdgcn_s_setprio(0); } while (0)
; #define PG8_WAIT_V(n) asm volatile("s_waitcnt vmcnt(" #n ")" ::: "memory")
; template <class Epi, class Sched, bool ALIGN_EPI = false, bool SP2 = false>
; __device__ __forceinline__ void gemm_phase(PG8_LAS unsigned char* lds, const Gemm g, const Sched& S, const Epi& E, const int wv) {
;     ...
;         for (int t = 0; t < nt; t += 2) {
;             const bool last = (t == nt - 2);
;             const char* a1 = cA + (size_t)(t + 1) * kstep;
;             const char* a2 = last ? nA : cA + (size_t)(t + 2) * kstep; const char* b2 = last ? nB : cB + (size_t)(t + 2) * kstep;
;             const char* a3 = a2 + kstep; const char* b3 = b2 + kstep;
;             if (last && has_next) S.a_ready(nxt);
;             if constexpr (SP2) {
;             PG8_LDB(B0, 0, 0); PG8_LDB(B1, 0, 1); PG8_SCHED; PG8_LDA(At, 0, 0); PG8_STAGE(PG8_SA(1, 1), a1 + hstepA, voffA);
;             PG8_WAIT_V(8); PG8_WAIT_L(0); PG8_BAR; PG8_MMA(0, 0, At, B0); PG8_MMA(0, 1, At, B1); PG8_BAR; PG8_SCHED;
;             PG8_LDA(At, 0, 1); PG8_STAGE(PG8_SB(0, 0), b2, voffB); PG8_STAGE(PG8_SB(0, 1), b2 + hstepB, voffB); PG8_STAGE(PG8_SA(0, 0), a2, voffA);
;             PG8_WAIT_V(8); PG8_WAIT_L(0); PG8_BAR; PG8_MMA(1, 0, At, B0); PG8_MMA(1, 1, At, B1); PG8_BAR; PG8_SCHED;
.LBB0_343:
	v_add_u32_e32 v140, 0x10000, v220
	v_add_u32_e32 v159, 0x14000, v220
	ds_read_b128 v[128:131], v140
	ds_read_b128 v[132:135], v140 offset:1024
	ds_read_b128 v[136:139], v140 offset:2048
	ds_read_b128 v[140:143], v140 offset:3072
	ds_read_b128 v[144:147], v159
	ds_read_b128 v[148:151], v159 offset:1024
	ds_read_b128 v[152:155], v159 offset:2048
	ds_read_b128 v[160:163], v159 offset:3072
	s_add_i32 s62, s30, 2
	s_cmp_eq_u32 s23, s30
	s_cselect_b32 s36, s24, s85
	s_cselect_b32 s37, s25, vcc_lo
	s_cselect_b32 s34, s26, vcc_hi
	s_cselect_b32 s35, s27, s79
	s_add_u32 s30, s36, 0x80
	s_addc_u32 s31, s37, 0
	ds_read_b128 v[164:167], v221
	ds_read_b128 v[168:171], v221 offset:1024
	ds_read_b128 v[172:175], v221 offset:2048
	ds_read_b128 v[176:179], v221 offset:3072
	ds_read_b128 v[180:183], v221 offset:4096
	ds_read_b128 v[184:187], v221 offset:5120
	ds_read_b128 v[188:191], v221 offset:6144
	ds_read_b128 v[194:197], v221 offset:7168
	s_mov_b32 m0, s93
	s_nop 0
	global_load_lds_dwordx4 v208, s[28:29]
	s_nop 0
	s_mov_b32 m0, s58
	s_nop 0
	global_load_lds_dwordx4 v210, s[28:29]
	s_waitcnt vmcnt(8) lgkmcnt(0)
	s_setprio 1
	s_barrier
	v_mfma_f32_16x16x32_bf16 v[124:127], v[128:131], v[164:167], v[124:127]
	v_mfma_f32_16x16x32_bf16 v[120:123], v[136:139], v[164:167], v[120:123]
	v_mfma_f32_16x16x32_bf16 v[108:111], v[128:131], v[172:175], v[108:111]
	v_mfma_f32_16x16x32_bf16 v[104:107], v[136:139], v[172:175], v[104:107]
	v_mfma_f32_16x16x32_bf16 v[92:95], v[128:131], v[180:183], v[92:95]
	v_mfma_f32_16x16x32_bf16 v[88:91], v[136:139], v[180:183], v[88:91]
	v_mfma_f32_16x16x32_bf16 v[76:79], v[128:131], v[188:191], v[76:79]
	v_mfma_f32_16x16x32_bf16 v[72:75], v[136:139], v[188:191], v[72:75]
	v_mfma_f32_16x16x32_bf16 v[124:127], v[132:135], v[168:171], v[124:127]
	v_mfma_f32_16x16x32_bf16 v[120:123], v[140:143], v[168:171], v[120:123]
	v_mfma_f32_16x16x32_bf16 v[108:111], v[132:135], v[176:179], v[108:111]
	v_mfma_f32_16x16x32_bf16 v[104:107], v[140:143], v[176:179], v[104:107]
	v_mfma_f32_16x16x32_bf16 v[92:95], v[132:135], v[184:187], v[92:95]
	v_mfma_f32_16x16x32_bf16 v[88:91], v[140:143], v[184:187], v[88:91]
	v_mfma_f32_16x16x32_bf16 v[76:79], v[132:135], v[194:197], v[76:79]
	v_mfma_f32_16x16x32_bf16 v[72:75], v[140:143], v[194:197], v[72:75]
	v_mfma_f32_16x16x32_bf16 v[116:119], v[144:147], v[164:167], v[116:119]
	v_mfma_f32_16x16x32_bf16 v[112:115], v[152:155], v[164:167], v[112:115]
	v_mfma_f32_16x16x32_bf16 v[100:103], v[144:147], v[172:175], v[100:103]
	v_mfma_f32_16x16x32_bf16 v[96:99], v[152:155], v[172:175], v[96:99]
	v_mfma_f32_16x16x32_bf16 v[84:87], v[144:147], v[180:183], v[84:87]
	v_mfma_f32_16x16x32_bf16 v[80:83], v[152:155], v[180:183], v[80:83]
	v_mfma_f32_16x16x32_bf16 v[68:71], v[144:147], v[188:191], v[68:71]
	v_mfma_f32_16x16x32_bf16 v[64:67], v[152:155], v[188:191], v[64:67]
	v_mfma_f32_16x16x32_bf16 v[116:119], v[148:151], v[168:171], v[116:119]
	v_mfma_f32_16x16x32_bf16 v[112:115], v[160:163], v[168:171], v[112:115]
	v_mfma_f32_16x16x32_bf16 v[100:103], v[148:151], v[176:179], v[100:103]
	v_mfma_f32_16x16x32_bf16 v[96:99], v[160:163], v[176:179], v[96:99]
	v_mfma_f32_16x16x32_bf16 v[84:87], v[148:151], v[184:187], v[84:87]
	v_mfma_f32_16x16x32_bf16 v[80:83], v[160:163], v[184:187], v[80:83]
	v_mfma_f32_16x16x32_bf16 v[68:71], v[148:151], v[194:197], v[68:71]
	v_mfma_f32_16x16x32_bf16 v[64:67], v[160:163], v[194:197], v[64:67]
	s_setprio 0
	s_barrier
	ds_read_b128 v[164:167], v221 offset:16384
	ds_read_b128 v[168:171], v221 offset:17408
	ds_read_b128 v[172:175], v221 offset:18432
	ds_read_b128 v[176:179], v221 offset:19456
	ds_read_b128 v[180:183], v221 offset:20480
	ds_read_b128 v[184:187], v221 offset:21504
	ds_read_b128 v[188:191], v221 offset:22528
	ds_read_b128 v[194:197], v221 offset:23552
	s_mov_b32 m0, s47
	s_nop 0
	global_load_lds_dwordx4 v209, s[34:35]
	s_add_u32 s8, s34, 0x160000
	s_mov_b32 m0, s48
	s_nop 0
	global_load_lds_dwordx4 v211, s[34:35]
	s_addc_u32 s9, s35, 0
	s_mov_b32 m0, s49
	s_nop 0
	global_load_lds_dwordx4 v209, s[8:9]
	s_nop 0
	s_mov_b32 m0, s50
	s_nop 0
	global_load_lds_dwordx4 v211, s[8:9]
	s_nop 0
	s_mov_b32 m0, s46
	s_nop 0
	global_load_lds_dwordx4 v208, s[36:37]
	s_nop 0
	s_mov_b32 m0, s51
	s_nop 0
	global_load_lds_dwordx4 v210, s[36:37]
	s_waitcnt vmcnt(8) lgkmcnt(0)
	s_setprio 1
	s_barrier
	v_mfma_f32_16x16x32_bf16 v[60:63], v[128:131], v[164:167], v[60:63]
	v_mfma_f32_16x16x32_bf16 v[56:59], v[136:139], v[164:167], v[56:59]
	v_mfma_f32_16x16x32_bf16 v[44:47], v[128:131], v[172:175], v[44:47]
	v_mfma_f32_16x16x32_bf16 v[40:43], v[136:139], v[172:175], v[40:43]
	v_mfma_f32_16x16x32_bf16 v[28:31], v[128:131], v[180:183], v[28:31]
	v_mfma_f32_16x16x32_bf16 v[24:27], v[136:139], v[180:183], v[24:27]
	v_mfma_f32_16x16x32_bf16 v[12:15], v[128:131], v[188:191], v[12:15]
	v_mfma_f32_16x16x32_bf16 v[8:11], v[136:139], v[188:191], v[8:11]
	v_mfma_f32_16x16x32_bf16 v[60:63], v[132:135], v[168:171], v[60:63]
	v_mfma_f32_16x16x32_bf16 v[56:59], v[140:143], v[168:171], v[56:59]
	v_mfma_f32_16x16x32_bf16 v[44:47], v[132:135], v[176:179], v[44:47]
	v_mfma_f32_16x16x32_bf16 v[40:43], v[140:143], v[176:179], v[40:43]
	v_mfma_f32_16x16x32_bf16 v[28:31], v[132:135], v[184:187], v[28:31]
	v_mfma_f32_16x16x32_bf16 v[24:27], v[140:143], v[184:187], v[24:27]
	v_mfma_f32_16x16x32_bf16 v[12:15], v[132:135], v[194:197], v[12:15]
	v_mfma_f32_16x16x32_bf16 v[8:11], v[140:143], v[194:197], v[8:11]
	v_mfma_f32_16x16x32_bf16 v[52:55], v[144:147], v[164:167], v[52:55]
	v_mfma_f32_16x16x32_bf16 v[48:51], v[152:155], v[164:167], v[48:51]
	v_mfma_f32_16x16x32_bf16 v[36:39], v[144:147], v[172:175], v[36:39]
	v_mfma_f32_16x16x32_bf16 v[32:35], v[152:155], v[172:175], v[32:35]
	v_mfma_f32_16x16x32_bf16 v[20:23], v[144:147], v[180:183], v[20:23]
	v_mfma_f32_16x16x32_bf16 v[16:19], v[152:155], v[180:183], v[16:19]
	v_mfma_f32_16x16x32_bf16 v[4:7], v[144:147], v[188:191], v[4:7]
	v_mfma_f32_16x16x32_bf16 v[0:3], v[152:155], v[188:191], v[0:3]
	v_mfma_f32_16x16x32_bf16 v[52:55], v[148:151], v[168:171], v[52:55]
	v_mfma_f32_16x16x32_bf16 v[48:51], v[160:163], v[168:171], v[48:51]
	v_mfma_f32_16x16x32_bf16 v[36:39], v[148:151], v[176:179], v[36:39]
	v_mfma_f32_16x16x32_bf16 v[32:35], v[160:163], v[176:179], v[32:35]
	v_mfma_f32_16x16x32_bf16 v[20:23], v[148:151], v[184:187], v[20:23]
	v_mfma_f32_16x16x32_bf16 v[16:19], v[160:163], v[184:187], v[16:19]
	v_mfma_f32_16x16x32_bf16 v[4:7], v[148:151], v[194:197], v[4:7]
	v_mfma_f32_16x16x32_bf16 v[0:3], v[160:163], v[194:197], v[0:3]
	s_setprio 0
	s_barrier
; #define PG8_STAGE(bufoff, gbase, voff) do { _Pragma("unroll") for (int _i = 0; _i < 2; ++_i) \
;         asm volatile("s_mov_b32 m0, %0\n\ts_nop 0\n\tglobal_load_lds_dwordx4 %1, %2" :: "s"(ldsb + (unsigned)((bufoff) + _i * 8192)), "v"((voff)[_i]), "s"(gbase) : "m0", "memory"); } while (0)
; #define PG8_LDA(dst, b, h) do { _Pragma("unroll") for (int m = 0; m < 4; ++m) _Pragma("unroll") for (int k = 0; k < 2; ++k) dst[m][k] = *(const PG8_LAS bf16x8*)(lds + PG8_SA(b, h) + aoff + m * 2048 + k * 1024); } while (0)
; #define PG8_LDB(dst, b, h) do { _Pragma("unroll") for (int n = 0; n < 2; ++n) _Pragma("unroll") for (int k = 0; k < 2; ++k) dst[n][k] = *(const PG8_LAS bf16x8*)(lds + PG8_SB(b, h) + boff + n * 2048 + k * 1024); } while (0)
; #define PG8_MMA(ai, bj, At, Bt) do { __builtin_amdgcn_s_setprio(1); _Pragma("unroll") for (int m = 0; m < 4; ++m) _Pragma("unroll") for (int n = 0; n < 2; ++n) _Pragma("unroll") for (int k = 0; k < 2; ++k) \
;         acc[ai][bj][m][n] = __builtin_amdgcn_mfma_f32_16x16x32_bf16(Bt[n][k], At[m][k], acc[ai][bj][m][n], 0, 0, 0); __builtin_amdgcn_s_setprio(0); } while (0)
; #define PG8_WAIT_V(n) asm volatile("s_waitcnt vmcnt(" #n ")" ::: "memory")
; #define PG8_WAIT_L(n) asm volatile("s_waitcnt lgkmcnt(" #n ")" ::: "memory")
; #define PG8_BAR __builtin_amdgcn_s_barrier()
; #define PG8_SCHED __builtin_amdgcn_sched_barrier(0)
; template <class Epi, class Sched, bool ALIGN_EPI = false, bool SP2 = false>
; __device__ __forceinline__ void gemm_phase(PG8_LAS unsigned char* lds, const Gemm g, const Sched& S, const Epi& E, const int wv) {
;     ...
;             PG8_LDB(B0, 1, 0); PG8_LDB(B1, 1, 1); PG8_SCHED; PG8_LDA(At, 1, 0); PG8_STAGE(PG8_SA(0, 1), a2 + hstepA, voffA);
;             PG8_WAIT_V(8); PG8_WAIT_L(0); PG8_BAR; PG8_MMA(0, 0, At, B0); PG8_MMA(0, 1, At, B1); PG8_BAR; PG8_SCHED;
;             PG8_LDA(At, 1, 1); PG8_STAGE(PG8_SB(1, 0), b3, voffB); PG8_STAGE(PG8_SB(1, 1), b3 + hstepB, voffB); PG8_STAGE(PG8_SA(1, 0), a3, voffA);
;             PG8_WAIT_V(8); PG8_WAIT_L(0); PG8_BAR; PG8_MMA(1, 0, At, B0); PG8_MMA(1, 1, At, B1); PG8_BAR; PG8_SCHED;
	v_add_u32_e32 v140, 0x18000, v220
	v_add_u32_e32 v159, 0x1c000, v220
	ds_read_b128 v[128:131], v140
	ds_read_b128 v[132:135], v140 offset:1024
	ds_read_b128 v[136:139], v140 offset:2048
	ds_read_b128 v[140:143], v140 offset:3072
	ds_read_b128 v[144:147], v159
	ds_read_b128 v[148:151], v159 offset:1024
	ds_read_b128 v[152:155], v159 offset:2048
	ds_read_b128 v[160:163], v159 offset:3072
	ds_read_b128 v[164:167], v221 offset:32768
	ds_read_b128 v[168:171], v221 offset:33792
	ds_read_b128 v[172:175], v221 offset:34816
	ds_read_b128 v[176:179], v221 offset:35840
	ds_read_b128 v[180:183], v221 offset:36864
	ds_read_b128 v[184:187], v221 offset:37888
	ds_read_b128 v[188:191], v221 offset:38912
	ds_read_b128 v[194:197], v221 offset:39936
	s_add_u32 s8, s36, 0x160000
	s_addc_u32 s9, s37, 0
	s_mov_b32 m0, s52
	s_nop 0
	global_load_lds_dwordx4 v208, s[8:9]
	s_nop 0
	s_mov_b32 m0, s53
	s_nop 0
	global_load_lds_dwordx4 v210, s[8:9]
	s_waitcnt vmcnt(8) lgkmcnt(0)
	s_setprio 1
	s_barrier
	v_mfma_f32_16x16x32_bf16 v[124:127], v[128:131], v[164:167], v[124:127]
	v_mfma_f32_16x16x32_bf16 v[120:123], v[136:139], v[164:167], v[120:123]
	v_mfma_f32_16x16x32_bf16 v[108:111], v[128:131], v[172:175], v[108:111]
	v_mfma_f32_16x16x32_bf16 v[104:107], v[136:139], v[172:175], v[104:107]
	v_mfma_f32_16x16x32_bf16 v[92:95], v[128:131], v[180:183], v[92:95]
	v_mfma_f32_16x16x32_bf16 v[88:91], v[136:139], v[180:183], v[88:91]
	v_mfma_f32_16x16x32_bf16 v[76:79], v[128:131], v[188:191], v[76:79]
	v_mfma_f32_16x16x32_bf16 v[72:75], v[136:139], v[188:191], v[72:75]
	v_mfma_f32_16x16x32_bf16 v[124:127], v[132:135], v[168:171], v[124:127]
	v_mfma_f32_16x16x32_bf16 v[120:123], v[140:143], v[168:171], v[120:123]
	v_mfma_f32_16x16x32_bf16 v[108:111], v[132:135], v[176:179], v[108:111]
	v_mfma_f32_16x16x32_bf16 v[104:107], v[140:143], v[176:179], v[104:107]
	v_mfma_f32_16x16x32_bf16 v[92:95], v[132:135], v[184:187], v[92:95]
	v_mfma_f32_16x16x32_bf16 v[88:91], v[140:143], v[184:187], v[88:91]
	v_mfma_f32_16x16x32_bf16 v[76:79], v[132:135], v[194:197], v[76:79]
	v_mfma_f32_16x16x32_bf16 v[72:75], v[140:143], v[194:197], v[72:75]
	v_mfma_f32_16x16x32_bf16 v[116:119], v[144:147], v[164:167], v[116:119]
	v_mfma_f32_16x16x32_bf16 v[112:115], v[152:155], v[164:167], v[112:115]
	v_mfma_f32_16x16x32_bf16 v[100:103], v[144:147], v[172:175], v[100:103]
	v_mfma_f32_16x16x32_bf16 v[96:99], v[152:155], v[172:175], v[96:99]
	v_mfma_f32_16x16x32_bf16 v[84:87], v[144:147], v[180:183], v[84:87]
	v_mfma_f32_16x16x32_bf16 v[80:83], v[152:155], v[180:183], v[80:83]
	v_mfma_f32_16x16x32_bf16 v[68:71], v[144:147], v[188:191], v[68:71]
	v_mfma_f32_16x16x32_bf16 v[64:67], v[152:155], v[188:191], v[64:67]
	v_mfma_f32_16x16x32_bf16 v[116:119], v[148:151], v[168:171], v[116:119]
	v_mfma_f32_16x16x32_bf16 v[112:115], v[160:163], v[168:171], v[112:115]
	v_mfma_f32_16x16x32_bf16 v[100:103], v[148:151], v[176:179], v[100:103]
	v_mfma_f32_16x16x32_bf16 v[96:99], v[160:163], v[176:179], v[96:99]
	v_mfma_f32_16x16x32_bf16 v[84:87], v[148:151], v[184:187], v[84:87]
	v_mfma_f32_16x16x32_bf16 v[80:83], v[160:163], v[184:187], v[80:83]
	v_mfma_f32_16x16x32_bf16 v[68:71], v[148:151], v[194:197], v[68:71]
	v_mfma_f32_16x16x32_bf16 v[64:67], v[160:163], v[194:197], v[64:67]
	s_setprio 0
	s_barrier
	ds_read_b128 v[164:167], v221 offset:49152
	ds_read_b128 v[168:171], v221 offset:50176
	ds_read_b128 v[172:175], v221 offset:51200
	ds_read_b128 v[176:179], v221 offset:52224
	ds_read_b128 v[180:183], v221 offset:53248
	ds_read_b128 v[184:187], v221 offset:54272
	ds_read_b128 v[188:191], v221 offset:55296
	ds_read_b128 v[194:197], v221 offset:56320
	s_add_u32 s8, s34, 0x80
	s_addc_u32 s9, s35, 0
	s_mov_b32 m0, s86
	s_nop 0
	global_load_lds_dwordx4 v209, s[8:9]
	s_nop 0
	s_mov_b32 m0, s87
	s_nop 0
	global_load_lds_dwordx4 v211, s[8:9]
	s_add_u32 s8, s34, 0x160080
	s_addc_u32 s9, s35, 0
	s_mov_b32 m0, s89
	s_nop 0
	global_load_lds_dwordx4 v209, s[8:9]
	s_nop 0
	s_mov_b32 m0, s92
	s_nop 0
	global_load_lds_dwordx4 v211, s[8:9]
	s_nop 0
	s_mov_b32 m0, s83
	s_nop 0
	global_load_lds_dwordx4 v208, s[30:31]
	s_nop 0
	s_mov_b32 m0, s60
	s_nop 0
	global_load_lds_dwordx4 v210, s[30:31]
	s_waitcnt vmcnt(8) lgkmcnt(0)
	s_setprio 1
	s_barrier
	v_mfma_f32_16x16x32_bf16 v[60:63], v[128:131], v[164:167], v[60:63]
	v_mfma_f32_16x16x32_bf16 v[56:59], v[136:139], v[164:167], v[56:59]
	v_mfma_f32_16x16x32_bf16 v[44:47], v[128:131], v[172:175], v[44:47]
	v_mfma_f32_16x16x32_bf16 v[40:43], v[136:139], v[172:175], v[40:43]
	v_mfma_f32_16x16x32_bf16 v[28:31], v[128:131], v[180:183], v[28:31]
	v_mfma_f32_16x16x32_bf16 v[24:27], v[136:139], v[180:183], v[24:27]
	v_mfma_f32_16x16x32_bf16 v[12:15], v[128:131], v[188:191], v[12:15]
	v_mfma_f32_16x16x32_bf16 v[8:11], v[136:139], v[188:191], v[8:11]
	v_mfma_f32_16x16x32_bf16 v[60:63], v[132:135], v[168:171], v[60:63]
	v_mfma_f32_16x16x32_bf16 v[56:59], v[140:143], v[168:171], v[56:59]
	v_mfma_f32_16x16x32_bf16 v[44:47], v[132:135], v[176:179], v[44:47]
	v_mfma_f32_16x16x32_bf16 v[40:43], v[140:143], v[176:179], v[40:43]
	v_mfma_f32_16x16x32_bf16 v[28:31], v[132:135], v[184:187], v[28:31]
	v_mfma_f32_16x16x32_bf16 v[24:27], v[140:143], v[184:187], v[24:27]
	v_mfma_f32_16x16x32_bf16 v[12:15], v[132:135], v[194:197], v[12:15]
	v_mfma_f32_16x16x32_bf16 v[8:11], v[140:143], v[194:197], v[8:11]
	v_mfma_f32_16x16x32_bf16 v[52:55], v[144:147], v[164:167], v[52:55]
	v_mfma_f32_16x16x32_bf16 v[48:51], v[152:155], v[164:167], v[48:51]
	v_mfma_f32_16x16x32_bf16 v[36:39], v[144:147], v[172:175], v[36:39]
	v_mfma_f32_16x16x32_bf16 v[32:35], v[152:155], v[172:175], v[32:35]
	v_mfma_f32_16x16x32_bf16 v[20:23], v[144:147], v[180:183], v[20:23]
	v_mfma_f32_16x16x32_bf16 v[16:19], v[152:155], v[180:183], v[16:19]
	v_mfma_f32_16x16x32_bf16 v[4:7], v[144:147], v[188:191], v[4:7]
	v_mfma_f32_16x16x32_bf16 v[0:3], v[152:155], v[188:191], v[0:3]
	v_mfma_f32_16x16x32_bf16 v[52:55], v[148:151], v[168:171], v[52:55]
	v_mfma_f32_16x16x32_bf16 v[48:51], v[160:163], v[168:171], v[48:51]
	v_mfma_f32_16x16x32_bf16 v[36:39], v[148:151], v[176:179], v[36:39]
	v_mfma_f32_16x16x32_bf16 v[32:35], v[160:163], v[176:179], v[32:35]
	v_mfma_f32_16x16x32_bf16 v[20:23], v[148:151], v[184:187], v[20:23]
	v_mfma_f32_16x16x32_bf16 v[16:19], v[160:163], v[184:187], v[16:19]
	v_mfma_f32_16x16x32_bf16 v[4:7], v[148:151], v[194:197], v[4:7]
	v_mfma_f32_16x16x32_bf16 v[0:3], v[160:163], v[194:197], v[0:3]
	s_setprio 0
	s_barrier
	s_add_u32 s85, s85, 0x100
	s_addc_u32 vcc_lo, vcc_lo, 0
	s_add_u32 vcc_hi, vcc_hi, 0x100
	s_addc_u32 s79, s79, 0
	s_add_u32 s28, s28, 0x100
	s_addc_u32 s29, s29, 0
	s_cmp_ge_i32 s62, s40
	s_mov_b32 s30, s62
	s_cbranch_scc0 .LBB0_343
	s_mov_b32 s79, 0xc00000
	s_and_b64 vcc, exec, s[18:19]
	s_cbranch_vccz .LBB0_346

; #define PG8_STAGE(bufoff, gbase, voff) do { _Pragma("unroll") for (int _i = 0; _i < 2; ++_i) \
;         asm volatile("s_mov_b32 m0, %0\n\ts_nop 0\n\tglobal_load_lds_dwordx4 %1, %2" :: "s"(ldsb + (unsigned)((bufoff) + _i * 8192)), "v"((voff)[_i]), "s"(gbase) : "m0", "memory"); } while (0)
; #define PG8_LDA(dst, b, h) do { _Pragma("unroll") for (int m = 0; m < 4; ++m) _Pragma("unroll") for (int k = 0; k < 2; ++k) dst[m][k] = *(const PG8_LAS bf16x8*)(lds + PG8_SA(b, h) + aoff + m * 2048 + k * 1024); } while (0)
; #define PG8_LDB(dst, b, h) do { _Pragma("unroll") for (int n = 0; n < 2; ++n) _Pragma("unroll") for (int k = 0; k < 2; ++k) dst[n][k] = *(const PG8_LAS bf16x8*)(lds + PG8_SB(b, h) + boff + n * 2048 + k * 1024); } while (0)
; #define PG8_MMA(ai, bj, At, Bt) do { __builtin_amdgcn_s_setprio(1); _Pragma("unroll") for (int m = 0; m < 4; ++m) _Pragma("unroll") for (int n = 0; n < 2; ++n) _Pragma("unroll") for (int k = 0; k < 2; ++k) \
;         acc[ai][bj][m][n] = __builtin_amdgcn_mfma_f32_16x16x32_bf16(Bt[n][k], At[m][k], acc[ai][bj][m][n], 0, 0, 0); __builtin_amdgcn_s_setprio(0); } while (0)
; #define PG8_WAIT_V(n) asm volatile("s_waitcnt vmcnt(" #n ")" ::: "memory")
; template <class Epi, class Sched, bool ALIGN_EPI = false, bool SP2 = false>
; __device__ __forceinline__ void gemm_phase(PG8_LAS unsigned char* lds, const Gemm g, const Sched& S, const Epi& E, const int wv) {
;     ...
;         for (int t = 0; t < nt; t += 2) {
;             const bool last = (t == nt - 2);
;             const char* a1 = cA + (size_t)(t + 1) * kstep;
;             const char* a2 = last ? nA : cA + (size_t)(t + 2) * kstep; const char* b2 = last ? nB : cB + (size_t)(t + 2) * kstep;
;             const char* a3 = a2 + kstep; const char* b3 = b2 + kstep;
;             if (last && has_next) S.a_ready(nxt);
;             if constexpr (SP2) {
;             PG8_LDB(B0, 0, 0); PG8_LDB(B1, 0, 1); PG8_SCHED; PG8_LDA(At, 0, 0); PG8_STAGE(PG8_SA(1, 1), a1 + hstepA, voffA);
;             PG8_WAIT_V(8); PG8_WAIT_L(0); PG8_BAR; PG8_MMA(0, 0, At, B0); PG8_MMA(0, 1, At, B1); PG8_BAR; PG8_SCHED;
;             PG8_LDA(At, 0, 1); PG8_STAGE(PG8_SB(0, 0), b2, voffB); PG8_STAGE(PG8_SB(0, 1), b2 + hstepB, voffB); PG8_STAGE(PG8_SA(0, 0), a2, voffA);
;             PG8_WAIT_V(8); PG8_WAIT_L(0); PG8_BAR; PG8_MMA(1, 0, At, B0); PG8_MMA(1, 1, At, B1); PG8_BAR; PG8_SCHED;
.LBB0_396:
	v_add_u32_e32 v140, 0x10000, v240
	v_add_u32_e32 v156, 0x14000, v240
	ds_read_b128 v[128:131], v140
	ds_read_b128 v[132:135], v140 offset:1024
	ds_read_b128 v[136:139], v140 offset:2048
	ds_read_b128 v[140:143], v140 offset:3072
	ds_read_b128 v[144:147], v156
	ds_read_b128 v[148:151], v156 offset:1024
	ds_read_b128 v[152:155], v156 offset:2048
	ds_read_b128 v[156:159], v156 offset:3072
	s_add_i32 vcc_hi, s30, 2
	s_cmp_eq_u32 s25, s30
	s_cselect_b32 s36, s26, s62
	s_cselect_b32 s37, s27, s79
	s_cselect_b32 s34, s28, s97
	s_cselect_b32 s35, s29, vcc_lo
	s_add_u32 s30, s36, 0x80
	s_addc_u32 s31, s37, 0
	ds_read_b128 v[160:163], v194
	ds_read_b128 v[164:167], v194 offset:1024
	ds_read_b128 v[168:171], v194 offset:2048
	ds_read_b128 v[172:175], v194 offset:3072
	ds_read_b128 v[176:179], v194 offset:4096
	ds_read_b128 v[180:183], v194 offset:5120
	ds_read_b128 v[184:187], v194 offset:6144
	ds_read_b128 v[188:191], v194 offset:7168
	s_add_u32 s10, s62, 0x15ff80
	s_addc_u32 s11, s79, 0
	s_mov_b32 m0, s83
	s_nop 0
	global_load_lds_dwordx4 v244, s[10:11]
	s_nop 0
	s_mov_b32 m0, s86
	s_nop 0
	global_load_lds_dwordx4 v246, s[10:11]
	s_waitcnt vmcnt(8) lgkmcnt(0)
	s_setprio 1
	s_barrier
	v_mfma_f32_16x16x32_bf16 v[124:127], v[128:131], v[160:163], v[124:127]
	v_mfma_f32_16x16x32_bf16 v[120:123], v[136:139], v[160:163], v[120:123]
	v_mfma_f32_16x16x32_bf16 v[108:111], v[128:131], v[168:171], v[108:111]
	v_mfma_f32_16x16x32_bf16 v[104:107], v[136:139], v[168:171], v[104:107]
	v_mfma_f32_16x16x32_bf16 v[92:95], v[128:131], v[176:179], v[92:95]
	v_mfma_f32_16x16x32_bf16 v[88:91], v[136:139], v[176:179], v[88:91]
	v_mfma_f32_16x16x32_bf16 v[76:79], v[128:131], v[184:187], v[76:79]
	v_mfma_f32_16x16x32_bf16 v[72:75], v[136:139], v[184:187], v[72:75]
	v_mfma_f32_16x16x32_bf16 v[124:127], v[132:135], v[164:167], v[124:127]
	v_mfma_f32_16x16x32_bf16 v[120:123], v[140:143], v[164:167], v[120:123]
	v_mfma_f32_16x16x32_bf16 v[108:111], v[132:135], v[172:175], v[108:111]
	v_mfma_f32_16x16x32_bf16 v[104:107], v[140:143], v[172:175], v[104:107]
	v_mfma_f32_16x16x32_bf16 v[92:95], v[132:135], v[180:183], v[92:95]
	v_mfma_f32_16x16x32_bf16 v[88:91], v[140:143], v[180:183], v[88:91]
	v_mfma_f32_16x16x32_bf16 v[76:79], v[132:135], v[188:191], v[76:79]
	v_mfma_f32_16x16x32_bf16 v[72:75], v[140:143], v[188:191], v[72:75]
	v_mfma_f32_16x16x32_bf16 v[116:119], v[144:147], v[160:163], v[116:119]
	v_mfma_f32_16x16x32_bf16 v[112:115], v[152:155], v[160:163], v[112:115]
	v_mfma_f32_16x16x32_bf16 v[100:103], v[144:147], v[168:171], v[100:103]
	v_mfma_f32_16x16x32_bf16 v[96:99], v[152:155], v[168:171], v[96:99]
	v_mfma_f32_16x16x32_bf16 v[84:87], v[144:147], v[176:179], v[84:87]
	v_mfma_f32_16x16x32_bf16 v[80:83], v[152:155], v[176:179], v[80:83]
	v_mfma_f32_16x16x32_bf16 v[68:71], v[144:147], v[184:187], v[68:71]
	v_mfma_f32_16x16x32_bf16 v[64:67], v[152:155], v[184:187], v[64:67]
	v_mfma_f32_16x16x32_bf16 v[116:119], v[148:151], v[164:167], v[116:119]
	v_mfma_f32_16x16x32_bf16 v[112:115], v[156:159], v[164:167], v[112:115]
	v_mfma_f32_16x16x32_bf16 v[100:103], v[148:151], v[172:175], v[100:103]
	v_mfma_f32_16x16x32_bf16 v[96:99], v[156:159], v[172:175], v[96:99]
	v_mfma_f32_16x16x32_bf16 v[84:87], v[148:151], v[180:183], v[84:87]
	v_mfma_f32_16x16x32_bf16 v[80:83], v[156:159], v[180:183], v[80:83]
	v_mfma_f32_16x16x32_bf16 v[68:71], v[148:151], v[188:191], v[68:71]
	v_mfma_f32_16x16x32_bf16 v[64:67], v[156:159], v[188:191], v[64:67]
	s_setprio 0
	s_barrier
	ds_read_b128 v[160:163], v194 offset:16384
	ds_read_b128 v[164:167], v194 offset:17408
	ds_read_b128 v[168:171], v194 offset:18432
	ds_read_b128 v[172:175], v194 offset:19456
	ds_read_b128 v[176:179], v194 offset:20480
	ds_read_b128 v[180:183], v194 offset:21504
	ds_read_b128 v[184:187], v194 offset:22528
	ds_read_b128 v[188:191], v194 offset:23552
	s_mov_b32 m0, s46
	s_nop 0
	global_load_lds_dwordx4 v245, s[34:35]
	s_add_u32 s10, s34, 0x160000
	s_mov_b32 m0, s47
	s_nop 0
	global_load_lds_dwordx4 v247, s[34:35]
	s_addc_u32 s11, s35, 0
	s_mov_b32 m0, s48
	s_nop 0
	global_load_lds_dwordx4 v245, s[10:11]
	s_nop 0
	s_mov_b32 m0, s49
	s_nop 0
	global_load_lds_dwordx4 v247, s[10:11]
	s_nop 0
	s_mov_b32 m0, s33
	s_nop 0
	global_load_lds_dwordx4 v244, s[36:37]
	s_nop 0
	s_mov_b32 m0, s50
	s_nop 0
	global_load_lds_dwordx4 v246, s[36:37]
	s_waitcnt vmcnt(8) lgkmcnt(0)
	s_setprio 1
	s_barrier
	v_mfma_f32_16x16x32_bf16 v[60:63], v[128:131], v[160:163], v[60:63]
	v_mfma_f32_16x16x32_bf16 v[56:59], v[136:139], v[160:163], v[56:59]
	v_mfma_f32_16x16x32_bf16 v[44:47], v[128:131], v[168:171], v[44:47]
	v_mfma_f32_16x16x32_bf16 v[40:43], v[136:139], v[168:171], v[40:43]
	v_mfma_f32_16x16x32_bf16 v[28:31], v[128:131], v[176:179], v[28:31]
	v_mfma_f32_16x16x32_bf16 v[24:27], v[136:139], v[176:179], v[24:27]
	v_mfma_f32_16x16x32_bf16 v[12:15], v[128:131], v[184:187], v[12:15]
	v_mfma_f32_16x16x32_bf16 v[8:11], v[136:139], v[184:187], v[8:11]
	v_mfma_f32_16x16x32_bf16 v[60:63], v[132:135], v[164:167], v[60:63]
	v_mfma_f32_16x16x32_bf16 v[56:59], v[140:143], v[164:167], v[56:59]
	v_mfma_f32_16x16x32_bf16 v[44:47], v[132:135], v[172:175], v[44:47]
	v_mfma_f32_16x16x32_bf16 v[40:43], v[140:143], v[172:175], v[40:43]
	v_mfma_f32_16x16x32_bf16 v[28:31], v[132:135], v[180:183], v[28:31]
	v_mfma_f32_16x16x32_bf16 v[24:27], v[140:143], v[180:183], v[24:27]
	v_mfma_f32_16x16x32_bf16 v[12:15], v[132:135], v[188:191], v[12:15]
	v_mfma_f32_16x16x32_bf16 v[8:11], v[140:143], v[188:191], v[8:11]
	v_mfma_f32_16x16x32_bf16 v[52:55], v[144:147], v[160:163], v[52:55]
	v_mfma_f32_16x16x32_bf16 v[48:51], v[152:155], v[160:163], v[48:51]
	v_mfma_f32_16x16x32_bf16 v[36:39], v[144:147], v[168:171], v[36:39]
	v_mfma_f32_16x16x32_bf16 v[32:35], v[152:155], v[168:171], v[32:35]
	v_mfma_f32_16x16x32_bf16 v[20:23], v[144:147], v[176:179], v[20:23]
	v_mfma_f32_16x16x32_bf16 v[16:19], v[152:155], v[176:179], v[16:19]
	v_mfma_f32_16x16x32_bf16 v[4:7], v[144:147], v[184:187], v[4:7]
	v_mfma_f32_16x16x32_bf16 v[0:3], v[152:155], v[184:187], v[0:3]
	v_mfma_f32_16x16x32_bf16 v[52:55], v[148:151], v[164:167], v[52:55]
	v_mfma_f32_16x16x32_bf16 v[48:51], v[156:159], v[164:167], v[48:51]
	v_mfma_f32_16x16x32_bf16 v[36:39], v[148:151], v[172:175], v[36:39]
	v_mfma_f32_16x16x32_bf16 v[32:35], v[156:159], v[172:175], v[32:35]
	v_mfma_f32_16x16x32_bf16 v[20:23], v[148:151], v[180:183], v[20:23]
	v_mfma_f32_16x16x32_bf16 v[16:19], v[156:159], v[180:183], v[16:19]
	v_mfma_f32_16x16x32_bf16 v[4:7], v[148:151], v[188:191], v[4:7]
	v_mfma_f32_16x16x32_bf16 v[0:3], v[156:159], v[188:191], v[0:3]
	s_setprio 0
	s_barrier
; #define PG8_STAGE(bufoff, gbase, voff) do { _Pragma("unroll") for (int _i = 0; _i < 2; ++_i) \
;         asm volatile("s_mov_b32 m0, %0\n\ts_nop 0\n\tglobal_load_lds_dwordx4 %1, %2" :: "s"(ldsb + (unsigned)((bufoff) + _i * 8192)), "v"((voff)[_i]), "s"(gbase) : "m0", "memory"); } while (0)
; #define PG8_LDA(dst, b, h) do { _Pragma("unroll") for (int m = 0; m < 4; ++m) _Pragma("unroll") for (int k = 0; k < 2; ++k) dst[m][k] = *(const PG8_LAS bf16x8*)(lds + PG8_SA(b, h) + aoff + m * 2048 + k * 1024); } while (0)
; #define PG8_LDB(dst, b, h) do { _Pragma("unroll") for (int n = 0; n < 2; ++n) _Pragma("unroll") for (int k = 0; k < 2; ++k) dst[n][k] = *(const PG8_LAS bf16x8*)(lds + PG8_SB(b, h) + boff + n * 2048 + k * 1024); } while (0)
; #define PG8_MMA(ai, bj, At, Bt) do { __builtin_amdgcn_s_setprio(1); _Pragma("unroll") for (int m = 0; m < 4; ++m) _Pragma("unroll") for (int n = 0; n < 2; ++n) _Pragma("unroll") for (int k = 0; k < 2; ++k) \
;         acc[ai][bj][m][n] = __builtin_amdgcn_mfma_f32_16x16x32_bf16(Bt[n][k], At[m][k], acc[ai][bj][m][n], 0, 0, 0); __builtin_amdgcn_s_setprio(0); } while (0)
; #define PG8_WAIT_V(n) asm volatile("s_waitcnt vmcnt(" #n ")" ::: "memory")
; #define PG8_WAIT_L(n) asm volatile("s_waitcnt lgkmcnt(" #n ")" ::: "memory")
; #define PG8_BAR __builtin_amdgcn_s_barrier()
; #define PG8_SCHED __builtin_amdgcn_sched_barrier(0)
; template <class Epi, class Sched, bool ALIGN_EPI = false, bool SP2 = false>
; __device__ __forceinline__ void gemm_phase(PG8_LAS unsigned char* lds, const Gemm g, const Sched& S, const Epi& E, const int wv) {
;     ...
;             PG8_LDB(B0, 1, 0); PG8_LDB(B1, 1, 1); PG8_SCHED; PG8_LDA(At, 1, 0); PG8_STAGE(PG8_SA(0, 1), a2 + hstepA, voffA);
;             PG8_WAIT_V(8); PG8_WAIT_L(0); PG8_BAR; PG8_MMA(0, 0, At, B0); PG8_MMA(0, 1, At, B1); PG8_BAR; PG8_SCHED;
;             PG8_LDA(At, 1, 1); PG8_STAGE(PG8_SB(1, 0), b3, voffB); PG8_STAGE(PG8_SB(1, 1), b3 + hstepB, voffB); PG8_STAGE(PG8_SA(1, 0), a3, voffA);
;             PG8_WAIT_V(8); PG8_WAIT_L(0); PG8_BAR; PG8_MMA(1, 0, At, B0); PG8_MMA(1, 1, At, B1); PG8_BAR; PG8_SCHED;
	v_add_u32_e32 v140, 0x18000, v240
	v_add_u32_e32 v156, 0x1c000, v240
	ds_read_b128 v[128:131], v140
	ds_read_b128 v[132:135], v140 offset:1024
	ds_read_b128 v[136:139], v140 offset:2048
	ds_read_b128 v[140:143], v140 offset:3072
	ds_read_b128 v[144:147], v156
	ds_read_b128 v[148:151], v156 offset:1024
	ds_read_b128 v[152:155], v156 offset:2048
	ds_read_b128 v[156:159], v156 offset:3072
	ds_read_b128 v[160:163], v194 offset:32768
	ds_read_b128 v[164:167], v194 offset:33792
	ds_read_b128 v[168:171], v194 offset:34816
	ds_read_b128 v[172:175], v194 offset:35840
	ds_read_b128 v[176:179], v194 offset:36864
	ds_read_b128 v[180:183], v194 offset:37888
	ds_read_b128 v[184:187], v194 offset:38912
	ds_read_b128 v[188:191], v194 offset:39936
	s_add_u32 s10, s36, 0x160000
	s_addc_u32 s11, s37, 0
	s_mov_b32 m0, s51
	s_nop 0
	global_load_lds_dwordx4 v244, s[10:11]
	s_nop 0
	s_mov_b32 m0, s52
	s_nop 0
	global_load_lds_dwordx4 v246, s[10:11]
	s_waitcnt vmcnt(8) lgkmcnt(0)
	s_setprio 1
	s_barrier
	v_mfma_f32_16x16x32_bf16 v[124:127], v[128:131], v[160:163], v[124:127]
	v_mfma_f32_16x16x32_bf16 v[120:123], v[136:139], v[160:163], v[120:123]
	v_mfma_f32_16x16x32_bf16 v[108:111], v[128:131], v[168:171], v[108:111]
	v_mfma_f32_16x16x32_bf16 v[104:107], v[136:139], v[168:171], v[104:107]
	v_mfma_f32_16x16x32_bf16 v[92:95], v[128:131], v[176:179], v[92:95]
	v_mfma_f32_16x16x32_bf16 v[88:91], v[136:139], v[176:179], v[88:91]
	v_mfma_f32_16x16x32_bf16 v[76:79], v[128:131], v[184:187], v[76:79]
	v_mfma_f32_16x16x32_bf16 v[72:75], v[136:139], v[184:187], v[72:75]
	v_mfma_f32_16x16x32_bf16 v[124:127], v[132:135], v[164:167], v[124:127]
	v_mfma_f32_16x16x32_bf16 v[120:123], v[140:143], v[164:167], v[120:123]
	v_mfma_f32_16x16x32_bf16 v[108:111], v[132:135], v[172:175], v[108:111]
	v_mfma_f32_16x16x32_bf16 v[104:107], v[140:143], v[172:175], v[104:107]
	v_mfma_f32_16x16x32_bf16 v[92:95], v[132:135], v[180:183], v[92:95]
	v_mfma_f32_16x16x32_bf16 v[88:91], v[140:143], v[180:183], v[88:91]
	v_mfma_f32_16x16x32_bf16 v[76:79], v[132:135], v[188:191], v[76:79]
	v_mfma_f32_16x16x32_bf16 v[72:75], v[140:143], v[188:191], v[72:75]
	v_mfma_f32_16x16x32_bf16 v[116:119], v[144:147], v[160:163], v[116:119]
	v_mfma_f32_16x16x32_bf16 v[112:115], v[152:155], v[160:163], v[112:115]
	v_mfma_f32_16x16x32_bf16 v[100:103], v[144:147], v[168:171], v[100:103]
	v_mfma_f32_16x16x32_bf16 v[96:99], v[152:155], v[168:171], v[96:99]
	v_mfma_f32_16x16x32_bf16 v[84:87], v[144:147], v[176:179], v[84:87]
	v_mfma_f32_16x16x32_bf16 v[80:83], v[152:155], v[176:179], v[80:83]
	v_mfma_f32_16x16x32_bf16 v[68:71], v[144:147], v[184:187], v[68:71]
	v_mfma_f32_16x16x32_bf16 v[64:67], v[152:155], v[184:187], v[64:67]
	v_mfma_f32_16x16x32_bf16 v[116:119], v[148:151], v[164:167], v[116:119]
	v_mfma_f32_16x16x32_bf16 v[112:115], v[156:159], v[164:167], v[112:115]
	v_mfma_f32_16x16x32_bf16 v[100:103], v[148:151], v[172:175], v[100:103]
	v_mfma_f32_16x16x32_bf16 v[96:99], v[156:159], v[172:175], v[96:99]
	v_mfma_f32_16x16x32_bf16 v[84:87], v[148:151], v[180:183], v[84:87]
	v_mfma_f32_16x16x32_bf16 v[80:83], v[156:159], v[180:183], v[80:83]
	v_mfma_f32_16x16x32_bf16 v[68:71], v[148:151], v[188:191], v[68:71]
	v_mfma_f32_16x16x32_bf16 v[64:67], v[156:159], v[188:191], v[64:67]
	s_setprio 0
	s_barrier
	ds_read_b128 v[160:163], v194 offset:49152
	ds_read_b128 v[164:167], v194 offset:50176
	ds_read_b128 v[168:171], v194 offset:51200
	ds_read_b128 v[172:175], v194 offset:52224
	ds_read_b128 v[176:179], v194 offset:53248
	ds_read_b128 v[180:183], v194 offset:54272
	ds_read_b128 v[184:187], v194 offset:55296
	ds_read_b128 v[188:191], v194 offset:56320
	s_add_u32 s10, s34, 0x80
	s_addc_u32 s11, s35, 0
	s_mov_b32 m0, s58
	s_nop 0
	global_load_lds_dwordx4 v245, s[10:11]
	s_nop 0
	s_mov_b32 m0, s60
	s_nop 0
	global_load_lds_dwordx4 v247, s[10:11]
	s_add_u32 s10, s34, 0x160080
	s_addc_u32 s11, s35, 0
	s_mov_b32 m0, s72
	s_nop 0
	global_load_lds_dwordx4 v245, s[10:11]
	s_nop 0
	s_mov_b32 m0, s77
	s_nop 0
	global_load_lds_dwordx4 v247, s[10:11]
	s_nop 0
	s_mov_b32 m0, s65
	s_nop 0
	global_load_lds_dwordx4 v244, s[30:31]
	s_nop 0
	s_mov_b32 m0, s71
	s_nop 0
	global_load_lds_dwordx4 v246, s[30:31]
	s_waitcnt vmcnt(8) lgkmcnt(0)
	s_setprio 1
	s_barrier
	v_mfma_f32_16x16x32_bf16 v[60:63], v[128:131], v[160:163], v[60:63]
	v_mfma_f32_16x16x32_bf16 v[56:59], v[136:139], v[160:163], v[56:59]
	v_mfma_f32_16x16x32_bf16 v[44:47], v[128:131], v[168:171], v[44:47]
	v_mfma_f32_16x16x32_bf16 v[40:43], v[136:139], v[168:171], v[40:43]
	v_mfma_f32_16x16x32_bf16 v[28:31], v[128:131], v[176:179], v[28:31]
	v_mfma_f32_16x16x32_bf16 v[24:27], v[136:139], v[176:179], v[24:27]
	v_mfma_f32_16x16x32_bf16 v[12:15], v[128:131], v[184:187], v[12:15]
	v_mfma_f32_16x16x32_bf16 v[8:11], v[136:139], v[184:187], v[8:11]
	v_mfma_f32_16x16x32_bf16 v[60:63], v[132:135], v[164:167], v[60:63]
	v_mfma_f32_16x16x32_bf16 v[56:59], v[140:143], v[164:167], v[56:59]
	v_mfma_f32_16x16x32_bf16 v[44:47], v[132:135], v[172:175], v[44:47]
	v_mfma_f32_16x16x32_bf16 v[40:43], v[140:143], v[172:175], v[40:43]
	v_mfma_f32_16x16x32_bf16 v[28:31], v[132:135], v[180:183], v[28:31]
	v_mfma_f32_16x16x32_bf16 v[24:27], v[140:143], v[180:183], v[24:27]
	v_mfma_f32_16x16x32_bf16 v[12:15], v[132:135], v[188:191], v[12:15]
	v_mfma_f32_16x16x32_bf16 v[8:11], v[140:143], v[188:191], v[8:11]
	v_mfma_f32_16x16x32_bf16 v[52:55], v[144:147], v[160:163], v[52:55]
	v_mfma_f32_16x16x32_bf16 v[48:51], v[152:155], v[160:163], v[48:51]
	v_mfma_f32_16x16x32_bf16 v[36:39], v[144:147], v[168:171], v[36:39]
	v_mfma_f32_16x16x32_bf16 v[32:35], v[152:155], v[168:171], v[32:35]
	v_mfma_f32_16x16x32_bf16 v[20:23], v[144:147], v[176:179], v[20:23]
	v_mfma_f32_16x16x32_bf16 v[16:19], v[152:155], v[176:179], v[16:19]
	v_mfma_f32_16x16x32_bf16 v[4:7], v[144:147], v[184:187], v[4:7]
	v_mfma_f32_16x16x32_bf16 v[0:3], v[152:155], v[184:187], v[0:3]
	v_mfma_f32_16x16x32_bf16 v[52:55], v[148:151], v[164:167], v[52:55]
	v_mfma_f32_16x16x32_bf16 v[48:51], v[156:159], v[164:167], v[48:51]
	v_mfma_f32_16x16x32_bf16 v[36:39], v[148:151], v[172:175], v[36:39]
	v_mfma_f32_16x16x32_bf16 v[32:35], v[156:159], v[172:175], v[32:35]
	v_mfma_f32_16x16x32_bf16 v[20:23], v[148:151], v[180:183], v[20:23]
	v_mfma_f32_16x16x32_bf16 v[16:19], v[156:159], v[180:183], v[16:19]
	v_mfma_f32_16x16x32_bf16 v[4:7], v[148:151], v[188:191], v[4:7]
	v_mfma_f32_16x16x32_bf16 v[0:3], v[156:159], v[188:191], v[0:3]
	s_setprio 0
	s_barrier
	s_add_u32 s62, s62, 0x100
	s_addc_u32 s79, s79, 0
	s_add_u32 s97, s97, 0x100
	s_addc_u32 vcc_lo, vcc_lo, 0
	s_cmp_ge_i32 vcc_hi, s40
	s_mov_b32 s30, vcc_hi
	s_cbranch_scc0 .LBB0_396
	s_mov_b32 s79, 0xc00000
	s_and_b64 vcc, exec, s[20:21]
	s_cbranch_vccz .LBB0_399

; #define PG8_STAGE(bufoff, gbase, voff) do { _Pragma("unroll") for (int _i = 0; _i < 2; ++_i) \
;         asm volatile("s_mov_b32 m0, %0\n\ts_nop 0\n\tglobal_load_lds_dwordx4 %1, %2" :: "s"(ldsb + (unsigned)((bufoff) + _i * 8192)), "v"((voff)[_i]), "s"(gbase) : "m0", "memory"); } while (0)
; #define PG8_LDA(dst, b, h) do { _Pragma("unroll") for (int m = 0; m < 4; ++m) _Pragma("unroll") for (int k = 0; k < 2; ++k) dst[m][k] = *(const PG8_LAS bf16x8*)(lds + PG8_SA(b, h) + aoff + m * 2048 + k * 1024); } while (0)
; #define PG8_LDB(dst, b, h) do { _Pragma("unroll") for (int n = 0; n < 2; ++n) _Pragma("unroll") for (int k = 0; k < 2; ++k) dst[n][k] = *(const PG8_LAS bf16x8*)(lds + PG8_SB(b, h) + boff + n * 2048 + k * 1024); } while (0)
; #define PG8_MMA(ai, bj, At, Bt) do { __builtin_amdgcn_s_setprio(1); _Pragma("unroll") for (int m = 0; m < 4; ++m) _Pragma("unroll") for (int n = 0; n < 2; ++n) _Pragma("unroll") for (int k = 0; k < 2; ++k) \
;         acc[ai][bj][m][n] = __builtin_amdgcn_mfma_f32_16x16x32_bf16(Bt[n][k], At[m][k], acc[ai][bj][m][n], 0, 0, 0); __builtin_amdgcn_s_setprio(0); } while (0)
; #define PG8_WAIT_V(n) asm volatile("s_waitcnt vmcnt(" #n ")" ::: "memory")
; template <class Epi, class Sched, bool ALIGN_EPI = false, bool SP2 = false>
; __device__ __forceinline__ void gemm_phase(PG8_LAS unsigned char* lds, const Gemm g, const Sched& S, const Epi& E, const int wv) {
;     ...
;         for (int t = 0; t < nt; t += 2) {
;             const bool last = (t == nt - 2);
;             const char* a1 = cA + (size_t)(t + 1) * kstep;
;             const char* a2 = last ? nA : cA + (size_t)(t + 2) * kstep; const char* b2 = last ? nB : cB + (size_t)(t + 2) * kstep;
;             const char* a3 = a2 + kstep; const char* b3 = b2 + kstep;
;             if (last && has_next) S.a_ready(nxt);
;             if constexpr (SP2) {
;             PG8_LDB(B0, 0, 0); PG8_LDB(B1, 0, 1); PG8_SCHED; PG8_LDA(At, 0, 0); PG8_STAGE(PG8_SA(1, 1), a1 + hstepA, voffA);
;             PG8_WAIT_V(8); PG8_WAIT_L(0); PG8_BAR; PG8_MMA(0, 0, At, B0); PG8_MMA(0, 1, At, B1); PG8_BAR; PG8_SCHED;
;             PG8_LDA(At, 0, 1); PG8_STAGE(PG8_SB(0, 0), b2, voffB); PG8_STAGE(PG8_SB(0, 1), b2 + hstepB, voffB); PG8_STAGE(PG8_SA(0, 0), a2, voffA);
;             PG8_WAIT_V(8); PG8_WAIT_L(0); PG8_BAR; PG8_MMA(1, 0, At, B0); PG8_MMA(1, 1, At, B1); PG8_BAR; PG8_SCHED;
.LBB0_563:
	v_add_u32_e32 v140, 0x10000, v166
	v_add_u32_e32 v148, 0x14000, v166
	ds_read_b128 v[128:131], v140
	ds_read_b128 v[132:135], v140 offset:1024
	ds_read_b128 v[136:139], v140 offset:2048
	ds_read_b128 v[140:143], v140 offset:3072
	ds_read_b128 v[168:171], v148
	ds_read_b128 v[172:175], v148 offset:1024
	ds_read_b128 v[176:179], v148 offset:2048
	ds_read_b128 v[180:183], v148 offset:3072
	s_add_i32 s92, s24, 2
	s_cmp_eq_u32 s62, s24
	s_cselect_b32 s28, s20, s79
	s_cselect_b32 s29, s21, s88
	s_cselect_b32 s26, s87, s89
	s_cselect_b32 s27, s86, s90
	s_add_u32 s24, s28, 0x80
	s_addc_u32 s25, s29, 0
	ds_read_b128 v[184:187], v167
	ds_read_b128 v[188:191], v167 offset:1024
	ds_read_b128 v[194:197], v167 offset:2048
	ds_read_b128 v[198:201], v167 offset:3072
	ds_read_b128 v[202:205], v167 offset:4096
	ds_read_b128 v[206:209], v167 offset:5120
	ds_read_b128 v[210:213], v167 offset:6144
	ds_read_b128 v[214:217], v167 offset:7168
	s_add_u32 s96, s79, 0x83f80
	s_addc_u32 s97, s88, 0
	s_mov_b32 m0, s57
	s_nop 0
	global_load_lds_dwordx4 v147, s[96:97]
	s_nop 0
	s_mov_b32 m0, s58
	s_nop 0
	global_load_lds_dwordx4 v153, s[96:97]
	s_waitcnt vmcnt(8) lgkmcnt(0)
	s_setprio 1
	s_barrier
	v_mfma_f32_16x16x32_bf16 v[124:127], v[128:131], v[184:187], v[124:127]
	v_mfma_f32_16x16x32_bf16 v[120:123], v[136:139], v[184:187], v[120:123]
	v_mfma_f32_16x16x32_bf16 v[108:111], v[128:131], v[194:197], v[108:111]
	v_mfma_f32_16x16x32_bf16 v[104:107], v[136:139], v[194:197], v[104:107]
	v_mfma_f32_16x16x32_bf16 v[92:95], v[128:131], v[202:205], v[92:95]
	v_mfma_f32_16x16x32_bf16 v[88:91], v[136:139], v[202:205], v[88:91]
	v_mfma_f32_16x16x32_bf16 v[76:79], v[128:131], v[210:213], v[76:79]
	v_mfma_f32_16x16x32_bf16 v[72:75], v[136:139], v[210:213], v[72:75]
	v_mfma_f32_16x16x32_bf16 v[124:127], v[132:135], v[188:191], v[124:127]
	v_mfma_f32_16x16x32_bf16 v[120:123], v[140:143], v[188:191], v[120:123]
	v_mfma_f32_16x16x32_bf16 v[108:111], v[132:135], v[198:201], v[108:111]
	v_mfma_f32_16x16x32_bf16 v[104:107], v[140:143], v[198:201], v[104:107]
	v_mfma_f32_16x16x32_bf16 v[92:95], v[132:135], v[206:209], v[92:95]
	v_mfma_f32_16x16x32_bf16 v[88:91], v[140:143], v[206:209], v[88:91]
	v_mfma_f32_16x16x32_bf16 v[76:79], v[132:135], v[214:217], v[76:79]
	v_mfma_f32_16x16x32_bf16 v[72:75], v[140:143], v[214:217], v[72:75]
	v_mfma_f32_16x16x32_bf16 v[116:119], v[168:171], v[184:187], v[116:119]
	v_mfma_f32_16x16x32_bf16 v[112:115], v[176:179], v[184:187], v[112:115]
	v_mfma_f32_16x16x32_bf16 v[100:103], v[168:171], v[194:197], v[100:103]
	v_mfma_f32_16x16x32_bf16 v[96:99], v[176:179], v[194:197], v[96:99]
	v_mfma_f32_16x16x32_bf16 v[84:87], v[168:171], v[202:205], v[84:87]
	v_mfma_f32_16x16x32_bf16 v[80:83], v[176:179], v[202:205], v[80:83]
	v_mfma_f32_16x16x32_bf16 v[68:71], v[168:171], v[210:213], v[68:71]
	v_mfma_f32_16x16x32_bf16 v[64:67], v[176:179], v[210:213], v[64:67]
	v_mfma_f32_16x16x32_bf16 v[116:119], v[172:175], v[188:191], v[116:119]
	v_mfma_f32_16x16x32_bf16 v[112:115], v[180:183], v[188:191], v[112:115]
	v_mfma_f32_16x16x32_bf16 v[100:103], v[172:175], v[198:201], v[100:103]
	v_mfma_f32_16x16x32_bf16 v[96:99], v[180:183], v[198:201], v[96:99]
	v_mfma_f32_16x16x32_bf16 v[84:87], v[172:175], v[206:209], v[84:87]
	v_mfma_f32_16x16x32_bf16 v[80:83], v[180:183], v[206:209], v[80:83]
	v_mfma_f32_16x16x32_bf16 v[68:71], v[172:175], v[214:217], v[68:71]
	v_mfma_f32_16x16x32_bf16 v[64:67], v[180:183], v[214:217], v[64:67]
	s_setprio 0
	s_barrier
	ds_read_b128 v[184:187], v167 offset:16384
	ds_read_b128 v[188:191], v167 offset:17408
	ds_read_b128 v[194:197], v167 offset:18432
	ds_read_b128 v[198:201], v167 offset:19456
	ds_read_b128 v[202:205], v167 offset:20480
	ds_read_b128 v[206:209], v167 offset:21504
	ds_read_b128 v[210:213], v167 offset:22528
	ds_read_b128 v[214:217], v167 offset:23552
	s_mov_b32 m0, s34
	s_nop 0
	global_load_lds_dwordx4 v151, s[26:27]
	s_add_u32 s96, s26, 0x80000
	s_mov_b32 m0, s35
	s_nop 0
	global_load_lds_dwordx4 v155, s[26:27]
	s_addc_u32 s97, s27, 0
	s_mov_b32 m0, s36
	s_nop 0
	global_load_lds_dwordx4 v151, s[96:97]
	s_nop 0
	s_mov_b32 m0, s37
	s_nop 0
	global_load_lds_dwordx4 v155, s[96:97]
	s_nop 0
	s_mov_b32 m0, s33
	s_nop 0
	global_load_lds_dwordx4 v147, s[28:29]
	s_nop 0
	s_mov_b32 m0, s44
	s_nop 0
	global_load_lds_dwordx4 v153, s[28:29]
	s_waitcnt vmcnt(8) lgkmcnt(0)
	s_setprio 1
	s_barrier
	v_mfma_f32_16x16x32_bf16 v[60:63], v[128:131], v[184:187], v[60:63]
	v_mfma_f32_16x16x32_bf16 v[56:59], v[136:139], v[184:187], v[56:59]
	v_mfma_f32_16x16x32_bf16 v[44:47], v[128:131], v[194:197], v[44:47]
	v_mfma_f32_16x16x32_bf16 v[40:43], v[136:139], v[194:197], v[40:43]
	v_mfma_f32_16x16x32_bf16 v[28:31], v[128:131], v[202:205], v[28:31]
	v_mfma_f32_16x16x32_bf16 v[24:27], v[136:139], v[202:205], v[24:27]
	v_mfma_f32_16x16x32_bf16 v[12:15], v[128:131], v[210:213], v[12:15]
	v_mfma_f32_16x16x32_bf16 v[8:11], v[136:139], v[210:213], v[8:11]
	v_mfma_f32_16x16x32_bf16 v[60:63], v[132:135], v[188:191], v[60:63]
	v_mfma_f32_16x16x32_bf16 v[56:59], v[140:143], v[188:191], v[56:59]
	v_mfma_f32_16x16x32_bf16 v[44:47], v[132:135], v[198:201], v[44:47]
	v_mfma_f32_16x16x32_bf16 v[40:43], v[140:143], v[198:201], v[40:43]
	v_mfma_f32_16x16x32_bf16 v[28:31], v[132:135], v[206:209], v[28:31]
	v_mfma_f32_16x16x32_bf16 v[24:27], v[140:143], v[206:209], v[24:27]
	v_mfma_f32_16x16x32_bf16 v[12:15], v[132:135], v[214:217], v[12:15]
	v_mfma_f32_16x16x32_bf16 v[8:11], v[140:143], v[214:217], v[8:11]
	v_mfma_f32_16x16x32_bf16 v[52:55], v[168:171], v[184:187], v[52:55]
	v_mfma_f32_16x16x32_bf16 v[48:51], v[176:179], v[184:187], v[48:51]
	v_mfma_f32_16x16x32_bf16 v[36:39], v[168:171], v[194:197], v[36:39]
	v_mfma_f32_16x16x32_bf16 v[32:35], v[176:179], v[194:197], v[32:35]
	v_mfma_f32_16x16x32_bf16 v[20:23], v[168:171], v[202:205], v[20:23]
	v_mfma_f32_16x16x32_bf16 v[16:19], v[176:179], v[202:205], v[16:19]
	v_mfma_f32_16x16x32_bf16 v[4:7], v[168:171], v[210:213], v[4:7]
	v_mfma_f32_16x16x32_bf16 v[0:3], v[176:179], v[210:213], v[0:3]
	v_mfma_f32_16x16x32_bf16 v[52:55], v[172:175], v[188:191], v[52:55]
	v_mfma_f32_16x16x32_bf16 v[48:51], v[180:183], v[188:191], v[48:51]
	v_mfma_f32_16x16x32_bf16 v[36:39], v[172:175], v[198:201], v[36:39]
	v_mfma_f32_16x16x32_bf16 v[32:35], v[180:183], v[198:201], v[32:35]
	v_mfma_f32_16x16x32_bf16 v[20:23], v[172:175], v[206:209], v[20:23]
	v_mfma_f32_16x16x32_bf16 v[16:19], v[180:183], v[206:209], v[16:19]
	v_mfma_f32_16x16x32_bf16 v[4:7], v[172:175], v[214:217], v[4:7]
	v_mfma_f32_16x16x32_bf16 v[0:3], v[180:183], v[214:217], v[0:3]
	s_setprio 0
	s_barrier
; #define PG8_STAGE(bufoff, gbase, voff) do { _Pragma("unroll") for (int _i = 0; _i < 2; ++_i) \
;         asm volatile("s_mov_b32 m0, %0\n\ts_nop 0\n\tglobal_load_lds_dwordx4 %1, %2" :: "s"(ldsb + (unsigned)((bufoff) + _i * 8192)), "v"((voff)[_i]), "s"(gbase) : "m0", "memory"); } while (0)
; #define PG8_LDA(dst, b, h) do { _Pragma("unroll") for (int m = 0; m < 4; ++m) _Pragma("unroll") for (int k = 0; k < 2; ++k) dst[m][k] = *(const PG8_LAS bf16x8*)(lds + PG8_SA(b, h) + aoff + m * 2048 + k * 1024); } while (0)
; #define PG8_LDB(dst, b, h) do { _Pragma("unroll") for (int n = 0; n < 2; ++n) _Pragma("unroll") for (int k = 0; k < 2; ++k) dst[n][k] = *(const PG8_LAS bf16x8*)(lds + PG8_SB(b, h) + boff + n * 2048 + k * 1024); } while (0)
; #define PG8_MMA(ai, bj, At, Bt) do { __builtin_amdgcn_s_setprio(1); _Pragma("unroll") for (int m = 0; m < 4; ++m) _Pragma("unroll") for (int n = 0; n < 2; ++n) _Pragma("unroll") for (int k = 0; k < 2; ++k) \
;         acc[ai][bj][m][n] = __builtin_amdgcn_mfma_f32_16x16x32_bf16(Bt[n][k], At[m][k], acc[ai][bj][m][n], 0, 0, 0); __builtin_amdgcn_s_setprio(0); } while (0)
; #define PG8_WAIT_V(n) asm volatile("s_waitcnt vmcnt(" #n ")" ::: "memory")
; #define PG8_WAIT_L(n) asm volatile("s_waitcnt lgkmcnt(" #n ")" ::: "memory")
; #define PG8_BAR __builtin_amdgcn_s_barrier()
; #define PG8_SCHED __builtin_amdgcn_sched_barrier(0)
; template <class Epi, class Sched, bool ALIGN_EPI = false, bool SP2 = false>
; __device__ __forceinline__ void gemm_phase(PG8_LAS unsigned char* lds, const Gemm g, const Sched& S, const Epi& E, const int wv) {
;     ...
;             PG8_LDB(B0, 1, 0); PG8_LDB(B1, 1, 1); PG8_SCHED; PG8_LDA(At, 1, 0); PG8_STAGE(PG8_SA(0, 1), a2 + hstepA, voffA);
;             PG8_WAIT_V(8); PG8_WAIT_L(0); PG8_BAR; PG8_MMA(0, 0, At, B0); PG8_MMA(0, 1, At, B1); PG8_BAR; PG8_SCHED;
;             PG8_LDA(At, 1, 1); PG8_STAGE(PG8_SB(1, 0), b3, voffB); PG8_STAGE(PG8_SB(1, 1), b3 + hstepB, voffB); PG8_STAGE(PG8_SA(1, 0), a3, voffA);
;             PG8_WAIT_V(8); PG8_WAIT_L(0); PG8_BAR; PG8_MMA(1, 0, At, B0); PG8_MMA(1, 1, At, B1); PG8_BAR; PG8_SCHED;
	v_add_u32_e32 v140, 0x18000, v166
	v_add_u32_e32 v148, 0x1c000, v166
	ds_read_b128 v[128:131], v140
	ds_read_b128 v[132:135], v140 offset:1024
	ds_read_b128 v[136:139], v140 offset:2048
	ds_read_b128 v[140:143], v140 offset:3072
	ds_read_b128 v[168:171], v148
	ds_read_b128 v[172:175], v148 offset:1024
	ds_read_b128 v[176:179], v148 offset:2048
	ds_read_b128 v[180:183], v148 offset:3072
	ds_read_b128 v[184:187], v167 offset:32768
	ds_read_b128 v[188:191], v167 offset:33792
	ds_read_b128 v[194:197], v167 offset:34816
	ds_read_b128 v[198:201], v167 offset:35840
	ds_read_b128 v[202:205], v167 offset:36864
	ds_read_b128 v[206:209], v167 offset:37888
	ds_read_b128 v[210:213], v167 offset:38912
	ds_read_b128 v[214:217], v167 offset:39936
	s_add_u32 s28, s28, 0x84000
	s_addc_u32 s29, s29, 0
	s_mov_b32 m0, s45
	s_nop 0
	global_load_lds_dwordx4 v147, s[28:29]
	s_nop 0
	s_mov_b32 m0, s46
	s_nop 0
	global_load_lds_dwordx4 v153, s[28:29]
	s_waitcnt vmcnt(8) lgkmcnt(0)
	s_setprio 1
	s_barrier
	v_mfma_f32_16x16x32_bf16 v[124:127], v[128:131], v[184:187], v[124:127]
	v_mfma_f32_16x16x32_bf16 v[120:123], v[136:139], v[184:187], v[120:123]
	v_mfma_f32_16x16x32_bf16 v[108:111], v[128:131], v[194:197], v[108:111]
	v_mfma_f32_16x16x32_bf16 v[104:107], v[136:139], v[194:197], v[104:107]
	v_mfma_f32_16x16x32_bf16 v[92:95], v[128:131], v[202:205], v[92:95]
	v_mfma_f32_16x16x32_bf16 v[88:91], v[136:139], v[202:205], v[88:91]
	v_mfma_f32_16x16x32_bf16 v[76:79], v[128:131], v[210:213], v[76:79]
	v_mfma_f32_16x16x32_bf16 v[72:75], v[136:139], v[210:213], v[72:75]
	v_mfma_f32_16x16x32_bf16 v[124:127], v[132:135], v[188:191], v[124:127]
	v_mfma_f32_16x16x32_bf16 v[120:123], v[140:143], v[188:191], v[120:123]
	v_mfma_f32_16x16x32_bf16 v[108:111], v[132:135], v[198:201], v[108:111]
	v_mfma_f32_16x16x32_bf16 v[104:107], v[140:143], v[198:201], v[104:107]
	v_mfma_f32_16x16x32_bf16 v[92:95], v[132:135], v[206:209], v[92:95]
	v_mfma_f32_16x16x32_bf16 v[88:91], v[140:143], v[206:209], v[88:91]
	v_mfma_f32_16x16x32_bf16 v[76:79], v[132:135], v[214:217], v[76:79]
	v_mfma_f32_16x16x32_bf16 v[72:75], v[140:143], v[214:217], v[72:75]
	v_mfma_f32_16x16x32_bf16 v[116:119], v[168:171], v[184:187], v[116:119]
	v_mfma_f32_16x16x32_bf16 v[112:115], v[176:179], v[184:187], v[112:115]
	v_mfma_f32_16x16x32_bf16 v[100:103], v[168:171], v[194:197], v[100:103]
	v_mfma_f32_16x16x32_bf16 v[96:99], v[176:179], v[194:197], v[96:99]
	v_mfma_f32_16x16x32_bf16 v[84:87], v[168:171], v[202:205], v[84:87]
	v_mfma_f32_16x16x32_bf16 v[80:83], v[176:179], v[202:205], v[80:83]
	v_mfma_f32_16x16x32_bf16 v[68:71], v[168:171], v[210:213], v[68:71]
	v_mfma_f32_16x16x32_bf16 v[64:67], v[176:179], v[210:213], v[64:67]
	v_mfma_f32_16x16x32_bf16 v[116:119], v[172:175], v[188:191], v[116:119]
	v_mfma_f32_16x16x32_bf16 v[112:115], v[180:183], v[188:191], v[112:115]
	v_mfma_f32_16x16x32_bf16 v[100:103], v[172:175], v[198:201], v[100:103]
	v_mfma_f32_16x16x32_bf16 v[96:99], v[180:183], v[198:201], v[96:99]
	v_mfma_f32_16x16x32_bf16 v[84:87], v[172:175], v[206:209], v[84:87]
	v_mfma_f32_16x16x32_bf16 v[80:83], v[180:183], v[206:209], v[80:83]
	v_mfma_f32_16x16x32_bf16 v[68:71], v[172:175], v[214:217], v[68:71]
	v_mfma_f32_16x16x32_bf16 v[64:67], v[180:183], v[214:217], v[64:67]
	s_setprio 0
	s_barrier
	ds_read_b128 v[184:187], v167 offset:49152
	ds_read_b128 v[188:191], v167 offset:50176
	ds_read_b128 v[194:197], v167 offset:51200
	ds_read_b128 v[198:201], v167 offset:52224
	ds_read_b128 v[202:205], v167 offset:53248
	ds_read_b128 v[206:209], v167 offset:54272
	ds_read_b128 v[210:213], v167 offset:55296
	ds_read_b128 v[214:217], v167 offset:56320
	s_add_u32 s28, s26, 0x80
	s_addc_u32 s29, s27, 0
	s_mov_b32 m0, s51
	s_nop 0
	global_load_lds_dwordx4 v151, s[28:29]
	s_add_u32 s26, s26, 0x80080
	s_mov_b32 m0, s52
	s_nop 0
	global_load_lds_dwordx4 v155, s[28:29]
	s_addc_u32 s27, s27, 0
	s_mov_b32 m0, s55
	s_nop 0
	global_load_lds_dwordx4 v151, s[26:27]
	s_nop 0
	s_mov_b32 m0, s56
	s_nop 0
	global_load_lds_dwordx4 v155, s[26:27]
	s_nop 0
	s_mov_b32 m0, s53
	s_nop 0
	global_load_lds_dwordx4 v147, s[24:25]
	s_nop 0
	s_mov_b32 m0, s54
	s_nop 0
	global_load_lds_dwordx4 v153, s[24:25]
	s_waitcnt vmcnt(8) lgkmcnt(0)
	s_setprio 1
	s_barrier
	v_mfma_f32_16x16x32_bf16 v[60:63], v[128:131], v[184:187], v[60:63]
	v_mfma_f32_16x16x32_bf16 v[56:59], v[136:139], v[184:187], v[56:59]
	v_mfma_f32_16x16x32_bf16 v[44:47], v[128:131], v[194:197], v[44:47]
	v_mfma_f32_16x16x32_bf16 v[40:43], v[136:139], v[194:197], v[40:43]
	v_mfma_f32_16x16x32_bf16 v[28:31], v[128:131], v[202:205], v[28:31]
	v_mfma_f32_16x16x32_bf16 v[24:27], v[136:139], v[202:205], v[24:27]
	v_mfma_f32_16x16x32_bf16 v[12:15], v[128:131], v[210:213], v[12:15]
	v_mfma_f32_16x16x32_bf16 v[8:11], v[136:139], v[210:213], v[8:11]
	v_mfma_f32_16x16x32_bf16 v[60:63], v[132:135], v[188:191], v[60:63]
	v_mfma_f32_16x16x32_bf16 v[56:59], v[140:143], v[188:191], v[56:59]
	v_mfma_f32_16x16x32_bf16 v[44:47], v[132:135], v[198:201], v[44:47]
	v_mfma_f32_16x16x32_bf16 v[40:43], v[140:143], v[198:201], v[40:43]
	v_mfma_f32_16x16x32_bf16 v[28:31], v[132:135], v[206:209], v[28:31]
	v_mfma_f32_16x16x32_bf16 v[24:27], v[140:143], v[206:209], v[24:27]
	v_mfma_f32_16x16x32_bf16 v[12:15], v[132:135], v[214:217], v[12:15]
	v_mfma_f32_16x16x32_bf16 v[8:11], v[140:143], v[214:217], v[8:11]
	v_mfma_f32_16x16x32_bf16 v[52:55], v[168:171], v[184:187], v[52:55]
	v_mfma_f32_16x16x32_bf16 v[48:51], v[176:179], v[184:187], v[48:51]
	v_mfma_f32_16x16x32_bf16 v[36:39], v[168:171], v[194:197], v[36:39]
	v_mfma_f32_16x16x32_bf16 v[32:35], v[176:179], v[194:197], v[32:35]
	v_mfma_f32_16x16x32_bf16 v[20:23], v[168:171], v[202:205], v[20:23]
	v_mfma_f32_16x16x32_bf16 v[16:19], v[176:179], v[202:205], v[16:19]
	v_mfma_f32_16x16x32_bf16 v[4:7], v[168:171], v[210:213], v[4:7]
	v_mfma_f32_16x16x32_bf16 v[0:3], v[176:179], v[210:213], v[0:3]
	v_mfma_f32_16x16x32_bf16 v[52:55], v[172:175], v[188:191], v[52:55]
	v_mfma_f32_16x16x32_bf16 v[48:51], v[180:183], v[188:191], v[48:51]
	v_mfma_f32_16x16x32_bf16 v[36:39], v[172:175], v[198:201], v[36:39]
	v_mfma_f32_16x16x32_bf16 v[32:35], v[180:183], v[198:201], v[32:35]
	v_mfma_f32_16x16x32_bf16 v[20:23], v[172:175], v[206:209], v[20:23]
	v_mfma_f32_16x16x32_bf16 v[16:19], v[180:183], v[206:209], v[16:19]
	v_mfma_f32_16x16x32_bf16 v[4:7], v[172:175], v[214:217], v[4:7]
	v_mfma_f32_16x16x32_bf16 v[0:3], v[180:183], v[214:217], v[0:3]
	s_setprio 0
	s_barrier
	s_add_u32 s79, s79, 0x100
	s_addc_u32 s88, s88, 0
	s_add_u32 s89, s89, 0x100
	s_addc_u32 s90, s90, 0
	s_cmp_ge_i32 s92, s85
	s_mov_b32 s24, s92
	s_cbranch_scc0 .LBB0_563
	v_readlane_b32 s96, v254, 47
	v_readlane_b32 s97, v254, 48
	v_readlane_b32 s90, v254, 52
	s_mov_b32 s79, 0xc00000
	s_branch .LBB0_566

; #define PG8_STAGE(bufoff, gbase, voff) do { _Pragma("unroll") for (int _i = 0; _i < 2; ++_i) \
;         asm volatile("s_mov_b32 m0, %0\n\ts_nop 0\n\tglobal_load_lds_dwordx4 %1, %2" :: "s"(ldsb + (unsigned)((bufoff) + _i * 8192)), "v"((voff)[_i]), "s"(gbase) : "m0", "memory"); } while (0)
; #define PG8_LDA(dst, b, h) do { _Pragma("unroll") for (int m = 0; m < 4; ++m) _Pragma("unroll") for (int k = 0; k < 2; ++k) dst[m][k] = *(const PG8_LAS bf16x8*)(lds + PG8_SA(b, h) + aoff + m * 2048 + k * 1024); } while (0)
; #define PG8_LDB(dst, b, h) do { _Pragma("unroll") for (int n = 0; n < 2; ++n) _Pragma("unroll") for (int k = 0; k < 2; ++k) dst[n][k] = *(const PG8_LAS bf16x8*)(lds + PG8_SB(b, h) + boff + n * 2048 + k * 1024); } while (0)
; #define PG8_MMA(ai, bj, At, Bt) do { __builtin_amdgcn_s_setprio(1); _Pragma("unroll") for (int m = 0; m < 4; ++m) _Pragma("unroll") for (int n = 0; n < 2; ++n) _Pragma("unroll") for (int k = 0; k < 2; ++k) \
;         acc[ai][bj][m][n] = __builtin_amdgcn_mfma_f32_16x16x32_bf16(Bt[n][k], At[m][k], acc[ai][bj][m][n], 0, 0, 0); __builtin_amdgcn_s_setprio(0); } while (0)
; #define PG8_WAIT_V(n) asm volatile("s_waitcnt vmcnt(" #n ")" ::: "memory")
; template <class Epi, class Sched, bool ALIGN_EPI = false, bool SP2 = false>
; __device__ __forceinline__ void gemm_phase(PG8_LAS unsigned char* lds, const Gemm g, const Sched& S, const Epi& E, const int wv) {
;     ...
;         for (int t = 0; t < nt; t += 2) {
;             const bool last = (t == nt - 2);
;             const char* a1 = cA + (size_t)(t + 1) * kstep;
;             const char* a2 = last ? nA : cA + (size_t)(t + 2) * kstep; const char* b2 = last ? nB : cB + (size_t)(t + 2) * kstep;
;             const char* a3 = a2 + kstep; const char* b3 = b2 + kstep;
;             if (last && has_next) S.a_ready(nxt);
;             if constexpr (SP2) {
;             PG8_LDB(B0, 0, 0); PG8_LDB(B1, 0, 1); PG8_SCHED; PG8_LDA(At, 0, 0); PG8_STAGE(PG8_SA(1, 1), a1 + hstepA, voffA);
;             PG8_WAIT_V(8); PG8_WAIT_L(0); PG8_BAR; PG8_MMA(0, 0, At, B0); PG8_MMA(0, 1, At, B1); PG8_BAR; PG8_SCHED;
;             PG8_LDA(At, 0, 1); PG8_STAGE(PG8_SB(0, 0), b2, voffB); PG8_STAGE(PG8_SB(0, 1), b2 + hstepB, voffB); PG8_STAGE(PG8_SA(0, 0), a2, voffA);
;             PG8_WAIT_V(8); PG8_WAIT_L(0); PG8_BAR; PG8_MMA(1, 0, At, B0); PG8_MMA(1, 1, At, B1); PG8_BAR; PG8_SCHED;
.LBB0_756:
	v_add_u32_e32 v141, 0x10000, v139
	ds_read_b128 v[142:145], v141
	ds_read_b128 v[146:149], v141 offset:1024
	ds_read_b128 v[150:153], v141 offset:2048
	ds_read_b128 v[154:157], v141 offset:3072
	v_add_u32_e32 v141, 0x14000, v139
	ds_read_b128 v[158:161], v141
	ds_read_b128 v[162:165], v141 offset:1024
	ds_read_b128 v[166:169], v141 offset:2048
	ds_read_b128 v[170:173], v141 offset:3072
	s_add_i32 s79, s24, 2
	s_cmp_eq_u32 s60, s24
	s_cselect_b32 s28, s18, s62
	s_cselect_b32 s29, s19, s65
	s_cselect_b32 s26, s58, s71
	s_cselect_b32 s27, s56, s77
	s_add_u32 s24, s28, 0x80
	s_addc_u32 s25, s29, 0
	ds_read_b128 v[174:177], v140
	ds_read_b128 v[178:181], v140 offset:1024
	ds_read_b128 v[182:185], v140 offset:2048
	ds_read_b128 v[186:189], v140 offset:3072
	ds_read_b128 v[194:197], v140 offset:4096
	ds_read_b128 v[198:201], v140 offset:5120
	ds_read_b128 v[202:205], v140 offset:6144
	ds_read_b128 v[206:209], v140 offset:7168
	s_add_u32 s88, s62, 0x1ff80
	s_addc_u32 s89, s65, 0
	s_mov_b32 m0, s55
	s_nop 0
	global_load_lds_dwordx4 v128, s[88:89]
	s_nop 0
	s_mov_b32 m0, s87
	s_nop 0
	global_load_lds_dwordx4 v130, s[88:89]
	s_waitcnt vmcnt(8) lgkmcnt(0)
	s_setprio 1
	s_barrier
	v_mfma_f32_16x16x32_bf16 v[124:127], v[142:145], v[174:177], v[124:127]
	v_mfma_f32_16x16x32_bf16 v[120:123], v[150:153], v[174:177], v[120:123]
	v_mfma_f32_16x16x32_bf16 v[116:119], v[142:145], v[182:185], v[116:119]
	v_mfma_f32_16x16x32_bf16 v[112:115], v[150:153], v[182:185], v[112:115]
	v_mfma_f32_16x16x32_bf16 v[108:111], v[142:145], v[194:197], v[108:111]
	v_mfma_f32_16x16x32_bf16 v[104:107], v[150:153], v[194:197], v[104:107]
	v_mfma_f32_16x16x32_bf16 v[100:103], v[142:145], v[202:205], v[100:103]
	v_mfma_f32_16x16x32_bf16 v[96:99], v[150:153], v[202:205], v[96:99]
	v_mfma_f32_16x16x32_bf16 v[124:127], v[146:149], v[178:181], v[124:127]
	v_mfma_f32_16x16x32_bf16 v[120:123], v[154:157], v[178:181], v[120:123]
	v_mfma_f32_16x16x32_bf16 v[116:119], v[146:149], v[186:189], v[116:119]
	v_mfma_f32_16x16x32_bf16 v[112:115], v[154:157], v[186:189], v[112:115]
	v_mfma_f32_16x16x32_bf16 v[108:111], v[146:149], v[198:201], v[108:111]
	v_mfma_f32_16x16x32_bf16 v[104:107], v[154:157], v[198:201], v[104:107]
	v_mfma_f32_16x16x32_bf16 v[100:103], v[146:149], v[206:209], v[100:103]
	v_mfma_f32_16x16x32_bf16 v[96:99], v[154:157], v[206:209], v[96:99]
	v_mfma_f32_16x16x32_bf16 v[60:63], v[158:161], v[174:177], v[60:63]
	v_mfma_f32_16x16x32_bf16 v[56:59], v[166:169], v[174:177], v[56:59]
	v_mfma_f32_16x16x32_bf16 v[52:55], v[158:161], v[182:185], v[52:55]
	v_mfma_f32_16x16x32_bf16 v[48:51], v[166:169], v[182:185], v[48:51]
	v_mfma_f32_16x16x32_bf16 v[44:47], v[158:161], v[194:197], v[44:47]
	v_mfma_f32_16x16x32_bf16 v[40:43], v[166:169], v[194:197], v[40:43]
	v_mfma_f32_16x16x32_bf16 v[36:39], v[158:161], v[202:205], v[36:39]
	v_mfma_f32_16x16x32_bf16 v[32:35], v[166:169], v[202:205], v[32:35]
	v_mfma_f32_16x16x32_bf16 v[60:63], v[162:165], v[178:181], v[60:63]
	v_mfma_f32_16x16x32_bf16 v[56:59], v[170:173], v[178:181], v[56:59]
	v_mfma_f32_16x16x32_bf16 v[52:55], v[162:165], v[186:189], v[52:55]
	v_mfma_f32_16x16x32_bf16 v[48:51], v[170:173], v[186:189], v[48:51]
	v_mfma_f32_16x16x32_bf16 v[44:47], v[162:165], v[198:201], v[44:47]
	v_mfma_f32_16x16x32_bf16 v[40:43], v[170:173], v[198:201], v[40:43]
	v_mfma_f32_16x16x32_bf16 v[36:39], v[162:165], v[206:209], v[36:39]
	v_mfma_f32_16x16x32_bf16 v[32:35], v[170:173], v[206:209], v[32:35]
	s_setprio 0
	s_barrier
	ds_read_b128 v[174:177], v140 offset:16384
	ds_read_b128 v[178:181], v140 offset:17408
	ds_read_b128 v[182:185], v140 offset:18432
	ds_read_b128 v[186:189], v140 offset:19456
	ds_read_b128 v[194:197], v140 offset:20480
	ds_read_b128 v[198:201], v140 offset:21504
	ds_read_b128 v[202:205], v140 offset:22528
	ds_read_b128 v[206:209], v140 offset:23552
	s_mov_b32 m0, s37
	s_nop 0
	global_load_lds_dwordx4 v129, s[26:27]
	s_add_u32 s88, s26, 0x20000
	s_mov_b32 m0, s42
	s_nop 0
	global_load_lds_dwordx4 v131, s[26:27]
	s_addc_u32 s89, s27, 0
	s_mov_b32 m0, s43
	s_nop 0
	global_load_lds_dwordx4 v129, s[88:89]
	s_nop 0
	s_mov_b32 m0, s44
	s_nop 0
	global_load_lds_dwordx4 v131, s[88:89]
	s_nop 0
	s_mov_b32 m0, s36
	s_nop 0
	global_load_lds_dwordx4 v128, s[28:29]
	s_nop 0
	s_mov_b32 m0, s45
	s_nop 0
	global_load_lds_dwordx4 v130, s[28:29]
	s_waitcnt vmcnt(8) lgkmcnt(0)
	s_setprio 1
	s_barrier
	v_mfma_f32_16x16x32_bf16 v[92:95], v[142:145], v[174:177], v[92:95]
	v_mfma_f32_16x16x32_bf16 v[88:91], v[150:153], v[174:177], v[88:91]
	v_mfma_f32_16x16x32_bf16 v[84:87], v[142:145], v[182:185], v[84:87]
	v_mfma_f32_16x16x32_bf16 v[80:83], v[150:153], v[182:185], v[80:83]
	v_mfma_f32_16x16x32_bf16 v[76:79], v[142:145], v[194:197], v[76:79]
	v_mfma_f32_16x16x32_bf16 v[72:75], v[150:153], v[194:197], v[72:75]
	v_mfma_f32_16x16x32_bf16 v[68:71], v[142:145], v[202:205], v[68:71]
	v_mfma_f32_16x16x32_bf16 v[64:67], v[150:153], v[202:205], v[64:67]
	v_mfma_f32_16x16x32_bf16 v[92:95], v[146:149], v[178:181], v[92:95]
	v_mfma_f32_16x16x32_bf16 v[88:91], v[154:157], v[178:181], v[88:91]
	v_mfma_f32_16x16x32_bf16 v[84:87], v[146:149], v[186:189], v[84:87]
	v_mfma_f32_16x16x32_bf16 v[80:83], v[154:157], v[186:189], v[80:83]
	v_mfma_f32_16x16x32_bf16 v[76:79], v[146:149], v[198:201], v[76:79]
	v_mfma_f32_16x16x32_bf16 v[72:75], v[154:157], v[198:201], v[72:75]
	v_mfma_f32_16x16x32_bf16 v[68:71], v[146:149], v[206:209], v[68:71]
	v_mfma_f32_16x16x32_bf16 v[64:67], v[154:157], v[206:209], v[64:67]
	v_mfma_f32_16x16x32_bf16 v[28:31], v[158:161], v[174:177], v[28:31]
	v_mfma_f32_16x16x32_bf16 v[24:27], v[166:169], v[174:177], v[24:27]
	v_mfma_f32_16x16x32_bf16 v[20:23], v[158:161], v[182:185], v[20:23]
	v_mfma_f32_16x16x32_bf16 v[16:19], v[166:169], v[182:185], v[16:19]
	v_mfma_f32_16x16x32_bf16 v[12:15], v[158:161], v[194:197], v[12:15]
	v_mfma_f32_16x16x32_bf16 v[8:11], v[166:169], v[194:197], v[8:11]
	v_mfma_f32_16x16x32_bf16 v[4:7], v[158:161], v[202:205], v[4:7]
	v_mfma_f32_16x16x32_bf16 v[0:3], v[166:169], v[202:205], v[0:3]
	v_mfma_f32_16x16x32_bf16 v[28:31], v[162:165], v[178:181], v[28:31]
	v_mfma_f32_16x16x32_bf16 v[24:27], v[170:173], v[178:181], v[24:27]
	v_mfma_f32_16x16x32_bf16 v[20:23], v[162:165], v[186:189], v[20:23]
	v_mfma_f32_16x16x32_bf16 v[16:19], v[170:173], v[186:189], v[16:19]
	v_mfma_f32_16x16x32_bf16 v[12:15], v[162:165], v[198:201], v[12:15]
	v_mfma_f32_16x16x32_bf16 v[8:11], v[170:173], v[198:201], v[8:11]
	v_mfma_f32_16x16x32_bf16 v[4:7], v[162:165], v[206:209], v[4:7]
	v_mfma_f32_16x16x32_bf16 v[0:3], v[170:173], v[206:209], v[0:3]
	s_setprio 0
	s_barrier
; #define PG8_STAGE(bufoff, gbase, voff) do { _Pragma("unroll") for (int _i = 0; _i < 2; ++_i) \
;         asm volatile("s_mov_b32 m0, %0\n\ts_nop 0\n\tglobal_load_lds_dwordx4 %1, %2" :: "s"(ldsb + (unsigned)((bufoff) + _i * 8192)), "v"((voff)[_i]), "s"(gbase) : "m0", "memory"); } while (0)
; #define PG8_LDA(dst, b, h) do { _Pragma("unroll") for (int m = 0; m < 4; ++m) _Pragma("unroll") for (int k = 0; k < 2; ++k) dst[m][k] = *(const PG8_LAS bf16x8*)(lds + PG8_SA(b, h) + aoff + m * 2048 + k * 1024); } while (0)
; #define PG8_LDB(dst, b, h) do { _Pragma("unroll") for (int n = 0; n < 2; ++n) _Pragma("unroll") for (int k = 0; k < 2; ++k) dst[n][k] = *(const PG8_LAS bf16x8*)(lds + PG8_SB(b, h) + boff + n * 2048 + k * 1024); } while (0)
; #define PG8_MMA(ai, bj, At, Bt) do { __builtin_amdgcn_s_setprio(1); _Pragma("unroll") for (int m = 0; m < 4; ++m) _Pragma("unroll") for (int n = 0; n < 2; ++n) _Pragma("unroll") for (int k = 0; k < 2; ++k) \
;         acc[ai][bj][m][n] = __builtin_amdgcn_mfma_f32_16x16x32_bf16(Bt[n][k], At[m][k], acc[ai][bj][m][n], 0, 0, 0); __builtin_amdgcn_s_setprio(0); } while (0)
; #define PG8_WAIT_V(n) asm volatile("s_waitcnt vmcnt(" #n ")" ::: "memory")
; #define PG8_WAIT_L(n) asm volatile("s_waitcnt lgkmcnt(" #n ")" ::: "memory")
; #define PG8_BAR __builtin_amdgcn_s_barrier()
; #define PG8_SCHED __builtin_amdgcn_sched_barrier(0)
; template <class Epi, class Sched, bool ALIGN_EPI = false, bool SP2 = false>
; __device__ __forceinline__ void gemm_phase(PG8_LAS unsigned char* lds, const Gemm g, const Sched& S, const Epi& E, const int wv) {
;     ...
;             PG8_LDB(B0, 1, 0); PG8_LDB(B1, 1, 1); PG8_SCHED; PG8_LDA(At, 1, 0); PG8_STAGE(PG8_SA(0, 1), a2 + hstepA, voffA);
;             PG8_WAIT_V(8); PG8_WAIT_L(0); PG8_BAR; PG8_MMA(0, 0, At, B0); PG8_MMA(0, 1, At, B1); PG8_BAR; PG8_SCHED;
;             PG8_LDA(At, 1, 1); PG8_STAGE(PG8_SB(1, 0), b3, voffB); PG8_STAGE(PG8_SB(1, 1), b3 + hstepB, voffB); PG8_STAGE(PG8_SA(1, 0), a3, voffA);
;             PG8_WAIT_V(8); PG8_WAIT_L(0); PG8_BAR; PG8_MMA(1, 0, At, B0); PG8_MMA(1, 1, At, B1); PG8_BAR; PG8_SCHED;
	v_add_u32_e32 v141, 0x18000, v139
	ds_read_b128 v[142:145], v141
	ds_read_b128 v[146:149], v141 offset:1024
	ds_read_b128 v[150:153], v141 offset:2048
	ds_read_b128 v[154:157], v141 offset:3072
	v_add_u32_e32 v141, 0x1c000, v139
	ds_read_b128 v[158:161], v141
	ds_read_b128 v[162:165], v141 offset:1024
	ds_read_b128 v[166:169], v141 offset:2048
	ds_read_b128 v[170:173], v141 offset:3072
	ds_read_b128 v[174:177], v140 offset:32768
	ds_read_b128 v[178:181], v140 offset:33792
	ds_read_b128 v[182:185], v140 offset:34816
	ds_read_b128 v[186:189], v140 offset:35840
	ds_read_b128 v[194:197], v140 offset:36864
	ds_read_b128 v[198:201], v140 offset:37888
	ds_read_b128 v[202:205], v140 offset:38912
	ds_read_b128 v[206:209], v140 offset:39936
	s_add_u32 s28, s28, 0x20000
	s_addc_u32 s29, s29, 0
	s_mov_b32 m0, s46
	s_nop 0
	global_load_lds_dwordx4 v128, s[28:29]
	s_nop 0
	s_mov_b32 m0, s47
	s_nop 0
	global_load_lds_dwordx4 v130, s[28:29]
	s_waitcnt vmcnt(8) lgkmcnt(0)
	s_setprio 1
	s_barrier
	v_mfma_f32_16x16x32_bf16 v[124:127], v[142:145], v[174:177], v[124:127]
	v_mfma_f32_16x16x32_bf16 v[120:123], v[150:153], v[174:177], v[120:123]
	v_mfma_f32_16x16x32_bf16 v[116:119], v[142:145], v[182:185], v[116:119]
	v_mfma_f32_16x16x32_bf16 v[112:115], v[150:153], v[182:185], v[112:115]
	v_mfma_f32_16x16x32_bf16 v[108:111], v[142:145], v[194:197], v[108:111]
	v_mfma_f32_16x16x32_bf16 v[104:107], v[150:153], v[194:197], v[104:107]
	v_mfma_f32_16x16x32_bf16 v[100:103], v[142:145], v[202:205], v[100:103]
	v_mfma_f32_16x16x32_bf16 v[96:99], v[150:153], v[202:205], v[96:99]
	v_mfma_f32_16x16x32_bf16 v[124:127], v[146:149], v[178:181], v[124:127]
	v_mfma_f32_16x16x32_bf16 v[120:123], v[154:157], v[178:181], v[120:123]
	v_mfma_f32_16x16x32_bf16 v[116:119], v[146:149], v[186:189], v[116:119]
	v_mfma_f32_16x16x32_bf16 v[112:115], v[154:157], v[186:189], v[112:115]
	v_mfma_f32_16x16x32_bf16 v[108:111], v[146:149], v[198:201], v[108:111]
	v_mfma_f32_16x16x32_bf16 v[104:107], v[154:157], v[198:201], v[104:107]
	v_mfma_f32_16x16x32_bf16 v[100:103], v[146:149], v[206:209], v[100:103]
	v_mfma_f32_16x16x32_bf16 v[96:99], v[154:157], v[206:209], v[96:99]
	v_mfma_f32_16x16x32_bf16 v[60:63], v[158:161], v[174:177], v[60:63]
	v_mfma_f32_16x16x32_bf16 v[56:59], v[166:169], v[174:177], v[56:59]
	v_mfma_f32_16x16x32_bf16 v[52:55], v[158:161], v[182:185], v[52:55]
	v_mfma_f32_16x16x32_bf16 v[48:51], v[166:169], v[182:185], v[48:51]
	v_mfma_f32_16x16x32_bf16 v[44:47], v[158:161], v[194:197], v[44:47]
	v_mfma_f32_16x16x32_bf16 v[40:43], v[166:169], v[194:197], v[40:43]
	v_mfma_f32_16x16x32_bf16 v[36:39], v[158:161], v[202:205], v[36:39]
	v_mfma_f32_16x16x32_bf16 v[32:35], v[166:169], v[202:205], v[32:35]
	v_mfma_f32_16x16x32_bf16 v[60:63], v[162:165], v[178:181], v[60:63]
	v_mfma_f32_16x16x32_bf16 v[56:59], v[170:173], v[178:181], v[56:59]
	v_mfma_f32_16x16x32_bf16 v[52:55], v[162:165], v[186:189], v[52:55]
	v_mfma_f32_16x16x32_bf16 v[48:51], v[170:173], v[186:189], v[48:51]
	v_mfma_f32_16x16x32_bf16 v[44:47], v[162:165], v[198:201], v[44:47]
	v_mfma_f32_16x16x32_bf16 v[40:43], v[170:173], v[198:201], v[40:43]
	v_mfma_f32_16x16x32_bf16 v[36:39], v[162:165], v[206:209], v[36:39]
	v_mfma_f32_16x16x32_bf16 v[32:35], v[170:173], v[206:209], v[32:35]
	s_setprio 0
	s_barrier
	ds_read_b128 v[174:177], v140 offset:49152
	ds_read_b128 v[178:181], v140 offset:50176
	ds_read_b128 v[182:185], v140 offset:51200
	ds_read_b128 v[186:189], v140 offset:52224
	ds_read_b128 v[194:197], v140 offset:53248
	ds_read_b128 v[198:201], v140 offset:54272
	ds_read_b128 v[202:205], v140 offset:55296
	ds_read_b128 v[206:209], v140 offset:56320
	s_add_u32 s28, s26, 0x80
	s_addc_u32 s29, s27, 0
	s_mov_b32 m0, s49
	s_nop 0
	global_load_lds_dwordx4 v129, s[28:29]
	s_add_u32 s26, s26, 0x20080
	s_mov_b32 m0, s50
	s_nop 0
	global_load_lds_dwordx4 v131, s[28:29]
	s_addc_u32 s27, s27, 0
	s_mov_b32 m0, s53
	s_nop 0
	global_load_lds_dwordx4 v129, s[26:27]
	s_nop 0
	s_mov_b32 m0, s54
	s_nop 0
	global_load_lds_dwordx4 v131, s[26:27]
	s_nop 0
	s_mov_b32 m0, s51
	s_nop 0
	global_load_lds_dwordx4 v128, s[24:25]
	s_nop 0
	s_mov_b32 m0, s52
	s_nop 0
	global_load_lds_dwordx4 v130, s[24:25]
	s_waitcnt vmcnt(8) lgkmcnt(0)
	s_setprio 1
	s_barrier
	v_mfma_f32_16x16x32_bf16 v[92:95], v[142:145], v[174:177], v[92:95]
	v_mfma_f32_16x16x32_bf16 v[88:91], v[150:153], v[174:177], v[88:91]
	v_mfma_f32_16x16x32_bf16 v[84:87], v[142:145], v[182:185], v[84:87]
	v_mfma_f32_16x16x32_bf16 v[80:83], v[150:153], v[182:185], v[80:83]
	v_mfma_f32_16x16x32_bf16 v[76:79], v[142:145], v[194:197], v[76:79]
	v_mfma_f32_16x16x32_bf16 v[72:75], v[150:153], v[194:197], v[72:75]
	v_mfma_f32_16x16x32_bf16 v[68:71], v[142:145], v[202:205], v[68:71]
	v_mfma_f32_16x16x32_bf16 v[64:67], v[150:153], v[202:205], v[64:67]
	v_mfma_f32_16x16x32_bf16 v[92:95], v[146:149], v[178:181], v[92:95]
	v_mfma_f32_16x16x32_bf16 v[88:91], v[154:157], v[178:181], v[88:91]
	v_mfma_f32_16x16x32_bf16 v[84:87], v[146:149], v[186:189], v[84:87]
	v_mfma_f32_16x16x32_bf16 v[80:83], v[154:157], v[186:189], v[80:83]
	v_mfma_f32_16x16x32_bf16 v[76:79], v[146:149], v[198:201], v[76:79]
	v_mfma_f32_16x16x32_bf16 v[72:75], v[154:157], v[198:201], v[72:75]
	v_mfma_f32_16x16x32_bf16 v[68:71], v[146:149], v[206:209], v[68:71]
	v_mfma_f32_16x16x32_bf16 v[64:67], v[154:157], v[206:209], v[64:67]
	v_mfma_f32_16x16x32_bf16 v[28:31], v[158:161], v[174:177], v[28:31]
	v_mfma_f32_16x16x32_bf16 v[24:27], v[166:169], v[174:177], v[24:27]
	v_mfma_f32_16x16x32_bf16 v[20:23], v[158:161], v[182:185], v[20:23]
	v_mfma_f32_16x16x32_bf16 v[16:19], v[166:169], v[182:185], v[16:19]
	v_mfma_f32_16x16x32_bf16 v[12:15], v[158:161], v[194:197], v[12:15]
	v_mfma_f32_16x16x32_bf16 v[8:11], v[166:169], v[194:197], v[8:11]
	v_mfma_f32_16x16x32_bf16 v[4:7], v[158:161], v[202:205], v[4:7]
	v_mfma_f32_16x16x32_bf16 v[0:3], v[166:169], v[202:205], v[0:3]
	v_mfma_f32_16x16x32_bf16 v[28:31], v[162:165], v[178:181], v[28:31]
	v_mfma_f32_16x16x32_bf16 v[24:27], v[170:173], v[178:181], v[24:27]
	v_mfma_f32_16x16x32_bf16 v[20:23], v[162:165], v[186:189], v[20:23]
	v_mfma_f32_16x16x32_bf16 v[16:19], v[170:173], v[186:189], v[16:19]
	v_mfma_f32_16x16x32_bf16 v[12:15], v[162:165], v[198:201], v[12:15]
	v_mfma_f32_16x16x32_bf16 v[8:11], v[170:173], v[198:201], v[8:11]
	v_mfma_f32_16x16x32_bf16 v[4:7], v[162:165], v[206:209], v[4:7]
	v_mfma_f32_16x16x32_bf16 v[0:3], v[170:173], v[206:209], v[0:3]
	s_setprio 0
	s_barrier
	s_add_u32 s62, s62, 0x100
	s_addc_u32 s65, s65, 0
	s_add_u32 s71, s71, 0x100
	s_addc_u32 s77, s77, 0
	s_cmp_ge_i32 s79, s40
	s_mov_b32 s24, s79
	s_cbranch_scc0 .LBB0_756
	s_mov_b32 s79, 0xc00000
	s_and_b64 vcc, exec, s[14:15]
	s_cbranch_vccz .LBB0_759

; #define PG8_STAGE(bufoff, gbase, voff) do { _Pragma("unroll") for (int _i = 0; _i < 2; ++_i) \
;         asm volatile("s_mov_b32 m0, %0\n\ts_nop 0\n\tglobal_load_lds_dwordx4 %1, %2" :: "s"(ldsb + (unsigned)((bufoff) + _i * 8192)), "v"((voff)[_i]), "s"(gbase) : "m0", "memory"); } while (0)
; #define PG8_LDA(dst, b, h) do { _Pragma("unroll") for (int m = 0; m < 4; ++m) _Pragma("unroll") for (int k = 0; k < 2; ++k) dst[m][k] = *(const PG8_LAS bf16x8*)(lds + PG8_SA(b, h) + aoff + m * 2048 + k * 1024); } while (0)
; #define PG8_LDB(dst, b, h) do { _Pragma("unroll") for (int n = 0; n < 2; ++n) _Pragma("unroll") for (int k = 0; k < 2; ++k) dst[n][k] = *(const PG8_LAS bf16x8*)(lds + PG8_SB(b, h) + boff + n * 2048 + k * 1024); } while (0)
; #define PG8_MMA(ai, bj, At, Bt) do { __builtin_amdgcn_s_setprio(1); _Pragma("unroll") for (int m = 0; m < 4; ++m) _Pragma("unroll") for (int n = 0; n < 2; ++n) _Pragma("unroll") for (int k = 0; k < 2; ++k) \
;         acc[ai][bj][m][n] = __builtin_amdgcn_mfma_f32_16x16x32_bf16(Bt[n][k], At[m][k], acc[ai][bj][m][n], 0, 0, 0); __builtin_amdgcn_s_setprio(0); } while (0)
; #define PG8_WAIT_V(n) asm volatile("s_waitcnt vmcnt(" #n ")" ::: "memory")
; template <class Epi, class Sched, bool ALIGN_EPI = false, bool SP2 = false>
; __device__ __forceinline__ void gemm_phase(PG8_LAS unsigned char* lds, const Gemm g, const Sched& S, const Epi& E, const int wv) {
;     ...
;         for (int t = 0; t < nt; t += 2) {
;             const bool last = (t == nt - 2);
;             const char* a1 = cA + (size_t)(t + 1) * kstep;
;             const char* a2 = last ? nA : cA + (size_t)(t + 2) * kstep; const char* b2 = last ? nB : cB + (size_t)(t + 2) * kstep;
;             const char* a3 = a2 + kstep; const char* b3 = b2 + kstep;
;             if (last && has_next) S.a_ready(nxt);
;             if constexpr (SP2) {
;             PG8_LDB(B0, 0, 0); PG8_LDB(B1, 0, 1); PG8_SCHED; PG8_LDA(At, 0, 0); PG8_STAGE(PG8_SA(1, 1), a1 + hstepA, voffA);
;             PG8_WAIT_V(8); PG8_WAIT_L(0); PG8_BAR; PG8_MMA(0, 0, At, B0); PG8_MMA(0, 1, At, B1); PG8_BAR; PG8_SCHED;
;             PG8_LDA(At, 0, 1); PG8_STAGE(PG8_SB(0, 0), b2, voffB); PG8_STAGE(PG8_SB(0, 1), b2 + hstepB, voffB); PG8_STAGE(PG8_SA(0, 0), a2, voffA);
;             PG8_WAIT_V(8); PG8_WAIT_L(0); PG8_BAR; PG8_MMA(1, 0, At, B0); PG8_MMA(1, 1, At, B1); PG8_BAR; PG8_SCHED;
.LBB0_810:
	v_add_u32_e32 v128, 0x10000, v136
	ds_read_b128 v[138:141], v128
	ds_read_b128 v[142:145], v128 offset:1024
	ds_read_b128 v[146:149], v128 offset:2048
	ds_read_b128 v[150:153], v128 offset:3072
	v_add_u32_e32 v128, 0x14000, v136
	ds_read_b128 v[154:157], v128
	ds_read_b128 v[158:161], v128 offset:1024
	ds_read_b128 v[162:165], v128 offset:2048
	ds_read_b128 v[166:169], v128 offset:3072
	s_add_i32 s85, s20, 2
	s_cmp_eq_u32 s62, s20
	s_cselect_b32 s24, s14, s77
	s_cselect_b32 s25, s15, s79
	s_cselect_b32 s22, s72, s83
	s_cselect_b32 s23, s71, s84
	s_add_u32 s20, s24, 0x80
	s_addc_u32 s21, s25, 0
	ds_read_b128 v[170:173], v137
	ds_read_b128 v[174:177], v137 offset:1024
	ds_read_b128 v[178:181], v137 offset:2048
	ds_read_b128 v[182:185], v137 offset:3072
	ds_read_b128 v[186:189], v137 offset:4096
	ds_read_b128 v[194:197], v137 offset:5120
	ds_read_b128 v[198:201], v137 offset:6144
	ds_read_b128 v[202:205], v137 offset:7168
	s_add_u32 s86, s77, 0xff80
	s_addc_u32 s87, s79, 0
	s_mov_b32 m0, s51
	s_nop 0
	global_load_lds_dwordx4 v130, s[86:87]
	s_nop 0
	s_mov_b32 m0, s52
	s_nop 0
	global_load_lds_dwordx4 v132, s[86:87]
	s_waitcnt vmcnt(8) lgkmcnt(0)
	s_setprio 1
	s_barrier
	v_mfma_f32_16x16x32_bf16 v[124:127], v[138:141], v[170:173], v[124:127]
	v_mfma_f32_16x16x32_bf16 v[120:123], v[146:149], v[170:173], v[120:123]
	v_mfma_f32_16x16x32_bf16 v[108:111], v[138:141], v[178:181], v[108:111]
	v_mfma_f32_16x16x32_bf16 v[104:107], v[146:149], v[178:181], v[104:107]
	v_mfma_f32_16x16x32_bf16 v[92:95], v[138:141], v[186:189], v[92:95]
	v_mfma_f32_16x16x32_bf16 v[88:91], v[146:149], v[186:189], v[88:91]
	v_mfma_f32_16x16x32_bf16 v[76:79], v[138:141], v[198:201], v[76:79]
	v_mfma_f32_16x16x32_bf16 v[72:75], v[146:149], v[198:201], v[72:75]
	v_mfma_f32_16x16x32_bf16 v[124:127], v[142:145], v[174:177], v[124:127]
	v_mfma_f32_16x16x32_bf16 v[120:123], v[150:153], v[174:177], v[120:123]
	v_mfma_f32_16x16x32_bf16 v[108:111], v[142:145], v[182:185], v[108:111]
	v_mfma_f32_16x16x32_bf16 v[104:107], v[150:153], v[182:185], v[104:107]
	v_mfma_f32_16x16x32_bf16 v[92:95], v[142:145], v[194:197], v[92:95]
	v_mfma_f32_16x16x32_bf16 v[88:91], v[150:153], v[194:197], v[88:91]
	v_mfma_f32_16x16x32_bf16 v[76:79], v[142:145], v[202:205], v[76:79]
	v_mfma_f32_16x16x32_bf16 v[72:75], v[150:153], v[202:205], v[72:75]
	v_mfma_f32_16x16x32_bf16 v[116:119], v[154:157], v[170:173], v[116:119]
	v_mfma_f32_16x16x32_bf16 v[112:115], v[162:165], v[170:173], v[112:115]
	v_mfma_f32_16x16x32_bf16 v[100:103], v[154:157], v[178:181], v[100:103]
	v_mfma_f32_16x16x32_bf16 v[96:99], v[162:165], v[178:181], v[96:99]
	v_mfma_f32_16x16x32_bf16 v[84:87], v[154:157], v[186:189], v[84:87]
	v_mfma_f32_16x16x32_bf16 v[80:83], v[162:165], v[186:189], v[80:83]
	v_mfma_f32_16x16x32_bf16 v[68:71], v[154:157], v[198:201], v[68:71]
	v_mfma_f32_16x16x32_bf16 v[64:67], v[162:165], v[198:201], v[64:67]
	v_mfma_f32_16x16x32_bf16 v[116:119], v[158:161], v[174:177], v[116:119]
	v_mfma_f32_16x16x32_bf16 v[112:115], v[166:169], v[174:177], v[112:115]
	v_mfma_f32_16x16x32_bf16 v[100:103], v[158:161], v[182:185], v[100:103]
	v_mfma_f32_16x16x32_bf16 v[96:99], v[166:169], v[182:185], v[96:99]
	v_mfma_f32_16x16x32_bf16 v[84:87], v[158:161], v[194:197], v[84:87]
	v_mfma_f32_16x16x32_bf16 v[80:83], v[166:169], v[194:197], v[80:83]
	v_mfma_f32_16x16x32_bf16 v[68:71], v[158:161], v[202:205], v[68:71]
	v_mfma_f32_16x16x32_bf16 v[64:67], v[166:169], v[202:205], v[64:67]
	s_setprio 0
	s_barrier
	ds_read_b128 v[170:173], v137 offset:16384
	ds_read_b128 v[174:177], v137 offset:17408
	ds_read_b128 v[178:181], v137 offset:18432
	ds_read_b128 v[182:185], v137 offset:19456
	ds_read_b128 v[186:189], v137 offset:20480
	ds_read_b128 v[194:197], v137 offset:21504
	ds_read_b128 v[198:201], v137 offset:22528
	ds_read_b128 v[202:205], v137 offset:23552
	s_mov_b32 m0, s33
	s_nop 0
	global_load_lds_dwordx4 v131, s[22:23]
	s_add_u32 s86, s22, 0x10000
	s_mov_b32 m0, s34
	s_nop 0
	global_load_lds_dwordx4 v133, s[22:23]
	s_addc_u32 s87, s23, 0
	s_mov_b32 m0, s35
	s_nop 0
	global_load_lds_dwordx4 v131, s[86:87]
	s_nop 0
	s_mov_b32 m0, s36
	s_nop 0
	global_load_lds_dwordx4 v133, s[86:87]
	s_nop 0
	s_mov_b32 m0, s31
	s_nop 0
	global_load_lds_dwordx4 v130, s[24:25]
	s_nop 0
	s_mov_b32 m0, s37
	s_nop 0
	global_load_lds_dwordx4 v132, s[24:25]
	s_waitcnt vmcnt(8) lgkmcnt(0)
	s_setprio 1
	s_barrier
	v_mfma_f32_16x16x32_bf16 v[60:63], v[138:141], v[170:173], v[60:63]
	v_mfma_f32_16x16x32_bf16 v[56:59], v[146:149], v[170:173], v[56:59]
	v_mfma_f32_16x16x32_bf16 v[44:47], v[138:141], v[178:181], v[44:47]
	v_mfma_f32_16x16x32_bf16 v[40:43], v[146:149], v[178:181], v[40:43]
	v_mfma_f32_16x16x32_bf16 v[28:31], v[138:141], v[186:189], v[28:31]
	v_mfma_f32_16x16x32_bf16 v[24:27], v[146:149], v[186:189], v[24:27]
	v_mfma_f32_16x16x32_bf16 v[12:15], v[138:141], v[198:201], v[12:15]
	v_mfma_f32_16x16x32_bf16 v[8:11], v[146:149], v[198:201], v[8:11]
	v_mfma_f32_16x16x32_bf16 v[60:63], v[142:145], v[174:177], v[60:63]
	v_mfma_f32_16x16x32_bf16 v[56:59], v[150:153], v[174:177], v[56:59]
	v_mfma_f32_16x16x32_bf16 v[44:47], v[142:145], v[182:185], v[44:47]
	v_mfma_f32_16x16x32_bf16 v[40:43], v[150:153], v[182:185], v[40:43]
	v_mfma_f32_16x16x32_bf16 v[28:31], v[142:145], v[194:197], v[28:31]
	v_mfma_f32_16x16x32_bf16 v[24:27], v[150:153], v[194:197], v[24:27]
	v_mfma_f32_16x16x32_bf16 v[12:15], v[142:145], v[202:205], v[12:15]
	v_mfma_f32_16x16x32_bf16 v[8:11], v[150:153], v[202:205], v[8:11]
	v_mfma_f32_16x16x32_bf16 v[52:55], v[154:157], v[170:173], v[52:55]
	v_mfma_f32_16x16x32_bf16 v[48:51], v[162:165], v[170:173], v[48:51]
	v_mfma_f32_16x16x32_bf16 v[36:39], v[154:157], v[178:181], v[36:39]
	v_mfma_f32_16x16x32_bf16 v[32:35], v[162:165], v[178:181], v[32:35]
	v_mfma_f32_16x16x32_bf16 v[20:23], v[154:157], v[186:189], v[20:23]
	v_mfma_f32_16x16x32_bf16 v[16:19], v[162:165], v[186:189], v[16:19]
	v_mfma_f32_16x16x32_bf16 v[4:7], v[154:157], v[198:201], v[4:7]
	v_mfma_f32_16x16x32_bf16 v[0:3], v[162:165], v[198:201], v[0:3]
	v_mfma_f32_16x16x32_bf16 v[52:55], v[158:161], v[174:177], v[52:55]
	v_mfma_f32_16x16x32_bf16 v[48:51], v[166:169], v[174:177], v[48:51]
	v_mfma_f32_16x16x32_bf16 v[36:39], v[158:161], v[182:185], v[36:39]
	v_mfma_f32_16x16x32_bf16 v[32:35], v[166:169], v[182:185], v[32:35]
	v_mfma_f32_16x16x32_bf16 v[20:23], v[158:161], v[194:197], v[20:23]
	v_mfma_f32_16x16x32_bf16 v[16:19], v[166:169], v[194:197], v[16:19]
	v_mfma_f32_16x16x32_bf16 v[4:7], v[158:161], v[202:205], v[4:7]
	v_mfma_f32_16x16x32_bf16 v[0:3], v[166:169], v[202:205], v[0:3]
	s_setprio 0
	s_barrier
; #define PG8_STAGE(bufoff, gbase, voff) do { _Pragma("unroll") for (int _i = 0; _i < 2; ++_i) \
;         asm volatile("s_mov_b32 m0, %0\n\ts_nop 0\n\tglobal_load_lds_dwordx4 %1, %2" :: "s"(ldsb + (unsigned)((bufoff) + _i * 8192)), "v"((voff)[_i]), "s"(gbase) : "m0", "memory"); } while (0)
; #define PG8_LDA(dst, b, h) do { _Pragma("unroll") for (int m = 0; m < 4; ++m) _Pragma("unroll") for (int k = 0; k < 2; ++k) dst[m][k] = *(const PG8_LAS bf16x8*)(lds + PG8_SA(b, h) + aoff + m * 2048 + k * 1024); } while (0)
; #define PG8_LDB(dst, b, h) do { _Pragma("unroll") for (int n = 0; n < 2; ++n) _Pragma("unroll") for (int k = 0; k < 2; ++k) dst[n][k] = *(const PG8_LAS bf16x8*)(lds + PG8_SB(b, h) + boff + n * 2048 + k * 1024); } while (0)
; #define PG8_MMA(ai, bj, At, Bt) do { __builtin_amdgcn_s_setprio(1); _Pragma("unroll") for (int m = 0; m < 4; ++m) _Pragma("unroll") for (int n = 0; n < 2; ++n) _Pragma("unroll") for (int k = 0; k < 2; ++k) \
;         acc[ai][bj][m][n] = __builtin_amdgcn_mfma_f32_16x16x32_bf16(Bt[n][k], At[m][k], acc[ai][bj][m][n], 0, 0, 0); __builtin_amdgcn_s_setprio(0); } while (0)
; #define PG8_WAIT_V(n) asm volatile("s_waitcnt vmcnt(" #n ")" ::: "memory")
; #define PG8_WAIT_L(n) asm volatile("s_waitcnt lgkmcnt(" #n ")" ::: "memory")
; #define PG8_BAR __builtin_amdgcn_s_barrier()
; #define PG8_SCHED __builtin_amdgcn_sched_barrier(0)
; template <class Epi, class Sched, bool ALIGN_EPI = false, bool SP2 = false>
; __device__ __forceinline__ void gemm_phase(PG8_LAS unsigned char* lds, const Gemm g, const Sched& S, const Epi& E, const int wv) {
;     ...
;             PG8_LDB(B0, 1, 0); PG8_LDB(B1, 1, 1); PG8_SCHED; PG8_LDA(At, 1, 0); PG8_STAGE(PG8_SA(0, 1), a2 + hstepA, voffA);
;             PG8_WAIT_V(8); PG8_WAIT_L(0); PG8_BAR; PG8_MMA(0, 0, At, B0); PG8_MMA(0, 1, At, B1); PG8_BAR; PG8_SCHED;
;             PG8_LDA(At, 1, 1); PG8_STAGE(PG8_SB(1, 0), b3, voffB); PG8_STAGE(PG8_SB(1, 1), b3 + hstepB, voffB); PG8_STAGE(PG8_SA(1, 0), a3, voffA);
;             PG8_WAIT_V(8); PG8_WAIT_L(0); PG8_BAR; PG8_MMA(1, 0, At, B0); PG8_MMA(1, 1, At, B1); PG8_BAR; PG8_SCHED;
	v_add_u32_e32 v128, 0x18000, v136
	ds_read_b128 v[138:141], v128
	ds_read_b128 v[142:145], v128 offset:1024
	ds_read_b128 v[146:149], v128 offset:2048
	ds_read_b128 v[150:153], v128 offset:3072
	v_add_u32_e32 v128, 0x1c000, v136
	ds_read_b128 v[154:157], v128
	ds_read_b128 v[158:161], v128 offset:1024
	ds_read_b128 v[162:165], v128 offset:2048
	ds_read_b128 v[166:169], v128 offset:3072
	ds_read_b128 v[170:173], v137 offset:32768
	ds_read_b128 v[174:177], v137 offset:33792
	ds_read_b128 v[178:181], v137 offset:34816
	ds_read_b128 v[182:185], v137 offset:35840
	ds_read_b128 v[186:189], v137 offset:36864
	ds_read_b128 v[194:197], v137 offset:37888
	ds_read_b128 v[198:201], v137 offset:38912
	ds_read_b128 v[202:205], v137 offset:39936
	s_add_u32 s24, s24, 0x10000
	s_addc_u32 s25, s25, 0
	s_mov_b32 m0, s42
	s_nop 0
	global_load_lds_dwordx4 v130, s[24:25]
	s_nop 0
	s_mov_b32 m0, s43
	s_nop 0
	global_load_lds_dwordx4 v132, s[24:25]
	s_waitcnt vmcnt(8) lgkmcnt(0)
	s_setprio 1
	s_barrier
	v_mfma_f32_16x16x32_bf16 v[124:127], v[138:141], v[170:173], v[124:127]
	v_mfma_f32_16x16x32_bf16 v[120:123], v[146:149], v[170:173], v[120:123]
	v_mfma_f32_16x16x32_bf16 v[108:111], v[138:141], v[178:181], v[108:111]
	v_mfma_f32_16x16x32_bf16 v[104:107], v[146:149], v[178:181], v[104:107]
	v_mfma_f32_16x16x32_bf16 v[92:95], v[138:141], v[186:189], v[92:95]
	v_mfma_f32_16x16x32_bf16 v[88:91], v[146:149], v[186:189], v[88:91]
	v_mfma_f32_16x16x32_bf16 v[76:79], v[138:141], v[198:201], v[76:79]
	v_mfma_f32_16x16x32_bf16 v[72:75], v[146:149], v[198:201], v[72:75]
	v_mfma_f32_16x16x32_bf16 v[124:127], v[142:145], v[174:177], v[124:127]
	v_mfma_f32_16x16x32_bf16 v[120:123], v[150:153], v[174:177], v[120:123]
	v_mfma_f32_16x16x32_bf16 v[108:111], v[142:145], v[182:185], v[108:111]
	v_mfma_f32_16x16x32_bf16 v[104:107], v[150:153], v[182:185], v[104:107]
	v_mfma_f32_16x16x32_bf16 v[92:95], v[142:145], v[194:197], v[92:95]
	v_mfma_f32_16x16x32_bf16 v[88:91], v[150:153], v[194:197], v[88:91]
	v_mfma_f32_16x16x32_bf16 v[76:79], v[142:145], v[202:205], v[76:79]
	v_mfma_f32_16x16x32_bf16 v[72:75], v[150:153], v[202:205], v[72:75]
	v_mfma_f32_16x16x32_bf16 v[116:119], v[154:157], v[170:173], v[116:119]
	v_mfma_f32_16x16x32_bf16 v[112:115], v[162:165], v[170:173], v[112:115]
	v_mfma_f32_16x16x32_bf16 v[100:103], v[154:157], v[178:181], v[100:103]
	v_mfma_f32_16x16x32_bf16 v[96:99], v[162:165], v[178:181], v[96:99]
	v_mfma_f32_16x16x32_bf16 v[84:87], v[154:157], v[186:189], v[84:87]
	v_mfma_f32_16x16x32_bf16 v[80:83], v[162:165], v[186:189], v[80:83]
	v_mfma_f32_16x16x32_bf16 v[68:71], v[154:157], v[198:201], v[68:71]
	v_mfma_f32_16x16x32_bf16 v[64:67], v[162:165], v[198:201], v[64:67]
	v_mfma_f32_16x16x32_bf16 v[116:119], v[158:161], v[174:177], v[116:119]
	v_mfma_f32_16x16x32_bf16 v[112:115], v[166:169], v[174:177], v[112:115]
	v_mfma_f32_16x16x32_bf16 v[100:103], v[158:161], v[182:185], v[100:103]
	v_mfma_f32_16x16x32_bf16 v[96:99], v[166:169], v[182:185], v[96:99]
	v_mfma_f32_16x16x32_bf16 v[84:87], v[158:161], v[194:197], v[84:87]
	v_mfma_f32_16x16x32_bf16 v[80:83], v[166:169], v[194:197], v[80:83]
	v_mfma_f32_16x16x32_bf16 v[68:71], v[158:161], v[202:205], v[68:71]
	v_mfma_f32_16x16x32_bf16 v[64:67], v[166:169], v[202:205], v[64:67]
	s_setprio 0
	s_barrier
	ds_read_b128 v[170:173], v137 offset:49152
	ds_read_b128 v[174:177], v137 offset:50176
	ds_read_b128 v[178:181], v137 offset:51200
	ds_read_b128 v[182:185], v137 offset:52224
	ds_read_b128 v[186:189], v137 offset:53248
	ds_read_b128 v[194:197], v137 offset:54272
	ds_read_b128 v[198:201], v137 offset:55296
	ds_read_b128 v[202:205], v137 offset:56320
	s_add_u32 s24, s22, 0x80
	s_addc_u32 s25, s23, 0
	s_mov_b32 m0, s45
	s_nop 0
	global_load_lds_dwordx4 v131, s[24:25]
	s_add_u32 s22, s22, 0x10080
	s_mov_b32 m0, s46
	s_nop 0
	global_load_lds_dwordx4 v133, s[24:25]
	s_addc_u32 s23, s23, 0
	s_mov_b32 m0, s49
	s_nop 0
	global_load_lds_dwordx4 v131, s[22:23]
	s_nop 0
	s_mov_b32 m0, s50
	s_nop 0
	global_load_lds_dwordx4 v133, s[22:23]
	s_nop 0
	s_mov_b32 m0, s47
	s_nop 0
	global_load_lds_dwordx4 v130, s[20:21]
	s_nop 0
	s_mov_b32 m0, s48
	s_nop 0
	global_load_lds_dwordx4 v132, s[20:21]
	s_waitcnt vmcnt(8) lgkmcnt(0)
	s_setprio 1
	s_barrier
	v_mfma_f32_16x16x32_bf16 v[60:63], v[138:141], v[170:173], v[60:63]
	v_mfma_f32_16x16x32_bf16 v[56:59], v[146:149], v[170:173], v[56:59]
	v_mfma_f32_16x16x32_bf16 v[44:47], v[138:141], v[178:181], v[44:47]
	v_mfma_f32_16x16x32_bf16 v[40:43], v[146:149], v[178:181], v[40:43]
	v_mfma_f32_16x16x32_bf16 v[28:31], v[138:141], v[186:189], v[28:31]
	v_mfma_f32_16x16x32_bf16 v[24:27], v[146:149], v[186:189], v[24:27]
	v_mfma_f32_16x16x32_bf16 v[12:15], v[138:141], v[198:201], v[12:15]
	v_mfma_f32_16x16x32_bf16 v[8:11], v[146:149], v[198:201], v[8:11]
	v_mfma_f32_16x16x32_bf16 v[60:63], v[142:145], v[174:177], v[60:63]
	v_mfma_f32_16x16x32_bf16 v[56:59], v[150:153], v[174:177], v[56:59]
	v_mfma_f32_16x16x32_bf16 v[44:47], v[142:145], v[182:185], v[44:47]
	v_mfma_f32_16x16x32_bf16 v[40:43], v[150:153], v[182:185], v[40:43]
	v_mfma_f32_16x16x32_bf16 v[28:31], v[142:145], v[194:197], v[28:31]
	v_mfma_f32_16x16x32_bf16 v[24:27], v[150:153], v[194:197], v[24:27]
	v_mfma_f32_16x16x32_bf16 v[12:15], v[142:145], v[202:205], v[12:15]
	v_mfma_f32_16x16x32_bf16 v[8:11], v[150:153], v[202:205], v[8:11]
	v_mfma_f32_16x16x32_bf16 v[52:55], v[154:157], v[170:173], v[52:55]
	v_mfma_f32_16x16x32_bf16 v[48:51], v[162:165], v[170:173], v[48:51]
	v_mfma_f32_16x16x32_bf16 v[36:39], v[154:157], v[178:181], v[36:39]
	v_mfma_f32_16x16x32_bf16 v[32:35], v[162:165], v[178:181], v[32:35]
	v_mfma_f32_16x16x32_bf16 v[20:23], v[154:157], v[186:189], v[20:23]
	v_mfma_f32_16x16x32_bf16 v[16:19], v[162:165], v[186:189], v[16:19]
	v_mfma_f32_16x16x32_bf16 v[4:7], v[154:157], v[198:201], v[4:7]
	v_mfma_f32_16x16x32_bf16 v[0:3], v[162:165], v[198:201], v[0:3]
	v_mfma_f32_16x16x32_bf16 v[52:55], v[158:161], v[174:177], v[52:55]
	v_mfma_f32_16x16x32_bf16 v[48:51], v[166:169], v[174:177], v[48:51]
	v_mfma_f32_16x16x32_bf16 v[36:39], v[158:161], v[182:185], v[36:39]
	v_mfma_f32_16x16x32_bf16 v[32:35], v[166:169], v[182:185], v[32:35]
	v_mfma_f32_16x16x32_bf16 v[20:23], v[158:161], v[194:197], v[20:23]
	v_mfma_f32_16x16x32_bf16 v[16:19], v[166:169], v[194:197], v[16:19]
	v_mfma_f32_16x16x32_bf16 v[4:7], v[158:161], v[202:205], v[4:7]
	v_mfma_f32_16x16x32_bf16 v[0:3], v[166:169], v[202:205], v[0:3]
	s_setprio 0
	s_barrier
	s_add_u32 s77, s77, 0x100
	s_addc_u32 s79, s79, 0
	s_add_u32 s83, s83, 0x100
	s_addc_u32 s84, s84, 0
	s_cmp_ge_i32 s85, s65
	s_mov_b32 s20, s85
	s_cbranch_scc0 .LBB0_810
	s_mov_b32 s79, 0xc00000
	s_and_b64 vcc, exec, s[12:13]
	s_cbranch_vccz .LBB0_813

; #define PG8_STAGE(bufoff, gbase, voff) do { _Pragma("unroll") for (int _i = 0; _i < 2; ++_i) \
;         asm volatile("s_mov_b32 m0, %0\n\ts_nop 0\n\tglobal_load_lds_dwordx4 %1, %2" :: "s"(ldsb + (unsigned)((bufoff) + _i * 8192)), "v"((voff)[_i]), "s"(gbase) : "m0", "memory"); } while (0)
; #define PG8_LDA(dst, b, h) do { _Pragma("unroll") for (int m = 0; m < 4; ++m) _Pragma("unroll") for (int k = 0; k < 2; ++k) dst[m][k] = *(const PG8_LAS bf16x8*)(lds + PG8_SA(b, h) + aoff + m * 2048 + k * 1024); } while (0)
; #define PG8_LDB(dst, b, h) do { _Pragma("unroll") for (int n = 0; n < 2; ++n) _Pragma("unroll") for (int k = 0; k < 2; ++k) dst[n][k] = *(const PG8_LAS bf16x8*)(lds + PG8_SB(b, h) + boff + n * 2048 + k * 1024); } while (0)
; #define PG8_MMA(ai, bj, At, Bt) do { __builtin_amdgcn_s_setprio(1); _Pragma("unroll") for (int m = 0; m < 4; ++m) _Pragma("unroll") for (int n = 0; n < 2; ++n) _Pragma("unroll") for (int k = 0; k < 2; ++k) \
;         acc[ai][bj][m][n] = __builtin_amdgcn_mfma_f32_16x16x32_bf16(Bt[n][k], At[m][k], acc[ai][bj][m][n], 0, 0, 0); __builtin_amdgcn_s_setprio(0); } while (0)
; #define PG8_WAIT_V(n) asm volatile("s_waitcnt vmcnt(" #n ")" ::: "memory")
; template <class Epi, class Sched, bool ALIGN_EPI = false, bool SP2 = false>
; __device__ __forceinline__ void gemm_phase(PG8_LAS unsigned char* lds, const Gemm g, const Sched& S, const Epi& E, const int wv) {
;     ...
;         for (int t = 0; t < nt; t += 2) {
;             const bool last = (t == nt - 2);
;             const char* a1 = cA + (size_t)(t + 1) * kstep;
;             const char* a2 = last ? nA : cA + (size_t)(t + 2) * kstep; const char* b2 = last ? nB : cB + (size_t)(t + 2) * kstep;
;             const char* a3 = a2 + kstep; const char* b3 = b2 + kstep;
;             if (last && has_next) S.a_ready(nxt);
;             if constexpr (SP2) {
;             PG8_LDB(B0, 0, 0); PG8_LDB(B1, 0, 1); PG8_SCHED; PG8_LDA(At, 0, 0); PG8_STAGE(PG8_SA(1, 1), a1 + hstepA, voffA);
;             PG8_WAIT_V(8); PG8_WAIT_L(0); PG8_BAR; PG8_MMA(0, 0, At, B0); PG8_MMA(0, 1, At, B1); PG8_BAR; PG8_SCHED;
;             PG8_LDA(At, 0, 1); PG8_STAGE(PG8_SB(0, 0), b2, voffB); PG8_STAGE(PG8_SB(0, 1), b2 + hstepB, voffB); PG8_STAGE(PG8_SA(0, 0), a2, voffA);
;             PG8_WAIT_V(8); PG8_WAIT_L(0); PG8_BAR; PG8_MMA(1, 0, At, B0); PG8_MMA(1, 1, At, B1); PG8_BAR; PG8_SCHED;
.LBB0_864:
	v_add_u32_e32 v137, 0x10000, v134
	ds_read_b128 v[138:141], v137
	ds_read_b128 v[142:145], v137 offset:1024
	ds_read_b128 v[146:149], v137 offset:2048
	ds_read_b128 v[150:153], v137 offset:3072
	v_add_u32_e32 v137, 0x14000, v134
	ds_read_b128 v[154:157], v137
	ds_read_b128 v[158:161], v137 offset:1024
	ds_read_b128 v[162:165], v137 offset:2048
	ds_read_b128 v[166:169], v137 offset:3072
	s_add_i32 s72, s18, 2
	s_cmp_eq_u32 s58, s18
	s_cselect_b32 s22, s12, s60
	s_cselect_b32 s23, s13, s62
	s_cselect_b32 s20, s57, s65
	s_cselect_b32 s21, s56, s71
	s_add_u32 s18, s22, 0x80
	s_addc_u32 s19, s23, 0
	ds_read_b128 v[170:173], v135
	ds_read_b128 v[174:177], v135 offset:1024
	ds_read_b128 v[178:181], v135 offset:2048
	ds_read_b128 v[182:185], v135 offset:3072
	ds_read_b128 v[186:189], v135 offset:4096
	ds_read_b128 v[194:197], v135 offset:5120
	ds_read_b128 v[198:201], v135 offset:6144
	ds_read_b128 v[202:205], v135 offset:7168
	s_add_u32 s84, s60, 0x1ff80
	s_addc_u32 s85, s62, 0
	s_mov_b32 m0, s45
	s_nop 0
	global_load_lds_dwordx4 v128, s[84:85]
	s_nop 0
	s_mov_b32 m0, s46
	s_nop 0
	global_load_lds_dwordx4 v130, s[84:85]
	s_waitcnt vmcnt(8) lgkmcnt(0)
	s_setprio 1
	s_barrier
	v_mfma_f32_16x16x32_bf16 v[124:127], v[138:141], v[170:173], v[124:127]
	v_mfma_f32_16x16x32_bf16 v[120:123], v[146:149], v[170:173], v[120:123]
	v_mfma_f32_16x16x32_bf16 v[108:111], v[138:141], v[178:181], v[108:111]
	v_mfma_f32_16x16x32_bf16 v[104:107], v[146:149], v[178:181], v[104:107]
	v_mfma_f32_16x16x32_bf16 v[92:95], v[138:141], v[186:189], v[92:95]
	v_mfma_f32_16x16x32_bf16 v[88:91], v[146:149], v[186:189], v[88:91]
	v_mfma_f32_16x16x32_bf16 v[76:79], v[138:141], v[198:201], v[76:79]
	v_mfma_f32_16x16x32_bf16 v[72:75], v[146:149], v[198:201], v[72:75]
	v_mfma_f32_16x16x32_bf16 v[124:127], v[142:145], v[174:177], v[124:127]
	v_mfma_f32_16x16x32_bf16 v[120:123], v[150:153], v[174:177], v[120:123]
	v_mfma_f32_16x16x32_bf16 v[108:111], v[142:145], v[182:185], v[108:111]
	v_mfma_f32_16x16x32_bf16 v[104:107], v[150:153], v[182:185], v[104:107]
	v_mfma_f32_16x16x32_bf16 v[92:95], v[142:145], v[194:197], v[92:95]
	v_mfma_f32_16x16x32_bf16 v[88:91], v[150:153], v[194:197], v[88:91]
	v_mfma_f32_16x16x32_bf16 v[76:79], v[142:145], v[202:205], v[76:79]
	v_mfma_f32_16x16x32_bf16 v[72:75], v[150:153], v[202:205], v[72:75]
	v_mfma_f32_16x16x32_bf16 v[116:119], v[154:157], v[170:173], v[116:119]
	v_mfma_f32_16x16x32_bf16 v[112:115], v[162:165], v[170:173], v[112:115]
	v_mfma_f32_16x16x32_bf16 v[100:103], v[154:157], v[178:181], v[100:103]
	v_mfma_f32_16x16x32_bf16 v[96:99], v[162:165], v[178:181], v[96:99]
	v_mfma_f32_16x16x32_bf16 v[84:87], v[154:157], v[186:189], v[84:87]
	v_mfma_f32_16x16x32_bf16 v[80:83], v[162:165], v[186:189], v[80:83]
	v_mfma_f32_16x16x32_bf16 v[68:71], v[154:157], v[198:201], v[68:71]
	v_mfma_f32_16x16x32_bf16 v[64:67], v[162:165], v[198:201], v[64:67]
	v_mfma_f32_16x16x32_bf16 v[116:119], v[158:161], v[174:177], v[116:119]
	v_mfma_f32_16x16x32_bf16 v[112:115], v[166:169], v[174:177], v[112:115]
	v_mfma_f32_16x16x32_bf16 v[100:103], v[158:161], v[182:185], v[100:103]
	v_mfma_f32_16x16x32_bf16 v[96:99], v[166:169], v[182:185], v[96:99]
	v_mfma_f32_16x16x32_bf16 v[84:87], v[158:161], v[194:197], v[84:87]
	v_mfma_f32_16x16x32_bf16 v[80:83], v[166:169], v[194:197], v[80:83]
	v_mfma_f32_16x16x32_bf16 v[68:71], v[158:161], v[202:205], v[68:71]
	v_mfma_f32_16x16x32_bf16 v[64:67], v[166:169], v[202:205], v[64:67]
	s_setprio 0
	s_barrier
	ds_read_b128 v[170:173], v135 offset:16384
	ds_read_b128 v[174:177], v135 offset:17408
	ds_read_b128 v[178:181], v135 offset:18432
	ds_read_b128 v[182:185], v135 offset:19456
	ds_read_b128 v[186:189], v135 offset:20480
	ds_read_b128 v[194:197], v135 offset:21504
	ds_read_b128 v[198:201], v135 offset:22528
	ds_read_b128 v[202:205], v135 offset:23552
	s_mov_b32 m0, s28
	s_nop 0
	global_load_lds_dwordx4 v129, s[20:21]
	s_add_u32 s84, s20, 0x20000
	s_mov_b32 m0, s29
	s_nop 0
	global_load_lds_dwordx4 v131, s[20:21]
	s_addc_u32 s85, s21, 0
	s_mov_b32 m0, s30
	s_nop 0
	global_load_lds_dwordx4 v129, s[84:85]
	s_nop 0
	s_mov_b32 m0, s31
	s_nop 0
	global_load_lds_dwordx4 v131, s[84:85]
	s_nop 0
	s_mov_b32 m0, s27
	s_nop 0
	global_load_lds_dwordx4 v128, s[22:23]
	s_nop 0
	s_mov_b32 m0, s33
	s_nop 0
	global_load_lds_dwordx4 v130, s[22:23]
	s_waitcnt vmcnt(8) lgkmcnt(0)
	s_setprio 1
	s_barrier
	v_mfma_f32_16x16x32_bf16 v[60:63], v[138:141], v[170:173], v[60:63]
	v_mfma_f32_16x16x32_bf16 v[56:59], v[146:149], v[170:173], v[56:59]
	v_mfma_f32_16x16x32_bf16 v[44:47], v[138:141], v[178:181], v[44:47]
	v_mfma_f32_16x16x32_bf16 v[40:43], v[146:149], v[178:181], v[40:43]
	v_mfma_f32_16x16x32_bf16 v[28:31], v[138:141], v[186:189], v[28:31]
	v_mfma_f32_16x16x32_bf16 v[24:27], v[146:149], v[186:189], v[24:27]
	v_mfma_f32_16x16x32_bf16 v[12:15], v[138:141], v[198:201], v[12:15]
	v_mfma_f32_16x16x32_bf16 v[8:11], v[146:149], v[198:201], v[8:11]
	v_mfma_f32_16x16x32_bf16 v[60:63], v[142:145], v[174:177], v[60:63]
	v_mfma_f32_16x16x32_bf16 v[56:59], v[150:153], v[174:177], v[56:59]
	v_mfma_f32_16x16x32_bf16 v[44:47], v[142:145], v[182:185], v[44:47]
	v_mfma_f32_16x16x32_bf16 v[40:43], v[150:153], v[182:185], v[40:43]
	v_mfma_f32_16x16x32_bf16 v[28:31], v[142:145], v[194:197], v[28:31]
	v_mfma_f32_16x16x32_bf16 v[24:27], v[150:153], v[194:197], v[24:27]
	v_mfma_f32_16x16x32_bf16 v[12:15], v[142:145], v[202:205], v[12:15]
	v_mfma_f32_16x16x32_bf16 v[8:11], v[150:153], v[202:205], v[8:11]
	v_mfma_f32_16x16x32_bf16 v[52:55], v[154:157], v[170:173], v[52:55]
	v_mfma_f32_16x16x32_bf16 v[48:51], v[162:165], v[170:173], v[48:51]
	v_mfma_f32_16x16x32_bf16 v[36:39], v[154:157], v[178:181], v[36:39]
	v_mfma_f32_16x16x32_bf16 v[32:35], v[162:165], v[178:181], v[32:35]
	v_mfma_f32_16x16x32_bf16 v[20:23], v[154:157], v[186:189], v[20:23]
	v_mfma_f32_16x16x32_bf16 v[16:19], v[162:165], v[186:189], v[16:19]
	v_mfma_f32_16x16x32_bf16 v[4:7], v[154:157], v[198:201], v[4:7]
	v_mfma_f32_16x16x32_bf16 v[0:3], v[162:165], v[198:201], v[0:3]
	v_mfma_f32_16x16x32_bf16 v[52:55], v[158:161], v[174:177], v[52:55]
	v_mfma_f32_16x16x32_bf16 v[48:51], v[166:169], v[174:177], v[48:51]
	v_mfma_f32_16x16x32_bf16 v[36:39], v[158:161], v[182:185], v[36:39]
	v_mfma_f32_16x16x32_bf16 v[32:35], v[166:169], v[182:185], v[32:35]
	v_mfma_f32_16x16x32_bf16 v[20:23], v[158:161], v[194:197], v[20:23]
	v_mfma_f32_16x16x32_bf16 v[16:19], v[166:169], v[194:197], v[16:19]
	v_mfma_f32_16x16x32_bf16 v[4:7], v[158:161], v[202:205], v[4:7]
	v_mfma_f32_16x16x32_bf16 v[0:3], v[166:169], v[202:205], v[0:3]
	s_setprio 0
	s_barrier
; #define PG8_STAGE(bufoff, gbase, voff) do { _Pragma("unroll") for (int _i = 0; _i < 2; ++_i) \
;         asm volatile("s_mov_b32 m0, %0\n\ts_nop 0\n\tglobal_load_lds_dwordx4 %1, %2" :: "s"(ldsb + (unsigned)((bufoff) + _i * 8192)), "v"((voff)[_i]), "s"(gbase) : "m0", "memory"); } while (0)
; #define PG8_LDA(dst, b, h) do { _Pragma("unroll") for (int m = 0; m < 4; ++m) _Pragma("unroll") for (int k = 0; k < 2; ++k) dst[m][k] = *(const PG8_LAS bf16x8*)(lds + PG8_SA(b, h) + aoff + m * 2048 + k * 1024); } while (0)
; #define PG8_LDB(dst, b, h) do { _Pragma("unroll") for (int n = 0; n < 2; ++n) _Pragma("unroll") for (int k = 0; k < 2; ++k) dst[n][k] = *(const PG8_LAS bf16x8*)(lds + PG8_SB(b, h) + boff + n * 2048 + k * 1024); } while (0)
; #define PG8_MMA(ai, bj, At, Bt) do { __builtin_amdgcn_s_setprio(1); _Pragma("unroll") for (int m = 0; m < 4; ++m) _Pragma("unroll") for (int n = 0; n < 2; ++n) _Pragma("unroll") for (int k = 0; k < 2; ++k) \
;         acc[ai][bj][m][n] = __builtin_amdgcn_mfma_f32_16x16x32_bf16(Bt[n][k], At[m][k], acc[ai][bj][m][n], 0, 0, 0); __builtin_amdgcn_s_setprio(0); } while (0)
; #define PG8_WAIT_V(n) asm volatile("s_waitcnt vmcnt(" #n ")" ::: "memory")
; #define PG8_WAIT_L(n) asm volatile("s_waitcnt lgkmcnt(" #n ")" ::: "memory")
; #define PG8_BAR __builtin_amdgcn_s_barrier()
; #define PG8_SCHED __builtin_amdgcn_sched_barrier(0)
; template <class Epi, class Sched, bool ALIGN_EPI = false, bool SP2 = false>
; __device__ __forceinline__ void gemm_phase(PG8_LAS unsigned char* lds, const Gemm g, const Sched& S, const Epi& E, const int wv) {
;     ...
;             PG8_LDB(B0, 1, 0); PG8_LDB(B1, 1, 1); PG8_SCHED; PG8_LDA(At, 1, 0); PG8_STAGE(PG8_SA(0, 1), a2 + hstepA, voffA);
;             PG8_WAIT_V(8); PG8_WAIT_L(0); PG8_BAR; PG8_MMA(0, 0, At, B0); PG8_MMA(0, 1, At, B1); PG8_BAR; PG8_SCHED;
;             PG8_LDA(At, 1, 1); PG8_STAGE(PG8_SB(1, 0), b3, voffB); PG8_STAGE(PG8_SB(1, 1), b3 + hstepB, voffB); PG8_STAGE(PG8_SA(1, 0), a3, voffA);
;             PG8_WAIT_V(8); PG8_WAIT_L(0); PG8_BAR; PG8_MMA(1, 0, At, B0); PG8_MMA(1, 1, At, B1); PG8_BAR; PG8_SCHED;
	v_add_u32_e32 v137, 0x18000, v134
	ds_read_b128 v[138:141], v137
	ds_read_b128 v[142:145], v137 offset:1024
	ds_read_b128 v[146:149], v137 offset:2048
	ds_read_b128 v[150:153], v137 offset:3072
	v_add_u32_e32 v137, 0x1c000, v134
	ds_read_b128 v[154:157], v137
	ds_read_b128 v[158:161], v137 offset:1024
	ds_read_b128 v[162:165], v137 offset:2048
	ds_read_b128 v[166:169], v137 offset:3072
	ds_read_b128 v[170:173], v135 offset:32768
	ds_read_b128 v[174:177], v135 offset:33792
	ds_read_b128 v[178:181], v135 offset:34816
	ds_read_b128 v[182:185], v135 offset:35840
	ds_read_b128 v[186:189], v135 offset:36864
	ds_read_b128 v[194:197], v135 offset:37888
	ds_read_b128 v[198:201], v135 offset:38912
	ds_read_b128 v[202:205], v135 offset:39936
	s_add_u32 s22, s22, 0x20000
	s_addc_u32 s23, s23, 0
	s_mov_b32 m0, s34
	s_nop 0
	global_load_lds_dwordx4 v128, s[22:23]
	s_nop 0
	s_mov_b32 m0, s35
	s_nop 0
	global_load_lds_dwordx4 v130, s[22:23]
	s_waitcnt vmcnt(8) lgkmcnt(0)
	s_setprio 1
	s_barrier
	v_mfma_f32_16x16x32_bf16 v[124:127], v[138:141], v[170:173], v[124:127]
	v_mfma_f32_16x16x32_bf16 v[120:123], v[146:149], v[170:173], v[120:123]
	v_mfma_f32_16x16x32_bf16 v[108:111], v[138:141], v[178:181], v[108:111]
	v_mfma_f32_16x16x32_bf16 v[104:107], v[146:149], v[178:181], v[104:107]
	v_mfma_f32_16x16x32_bf16 v[92:95], v[138:141], v[186:189], v[92:95]
	v_mfma_f32_16x16x32_bf16 v[88:91], v[146:149], v[186:189], v[88:91]
	v_mfma_f32_16x16x32_bf16 v[76:79], v[138:141], v[198:201], v[76:79]
	v_mfma_f32_16x16x32_bf16 v[72:75], v[146:149], v[198:201], v[72:75]
	v_mfma_f32_16x16x32_bf16 v[124:127], v[142:145], v[174:177], v[124:127]
	v_mfma_f32_16x16x32_bf16 v[120:123], v[150:153], v[174:177], v[120:123]
	v_mfma_f32_16x16x32_bf16 v[108:111], v[142:145], v[182:185], v[108:111]
	v_mfma_f32_16x16x32_bf16 v[104:107], v[150:153], v[182:185], v[104:107]
	v_mfma_f32_16x16x32_bf16 v[92:95], v[142:145], v[194:197], v[92:95]
	v_mfma_f32_16x16x32_bf16 v[88:91], v[150:153], v[194:197], v[88:91]
	v_mfma_f32_16x16x32_bf16 v[76:79], v[142:145], v[202:205], v[76:79]
	v_mfma_f32_16x16x32_bf16 v[72:75], v[150:153], v[202:205], v[72:75]
	v_mfma_f32_16x16x32_bf16 v[116:119], v[154:157], v[170:173], v[116:119]
	v_mfma_f32_16x16x32_bf16 v[112:115], v[162:165], v[170:173], v[112:115]
	v_mfma_f32_16x16x32_bf16 v[100:103], v[154:157], v[178:181], v[100:103]
	v_mfma_f32_16x16x32_bf16 v[96:99], v[162:165], v[178:181], v[96:99]
	v_mfma_f32_16x16x32_bf16 v[84:87], v[154:157], v[186:189], v[84:87]
	v_mfma_f32_16x16x32_bf16 v[80:83], v[162:165], v[186:189], v[80:83]
	v_mfma_f32_16x16x32_bf16 v[68:71], v[154:157], v[198:201], v[68:71]
	v_mfma_f32_16x16x32_bf16 v[64:67], v[162:165], v[198:201], v[64:67]
	v_mfma_f32_16x16x32_bf16 v[116:119], v[158:161], v[174:177], v[116:119]
	v_mfma_f32_16x16x32_bf16 v[112:115], v[166:169], v[174:177], v[112:115]
	v_mfma_f32_16x16x32_bf16 v[100:103], v[158:161], v[182:185], v[100:103]
	v_mfma_f32_16x16x32_bf16 v[96:99], v[166:169], v[182:185], v[96:99]
	v_mfma_f32_16x16x32_bf16 v[84:87], v[158:161], v[194:197], v[84:87]
	v_mfma_f32_16x16x32_bf16 v[80:83], v[166:169], v[194:197], v[80:83]
	v_mfma_f32_16x16x32_bf16 v[68:71], v[158:161], v[202:205], v[68:71]
	v_mfma_f32_16x16x32_bf16 v[64:67], v[166:169], v[202:205], v[64:67]
	s_setprio 0
	s_barrier
	ds_read_b128 v[170:173], v135 offset:49152
	ds_read_b128 v[174:177], v135 offset:50176
	ds_read_b128 v[178:181], v135 offset:51200
	ds_read_b128 v[182:185], v135 offset:52224
	ds_read_b128 v[186:189], v135 offset:53248
	ds_read_b128 v[194:197], v135 offset:54272
	ds_read_b128 v[198:201], v135 offset:55296
	ds_read_b128 v[202:205], v135 offset:56320
	s_add_u32 s22, s20, 0x80
	s_addc_u32 s23, s21, 0
	s_mov_b32 m0, s36
	s_nop 0
	global_load_lds_dwordx4 v129, s[22:23]
	s_add_u32 s20, s20, 0x20080
	s_mov_b32 m0, s37
	s_nop 0
	global_load_lds_dwordx4 v131, s[22:23]
	s_addc_u32 s21, s21, 0
	s_mov_b32 m0, s43
	s_nop 0
	global_load_lds_dwordx4 v129, s[20:21]
	s_nop 0
	s_mov_b32 m0, s44
	s_nop 0
	global_load_lds_dwordx4 v131, s[20:21]
	s_nop 0
	s_mov_b32 m0, s40
	s_nop 0
	global_load_lds_dwordx4 v128, s[18:19]
	s_nop 0
	s_mov_b32 m0, s42
	s_nop 0
	global_load_lds_dwordx4 v130, s[18:19]
	s_waitcnt vmcnt(8) lgkmcnt(0)
	s_setprio 1
	s_barrier
	v_mfma_f32_16x16x32_bf16 v[60:63], v[138:141], v[170:173], v[60:63]
	v_mfma_f32_16x16x32_bf16 v[56:59], v[146:149], v[170:173], v[56:59]
	v_mfma_f32_16x16x32_bf16 v[44:47], v[138:141], v[178:181], v[44:47]
	v_mfma_f32_16x16x32_bf16 v[40:43], v[146:149], v[178:181], v[40:43]
	v_mfma_f32_16x16x32_bf16 v[28:31], v[138:141], v[186:189], v[28:31]
	v_mfma_f32_16x16x32_bf16 v[24:27], v[146:149], v[186:189], v[24:27]
	v_mfma_f32_16x16x32_bf16 v[12:15], v[138:141], v[198:201], v[12:15]
	v_mfma_f32_16x16x32_bf16 v[8:11], v[146:149], v[198:201], v[8:11]
	v_mfma_f32_16x16x32_bf16 v[60:63], v[142:145], v[174:177], v[60:63]
	v_mfma_f32_16x16x32_bf16 v[56:59], v[150:153], v[174:177], v[56:59]
	v_mfma_f32_16x16x32_bf16 v[44:47], v[142:145], v[182:185], v[44:47]
	v_mfma_f32_16x16x32_bf16 v[40:43], v[150:153], v[182:185], v[40:43]
	v_mfma_f32_16x16x32_bf16 v[28:31], v[142:145], v[194:197], v[28:31]
	v_mfma_f32_16x16x32_bf16 v[24:27], v[150:153], v[194:197], v[24:27]
	v_mfma_f32_16x16x32_bf16 v[12:15], v[142:145], v[202:205], v[12:15]
	v_mfma_f32_16x16x32_bf16 v[8:11], v[150:153], v[202:205], v[8:11]
	v_mfma_f32_16x16x32_bf16 v[52:55], v[154:157], v[170:173], v[52:55]
	v_mfma_f32_16x16x32_bf16 v[48:51], v[162:165], v[170:173], v[48:51]
	v_mfma_f32_16x16x32_bf16 v[36:39], v[154:157], v[178:181], v[36:39]
	v_mfma_f32_16x16x32_bf16 v[32:35], v[162:165], v[178:181], v[32:35]
	v_mfma_f32_16x16x32_bf16 v[20:23], v[154:157], v[186:189], v[20:23]
	v_mfma_f32_16x16x32_bf16 v[16:19], v[162:165], v[186:189], v[16:19]
	v_mfma_f32_16x16x32_bf16 v[4:7], v[154:157], v[198:201], v[4:7]
	v_mfma_f32_16x16x32_bf16 v[0:3], v[162:165], v[198:201], v[0:3]
	v_mfma_f32_16x16x32_bf16 v[52:55], v[158:161], v[174:177], v[52:55]
	v_mfma_f32_16x16x32_bf16 v[48:51], v[166:169], v[174:177], v[48:51]
	v_mfma_f32_16x16x32_bf16 v[36:39], v[158:161], v[182:185], v[36:39]
	v_mfma_f32_16x16x32_bf16 v[32:35], v[166:169], v[182:185], v[32:35]
	v_mfma_f32_16x16x32_bf16 v[20:23], v[158:161], v[194:197], v[20:23]
	v_mfma_f32_16x16x32_bf16 v[16:19], v[166:169], v[194:197], v[16:19]
	v_mfma_f32_16x16x32_bf16 v[4:7], v[158:161], v[202:205], v[4:7]
	v_mfma_f32_16x16x32_bf16 v[0:3], v[166:169], v[202:205], v[0:3]
	s_setprio 0
	s_barrier
	s_add_u32 s60, s60, 0x100
	s_addc_u32 s62, s62, 0
	s_add_u32 s65, s65, 0x100
	s_addc_u32 s71, s71, 0
	s_cmp_ge_i32 s72, s55
	s_mov_b32 s18, s72
	s_cbranch_scc0 .LBB0_864
	s_and_b64 vcc, exec, s[10:11]
	s_cbranch_vccz .LBB0_867

; #define PG8_STAGE(bufoff, gbase, voff) do { _Pragma("unroll") for (int _i = 0; _i < 2; ++_i) \
;         asm volatile("s_mov_b32 m0, %0\n\ts_nop 0\n\tglobal_load_lds_dwordx4 %1, %2" :: "s"(ldsb + (unsigned)((bufoff) + _i * 8192)), "v"((voff)[_i]), "s"(gbase) : "m0", "memory"); } while (0)
; #define PG8_LDA(dst, b, h) do { _Pragma("unroll") for (int m = 0; m < 4; ++m) _Pragma("unroll") for (int k = 0; k < 2; ++k) dst[m][k] = *(const PG8_LAS bf16x8*)(lds + PG8_SA(b, h) + aoff + m * 2048 + k * 1024); } while (0)
; #define PG8_LDB(dst, b, h) do { _Pragma("unroll") for (int n = 0; n < 2; ++n) _Pragma("unroll") for (int k = 0; k < 2; ++k) dst[n][k] = *(const PG8_LAS bf16x8*)(lds + PG8_SB(b, h) + boff + n * 2048 + k * 1024); } while (0)
; #define PG8_MMA(ai, bj, At, Bt) do { __builtin_amdgcn_s_setprio(1); _Pragma("unroll") for (int m = 0; m < 4; ++m) _Pragma("unroll") for (int n = 0; n < 2; ++n) _Pragma("unroll") for (int k = 0; k < 2; ++k) \
;         acc[ai][bj][m][n] = __builtin_amdgcn_mfma_f32_16x16x32_bf16(Bt[n][k], At[m][k], acc[ai][bj][m][n], 0, 0, 0); __builtin_amdgcn_s_setprio(0); } while (0)
; #define PG8_WAIT_V(n) asm volatile("s_waitcnt vmcnt(" #n ")" ::: "memory")
; template <class Epi, class Sched, bool ALIGN_EPI = false, bool SP2 = false>
; __device__ __forceinline__ void gemm_phase(PG8_LAS unsigned char* lds, const Gemm g, const Sched& S, const Epi& E, const int wv) {
;     ...
;         for (int t = 0; t < nt; t += 2) {
;             const bool last = (t == nt - 2);
;             const char* a1 = cA + (size_t)(t + 1) * kstep;
;             const char* a2 = last ? nA : cA + (size_t)(t + 2) * kstep; const char* b2 = last ? nB : cB + (size_t)(t + 2) * kstep;
;             const char* a3 = a2 + kstep; const char* b3 = b2 + kstep;
;             if (last && has_next) S.a_ready(nxt);
;             if constexpr (SP2) {
;             PG8_LDB(B0, 0, 0); PG8_LDB(B1, 0, 1); PG8_SCHED; PG8_LDA(At, 0, 0); PG8_STAGE(PG8_SA(1, 1), a1 + hstepA, voffA);
;             PG8_WAIT_V(8); PG8_WAIT_L(0); PG8_BAR; PG8_MMA(0, 0, At, B0); PG8_MMA(0, 1, At, B1); PG8_BAR; PG8_SCHED;
;             PG8_LDA(At, 0, 1); PG8_STAGE(PG8_SB(0, 0), b2, voffB); PG8_STAGE(PG8_SB(0, 1), b2 + hstepB, voffB); PG8_STAGE(PG8_SA(0, 0), a2, voffA);
;             PG8_WAIT_V(8); PG8_WAIT_L(0); PG8_BAR; PG8_MMA(1, 0, At, B0); PG8_MMA(1, 1, At, B1); PG8_BAR; PG8_SCHED;
.LBB0_1031:
	v_add_u32_e32 v124, 0x10000, v220
	v_add_u32_e32 v156, 0x14000, v220
	ds_read_b128 v[108:111], v124
	ds_read_b128 v[116:119], v124 offset:1024
	ds_read_b128 v[120:123], v124 offset:2048
	ds_read_b128 v[124:127], v124 offset:3072
	ds_read_b128 v[144:147], v156
	ds_read_b128 v[148:151], v156 offset:1024
	ds_read_b128 v[152:155], v156 offset:2048
	ds_read_b128 v[156:159], v156 offset:3072
	s_add_i32 s12, s34, 2
	s_cmp_eq_u32 s11, s34
	s_cselect_b32 s42, s26, vcc_lo
	s_cselect_b32 s43, s27, vcc_hi
	s_cselect_b32 s36, s28, s79
	s_cselect_b32 s37, s29, s62
	s_add_u32 s34, s42, 0x80
	s_addc_u32 s35, s43, 0
	ds_read_b128 v[160:163], v221
	ds_read_b128 v[164:167], v221 offset:1024
	ds_read_b128 v[168:171], v221 offset:2048
	ds_read_b128 v[176:179], v221 offset:3072
	ds_read_b128 v[180:183], v221 offset:4096
	ds_read_b128 v[184:187], v221 offset:5120
	ds_read_b128 v[188:191], v221 offset:6144
	ds_read_b128 v[194:197], v221 offset:7168
	s_mov_b32 m0, s88
	s_nop 0
	global_load_lds_dwordx4 v208, s[30:31]
	s_nop 0
	s_mov_b32 m0, s93
	s_nop 0
	global_load_lds_dwordx4 v210, s[30:31]
	s_waitcnt vmcnt(8) lgkmcnt(0)
	s_setprio 1
	s_barrier
	v_mfma_f32_16x16x32_bf16 v[140:143], v[108:111], v[160:163], v[140:143]
	v_mfma_f32_16x16x32_bf16 v[136:139], v[120:123], v[160:163], v[136:139]
	v_mfma_f32_16x16x32_bf16 v[112:115], v[108:111], v[168:171], v[112:115]
	v_mfma_f32_16x16x32_bf16 v[104:107], v[120:123], v[168:171], v[104:107]
	v_mfma_f32_16x16x32_bf16 v[92:95], v[108:111], v[180:183], v[92:95]
	v_mfma_f32_16x16x32_bf16 v[88:91], v[120:123], v[180:183], v[88:91]
	v_mfma_f32_16x16x32_bf16 v[76:79], v[108:111], v[188:191], v[76:79]
	v_mfma_f32_16x16x32_bf16 v[72:75], v[120:123], v[188:191], v[72:75]
	v_mfma_f32_16x16x32_bf16 v[140:143], v[116:119], v[164:167], v[140:143]
	v_mfma_f32_16x16x32_bf16 v[136:139], v[124:127], v[164:167], v[136:139]
	v_mfma_f32_16x16x32_bf16 v[112:115], v[116:119], v[176:179], v[112:115]
	v_mfma_f32_16x16x32_bf16 v[104:107], v[124:127], v[176:179], v[104:107]
	v_mfma_f32_16x16x32_bf16 v[92:95], v[116:119], v[184:187], v[92:95]
	v_mfma_f32_16x16x32_bf16 v[88:91], v[124:127], v[184:187], v[88:91]
	v_mfma_f32_16x16x32_bf16 v[76:79], v[116:119], v[194:197], v[76:79]
	v_mfma_f32_16x16x32_bf16 v[72:75], v[124:127], v[194:197], v[72:75]
	v_mfma_f32_16x16x32_bf16 v[132:135], v[144:147], v[160:163], v[132:135]
	v_mfma_f32_16x16x32_bf16 v[128:131], v[152:155], v[160:163], v[128:131]
	v_mfma_f32_16x16x32_bf16 v[100:103], v[144:147], v[168:171], v[100:103]
	v_mfma_f32_16x16x32_bf16 v[96:99], v[152:155], v[168:171], v[96:99]
	v_mfma_f32_16x16x32_bf16 v[84:87], v[144:147], v[180:183], v[84:87]
	v_mfma_f32_16x16x32_bf16 v[80:83], v[152:155], v[180:183], v[80:83]
	v_mfma_f32_16x16x32_bf16 v[68:71], v[144:147], v[188:191], v[68:71]
	v_mfma_f32_16x16x32_bf16 v[64:67], v[152:155], v[188:191], v[64:67]
	v_mfma_f32_16x16x32_bf16 v[132:135], v[148:151], v[164:167], v[132:135]
	v_mfma_f32_16x16x32_bf16 v[128:131], v[156:159], v[164:167], v[128:131]
	v_mfma_f32_16x16x32_bf16 v[100:103], v[148:151], v[176:179], v[100:103]
	v_mfma_f32_16x16x32_bf16 v[96:99], v[156:159], v[176:179], v[96:99]
	v_mfma_f32_16x16x32_bf16 v[84:87], v[148:151], v[184:187], v[84:87]
	v_mfma_f32_16x16x32_bf16 v[80:83], v[156:159], v[184:187], v[80:83]
	v_mfma_f32_16x16x32_bf16 v[68:71], v[148:151], v[194:197], v[68:71]
	v_mfma_f32_16x16x32_bf16 v[64:67], v[156:159], v[194:197], v[64:67]
	s_setprio 0
	s_barrier
	ds_read_b128 v[160:163], v221 offset:16384
	ds_read_b128 v[164:167], v221 offset:17408
	ds_read_b128 v[168:171], v221 offset:18432
	ds_read_b128 v[176:179], v221 offset:19456
	ds_read_b128 v[180:183], v221 offset:20480
	ds_read_b128 v[184:187], v221 offset:21504
	ds_read_b128 v[188:191], v221 offset:22528
	ds_read_b128 v[194:197], v221 offset:23552
	s_mov_b32 m0, s48
	s_nop 0
	global_load_lds_dwordx4 v209, s[36:37]
	s_add_u32 s44, s36, 0x80000
	s_mov_b32 m0, s49
	s_nop 0
	global_load_lds_dwordx4 v211, s[36:37]
	s_addc_u32 s45, s37, 0
	s_mov_b32 m0, s50
	s_nop 0
	global_load_lds_dwordx4 v209, s[44:45]
	s_nop 0
	s_mov_b32 m0, s51
	s_nop 0
	global_load_lds_dwordx4 v211, s[44:45]
	s_nop 0
	s_mov_b32 m0, s47
	s_nop 0
	global_load_lds_dwordx4 v208, s[42:43]
	s_nop 0
	s_mov_b32 m0, s52
	s_nop 0
	global_load_lds_dwordx4 v210, s[42:43]
	s_waitcnt vmcnt(8) lgkmcnt(0)
	s_setprio 1
	s_barrier
	v_mfma_f32_16x16x32_bf16 v[60:63], v[108:111], v[160:163], v[60:63]
	v_mfma_f32_16x16x32_bf16 v[56:59], v[120:123], v[160:163], v[56:59]
	v_mfma_f32_16x16x32_bf16 v[44:47], v[108:111], v[168:171], v[44:47]
	v_mfma_f32_16x16x32_bf16 v[40:43], v[120:123], v[168:171], v[40:43]
	v_mfma_f32_16x16x32_bf16 v[28:31], v[108:111], v[180:183], v[28:31]
	v_mfma_f32_16x16x32_bf16 v[24:27], v[120:123], v[180:183], v[24:27]
	v_mfma_f32_16x16x32_bf16 v[12:15], v[108:111], v[188:191], v[12:15]
	v_mfma_f32_16x16x32_bf16 v[8:11], v[120:123], v[188:191], v[8:11]
	v_mfma_f32_16x16x32_bf16 v[60:63], v[116:119], v[164:167], v[60:63]
	v_mfma_f32_16x16x32_bf16 v[56:59], v[124:127], v[164:167], v[56:59]
	v_mfma_f32_16x16x32_bf16 v[44:47], v[116:119], v[176:179], v[44:47]
	v_mfma_f32_16x16x32_bf16 v[40:43], v[124:127], v[176:179], v[40:43]
	v_mfma_f32_16x16x32_bf16 v[28:31], v[116:119], v[184:187], v[28:31]
	v_mfma_f32_16x16x32_bf16 v[24:27], v[124:127], v[184:187], v[24:27]
	v_mfma_f32_16x16x32_bf16 v[12:15], v[116:119], v[194:197], v[12:15]
	v_mfma_f32_16x16x32_bf16 v[8:11], v[124:127], v[194:197], v[8:11]
	v_mfma_f32_16x16x32_bf16 v[52:55], v[144:147], v[160:163], v[52:55]
	v_mfma_f32_16x16x32_bf16 v[48:51], v[152:155], v[160:163], v[48:51]
	v_mfma_f32_16x16x32_bf16 v[36:39], v[144:147], v[168:171], v[36:39]
	v_mfma_f32_16x16x32_bf16 v[32:35], v[152:155], v[168:171], v[32:35]
	v_mfma_f32_16x16x32_bf16 v[20:23], v[144:147], v[180:183], v[20:23]
	v_mfma_f32_16x16x32_bf16 v[16:19], v[152:155], v[180:183], v[16:19]
	v_mfma_f32_16x16x32_bf16 v[4:7], v[144:147], v[188:191], v[4:7]
	v_mfma_f32_16x16x32_bf16 v[0:3], v[152:155], v[188:191], v[0:3]
	v_mfma_f32_16x16x32_bf16 v[52:55], v[148:151], v[164:167], v[52:55]
	v_mfma_f32_16x16x32_bf16 v[48:51], v[156:159], v[164:167], v[48:51]
	v_mfma_f32_16x16x32_bf16 v[36:39], v[148:151], v[176:179], v[36:39]
	v_mfma_f32_16x16x32_bf16 v[32:35], v[156:159], v[176:179], v[32:35]
	v_mfma_f32_16x16x32_bf16 v[20:23], v[148:151], v[184:187], v[20:23]
	v_mfma_f32_16x16x32_bf16 v[16:19], v[156:159], v[184:187], v[16:19]
	v_mfma_f32_16x16x32_bf16 v[4:7], v[148:151], v[194:197], v[4:7]
	v_mfma_f32_16x16x32_bf16 v[0:3], v[156:159], v[194:197], v[0:3]
	s_setprio 0
	s_barrier
; #define PG8_STAGE(bufoff, gbase, voff) do { _Pragma("unroll") for (int _i = 0; _i < 2; ++_i) \
;         asm volatile("s_mov_b32 m0, %0\n\ts_nop 0\n\tglobal_load_lds_dwordx4 %1, %2" :: "s"(ldsb + (unsigned)((bufoff) + _i * 8192)), "v"((voff)[_i]), "s"(gbase) : "m0", "memory"); } while (0)
; #define PG8_LDA(dst, b, h) do { _Pragma("unroll") for (int m = 0; m < 4; ++m) _Pragma("unroll") for (int k = 0; k < 2; ++k) dst[m][k] = *(const PG8_LAS bf16x8*)(lds + PG8_SA(b, h) + aoff + m * 2048 + k * 1024); } while (0)
; #define PG8_LDB(dst, b, h) do { _Pragma("unroll") for (int n = 0; n < 2; ++n) _Pragma("unroll") for (int k = 0; k < 2; ++k) dst[n][k] = *(const PG8_LAS bf16x8*)(lds + PG8_SB(b, h) + boff + n * 2048 + k * 1024); } while (0)
; #define PG8_MMA(ai, bj, At, Bt) do { __builtin_amdgcn_s_setprio(1); _Pragma("unroll") for (int m = 0; m < 4; ++m) _Pragma("unroll") for (int n = 0; n < 2; ++n) _Pragma("unroll") for (int k = 0; k < 2; ++k) \
;         acc[ai][bj][m][n] = __builtin_amdgcn_mfma_f32_16x16x32_bf16(Bt[n][k], At[m][k], acc[ai][bj][m][n], 0, 0, 0); __builtin_amdgcn_s_setprio(0); } while (0)
; #define PG8_WAIT_V(n) asm volatile("s_waitcnt vmcnt(" #n ")" ::: "memory")
; #define PG8_WAIT_L(n) asm volatile("s_waitcnt lgkmcnt(" #n ")" ::: "memory")
; #define PG8_BAR __builtin_amdgcn_s_barrier()
; #define PG8_SCHED __builtin_amdgcn_sched_barrier(0)
; template <class Epi, class Sched, bool ALIGN_EPI = false, bool SP2 = false>
; __device__ __forceinline__ void gemm_phase(PG8_LAS unsigned char* lds, const Gemm g, const Sched& S, const Epi& E, const int wv) {
;     ...
;             PG8_LDB(B0, 1, 0); PG8_LDB(B1, 1, 1); PG8_SCHED; PG8_LDA(At, 1, 0); PG8_STAGE(PG8_SA(0, 1), a2 + hstepA, voffA);
;             PG8_WAIT_V(8); PG8_WAIT_L(0); PG8_BAR; PG8_MMA(0, 0, At, B0); PG8_MMA(0, 1, At, B1); PG8_BAR; PG8_SCHED;
;             PG8_LDA(At, 1, 1); PG8_STAGE(PG8_SB(1, 0), b3, voffB); PG8_STAGE(PG8_SB(1, 1), b3 + hstepB, voffB); PG8_STAGE(PG8_SA(1, 0), a3, voffA);
;             PG8_WAIT_V(8); PG8_WAIT_L(0); PG8_BAR; PG8_MMA(1, 0, At, B0); PG8_MMA(1, 1, At, B1); PG8_BAR; PG8_SCHED;
	v_add_u32_e32 v124, 0x18000, v220
	v_add_u32_e32 v156, 0x1c000, v220
	ds_read_b128 v[108:111], v124
	ds_read_b128 v[116:119], v124 offset:1024
	ds_read_b128 v[120:123], v124 offset:2048
	ds_read_b128 v[124:127], v124 offset:3072
	ds_read_b128 v[144:147], v156
	ds_read_b128 v[148:151], v156 offset:1024
	ds_read_b128 v[152:155], v156 offset:2048
	ds_read_b128 v[156:159], v156 offset:3072
	ds_read_b128 v[160:163], v221 offset:32768
	ds_read_b128 v[164:167], v221 offset:33792
	ds_read_b128 v[168:171], v221 offset:34816
	ds_read_b128 v[176:179], v221 offset:35840
	ds_read_b128 v[180:183], v221 offset:36864
	ds_read_b128 v[184:187], v221 offset:37888
	ds_read_b128 v[188:191], v221 offset:38912
	ds_read_b128 v[194:197], v221 offset:39936
	s_add_u32 s42, s42, 0x84000
	s_addc_u32 s43, s43, 0
	s_mov_b32 m0, s53
	s_nop 0
	global_load_lds_dwordx4 v208, s[42:43]
	s_nop 0
	s_mov_b32 m0, s54
	s_nop 0
	global_load_lds_dwordx4 v210, s[42:43]
	s_waitcnt vmcnt(8) lgkmcnt(0)
	s_setprio 1
	s_barrier
	v_mfma_f32_16x16x32_bf16 v[140:143], v[108:111], v[160:163], v[140:143]
	v_mfma_f32_16x16x32_bf16 v[136:139], v[120:123], v[160:163], v[136:139]
	v_mfma_f32_16x16x32_bf16 v[112:115], v[108:111], v[168:171], v[112:115]
	v_mfma_f32_16x16x32_bf16 v[104:107], v[120:123], v[168:171], v[104:107]
	v_mfma_f32_16x16x32_bf16 v[92:95], v[108:111], v[180:183], v[92:95]
	v_mfma_f32_16x16x32_bf16 v[88:91], v[120:123], v[180:183], v[88:91]
	v_mfma_f32_16x16x32_bf16 v[76:79], v[108:111], v[188:191], v[76:79]
	v_mfma_f32_16x16x32_bf16 v[72:75], v[120:123], v[188:191], v[72:75]
	v_mfma_f32_16x16x32_bf16 v[140:143], v[116:119], v[164:167], v[140:143]
	v_mfma_f32_16x16x32_bf16 v[136:139], v[124:127], v[164:167], v[136:139]
	v_mfma_f32_16x16x32_bf16 v[112:115], v[116:119], v[176:179], v[112:115]
	v_mfma_f32_16x16x32_bf16 v[104:107], v[124:127], v[176:179], v[104:107]
	v_mfma_f32_16x16x32_bf16 v[92:95], v[116:119], v[184:187], v[92:95]
	v_mfma_f32_16x16x32_bf16 v[88:91], v[124:127], v[184:187], v[88:91]
	v_mfma_f32_16x16x32_bf16 v[76:79], v[116:119], v[194:197], v[76:79]
	v_mfma_f32_16x16x32_bf16 v[72:75], v[124:127], v[194:197], v[72:75]
	v_mfma_f32_16x16x32_bf16 v[132:135], v[144:147], v[160:163], v[132:135]
	v_mfma_f32_16x16x32_bf16 v[128:131], v[152:155], v[160:163], v[128:131]
	v_mfma_f32_16x16x32_bf16 v[100:103], v[144:147], v[168:171], v[100:103]
	v_mfma_f32_16x16x32_bf16 v[96:99], v[152:155], v[168:171], v[96:99]
	v_mfma_f32_16x16x32_bf16 v[84:87], v[144:147], v[180:183], v[84:87]
	v_mfma_f32_16x16x32_bf16 v[80:83], v[152:155], v[180:183], v[80:83]
	v_mfma_f32_16x16x32_bf16 v[68:71], v[144:147], v[188:191], v[68:71]
	v_mfma_f32_16x16x32_bf16 v[64:67], v[152:155], v[188:191], v[64:67]
	v_mfma_f32_16x16x32_bf16 v[132:135], v[148:151], v[164:167], v[132:135]
	v_mfma_f32_16x16x32_bf16 v[128:131], v[156:159], v[164:167], v[128:131]
	v_mfma_f32_16x16x32_bf16 v[100:103], v[148:151], v[176:179], v[100:103]
	v_mfma_f32_16x16x32_bf16 v[96:99], v[156:159], v[176:179], v[96:99]
	v_mfma_f32_16x16x32_bf16 v[84:87], v[148:151], v[184:187], v[84:87]
	v_mfma_f32_16x16x32_bf16 v[80:83], v[156:159], v[184:187], v[80:83]
	v_mfma_f32_16x16x32_bf16 v[68:71], v[148:151], v[194:197], v[68:71]
	v_mfma_f32_16x16x32_bf16 v[64:67], v[156:159], v[194:197], v[64:67]
	s_setprio 0
	s_barrier
	ds_read_b128 v[160:163], v221 offset:49152
	ds_read_b128 v[164:167], v221 offset:50176
	ds_read_b128 v[168:171], v221 offset:51200
	ds_read_b128 v[176:179], v221 offset:52224
	ds_read_b128 v[180:183], v221 offset:53248
	ds_read_b128 v[184:187], v221 offset:54272
	ds_read_b128 v[188:191], v221 offset:55296
	ds_read_b128 v[194:197], v221 offset:56320
	s_add_u32 s42, s36, 0x80
	s_addc_u32 s43, s37, 0
	s_mov_b32 m0, s84
	s_nop 0
	global_load_lds_dwordx4 v209, s[42:43]
	s_add_u32 s36, s36, 0x80080
	s_mov_b32 m0, s71
	s_nop 0
	global_load_lds_dwordx4 v211, s[42:43]
	s_addc_u32 s37, s37, 0
	s_mov_b32 m0, s92
	s_nop 0
	global_load_lds_dwordx4 v209, s[36:37]
	s_nop 0
	s_mov_b32 m0, s58
	s_nop 0
	global_load_lds_dwordx4 v211, s[36:37]
	s_nop 0
	s_mov_b32 m0, s87
	s_nop 0
	global_load_lds_dwordx4 v208, s[34:35]
	s_nop 0
	s_mov_b32 m0, s89
	s_nop 0
	global_load_lds_dwordx4 v210, s[34:35]
	s_waitcnt vmcnt(8) lgkmcnt(0)
	s_setprio 1
	s_barrier
	v_mfma_f32_16x16x32_bf16 v[60:63], v[108:111], v[160:163], v[60:63]
	v_mfma_f32_16x16x32_bf16 v[56:59], v[120:123], v[160:163], v[56:59]
	v_mfma_f32_16x16x32_bf16 v[44:47], v[108:111], v[168:171], v[44:47]
	v_mfma_f32_16x16x32_bf16 v[40:43], v[120:123], v[168:171], v[40:43]
	v_mfma_f32_16x16x32_bf16 v[28:31], v[108:111], v[180:183], v[28:31]
	v_mfma_f32_16x16x32_bf16 v[24:27], v[120:123], v[180:183], v[24:27]
	v_mfma_f32_16x16x32_bf16 v[12:15], v[108:111], v[188:191], v[12:15]
	v_mfma_f32_16x16x32_bf16 v[8:11], v[120:123], v[188:191], v[8:11]
	v_mfma_f32_16x16x32_bf16 v[60:63], v[116:119], v[164:167], v[60:63]
	v_mfma_f32_16x16x32_bf16 v[56:59], v[124:127], v[164:167], v[56:59]
	v_mfma_f32_16x16x32_bf16 v[44:47], v[116:119], v[176:179], v[44:47]
	v_mfma_f32_16x16x32_bf16 v[40:43], v[124:127], v[176:179], v[40:43]
	v_mfma_f32_16x16x32_bf16 v[28:31], v[116:119], v[184:187], v[28:31]
	v_mfma_f32_16x16x32_bf16 v[24:27], v[124:127], v[184:187], v[24:27]
	v_mfma_f32_16x16x32_bf16 v[12:15], v[116:119], v[194:197], v[12:15]
	v_mfma_f32_16x16x32_bf16 v[8:11], v[124:127], v[194:197], v[8:11]
	v_mfma_f32_16x16x32_bf16 v[52:55], v[144:147], v[160:163], v[52:55]
	v_mfma_f32_16x16x32_bf16 v[48:51], v[152:155], v[160:163], v[48:51]
	v_mfma_f32_16x16x32_bf16 v[36:39], v[144:147], v[168:171], v[36:39]
	v_mfma_f32_16x16x32_bf16 v[32:35], v[152:155], v[168:171], v[32:35]
	v_mfma_f32_16x16x32_bf16 v[20:23], v[144:147], v[180:183], v[20:23]
	v_mfma_f32_16x16x32_bf16 v[16:19], v[152:155], v[180:183], v[16:19]
	v_mfma_f32_16x16x32_bf16 v[4:7], v[144:147], v[188:191], v[4:7]
	v_mfma_f32_16x16x32_bf16 v[0:3], v[152:155], v[188:191], v[0:3]
	v_mfma_f32_16x16x32_bf16 v[52:55], v[148:151], v[164:167], v[52:55]
	v_mfma_f32_16x16x32_bf16 v[48:51], v[156:159], v[164:167], v[48:51]
	v_mfma_f32_16x16x32_bf16 v[36:39], v[148:151], v[176:179], v[36:39]
	v_mfma_f32_16x16x32_bf16 v[32:35], v[156:159], v[176:179], v[32:35]
	v_mfma_f32_16x16x32_bf16 v[20:23], v[148:151], v[184:187], v[20:23]
	v_mfma_f32_16x16x32_bf16 v[16:19], v[156:159], v[184:187], v[16:19]
	v_mfma_f32_16x16x32_bf16 v[4:7], v[148:151], v[194:197], v[4:7]
	v_mfma_f32_16x16x32_bf16 v[0:3], v[156:159], v[194:197], v[0:3]
	s_setprio 0
	s_barrier
	s_add_u32 vcc_lo, vcc_lo, 0x100
	s_addc_u32 vcc_hi, vcc_hi, 0
	s_add_u32 s79, s79, 0x100
	s_addc_u32 s62, s62, 0
	s_add_u32 s30, s30, 0x100
	s_addc_u32 s31, s31, 0
	s_cmp_ge_i32 s12, s40
	s_mov_b32 s34, s12
	s_cbranch_scc0 .LBB0_1031
	s_mov_b32 s79, 0xc00000
	s_and_b64 vcc, exec, s[22:23]
	s_cbranch_vccz .LBB0_1034

; #define PG8_STAGE(bufoff, gbase, voff) do { _Pragma("unroll") for (int _i = 0; _i < 2; ++_i) \
;         asm volatile("s_mov_b32 m0, %0\n\ts_nop 0\n\tglobal_load_lds_dwordx4 %1, %2" :: "s"(ldsb + (unsigned)((bufoff) + _i * 8192)), "v"((voff)[_i]), "s"(gbase) : "m0", "memory"); } while (0)
; #define PG8_LDA(dst, b, h) do { _Pragma("unroll") for (int m = 0; m < 4; ++m) _Pragma("unroll") for (int k = 0; k < 2; ++k) dst[m][k] = *(const PG8_LAS bf16x8*)(lds + PG8_SA(b, h) + aoff + m * 2048 + k * 1024); } while (0)
; #define PG8_LDB(dst, b, h) do { _Pragma("unroll") for (int n = 0; n < 2; ++n) _Pragma("unroll") for (int k = 0; k < 2; ++k) dst[n][k] = *(const PG8_LAS bf16x8*)(lds + PG8_SB(b, h) + boff + n * 2048 + k * 1024); } while (0)
; #define PG8_MMA(ai, bj, At, Bt) do { __builtin_amdgcn_s_setprio(1); _Pragma("unroll") for (int m = 0; m < 4; ++m) _Pragma("unroll") for (int n = 0; n < 2; ++n) _Pragma("unroll") for (int k = 0; k < 2; ++k) \
;         acc[ai][bj][m][n] = __builtin_amdgcn_mfma_f32_16x16x32_bf16(Bt[n][k], At[m][k], acc[ai][bj][m][n], 0, 0, 0); __builtin_amdgcn_s_setprio(0); } while (0)
; #define PG8_WAIT_V(n) asm volatile("s_waitcnt vmcnt(" #n ")" ::: "memory")
; template <class Epi, class Sched, bool ALIGN_EPI = false, bool SP2 = false>
; __device__ __forceinline__ void gemm_phase(PG8_LAS unsigned char* lds, const Gemm g, const Sched& S, const Epi& E, const int wv) {
;     ...
;         for (int t = 0; t < nt; t += 2) {
;             const bool last = (t == nt - 2);
;             const char* a1 = cA + (size_t)(t + 1) * kstep;
;             const char* a2 = last ? nA : cA + (size_t)(t + 2) * kstep; const char* b2 = last ? nB : cB + (size_t)(t + 2) * kstep;
;             const char* a3 = a2 + kstep; const char* b3 = b2 + kstep;
;             if (last && has_next) S.a_ready(nxt);
;             if constexpr (SP2) {
;             PG8_LDB(B0, 0, 0); PG8_LDB(B1, 0, 1); PG8_SCHED; PG8_LDA(At, 0, 0); PG8_STAGE(PG8_SA(1, 1), a1 + hstepA, voffA);
;             PG8_WAIT_V(8); PG8_WAIT_L(0); PG8_BAR; PG8_MMA(0, 0, At, B0); PG8_MMA(0, 1, At, B1); PG8_BAR; PG8_SCHED;
;             PG8_LDA(At, 0, 1); PG8_STAGE(PG8_SB(0, 0), b2, voffB); PG8_STAGE(PG8_SB(0, 1), b2 + hstepB, voffB); PG8_STAGE(PG8_SA(0, 0), a2, voffA);
;             PG8_WAIT_V(8); PG8_WAIT_L(0); PG8_BAR; PG8_MMA(1, 0, At, B0); PG8_MMA(1, 1, At, B1); PG8_BAR; PG8_SCHED;
.LBB0_1175:
	v_add_u32_e32 v92, 0x10000, v160
	v_add_u32_e32 v144, 0x14000, v160
	ds_read_b128 v[80:83], v92
	ds_read_b128 v[84:87], v92 offset:1024
	ds_read_b128 v[88:91], v92 offset:2048
	ds_read_b128 v[92:95], v92 offset:3072
	ds_read_b128 v[164:167], v144
	ds_read_b128 v[168:171], v144 offset:1024
	ds_read_b128 v[172:175], v144 offset:2048
	ds_read_b128 v[176:179], v144 offset:3072
	s_add_i32 s88, s22, 2
	s_cmp_eq_u32 s62, s22
	s_cselect_b32 s26, s16, s79
	s_cselect_b32 s27, s17, s85
	s_cselect_b32 s24, s84, s86
	s_cselect_b32 s25, s83, s87
	s_add_u32 s22, s26, 0x80
	s_addc_u32 s23, s27, 0
	ds_read_b128 v[180:183], v161
	ds_read_b128 v[184:187], v161 offset:1024
	ds_read_b128 v[188:191], v161 offset:2048
	ds_read_b128 v[194:197], v161 offset:3072
	ds_read_b128 v[198:201], v161 offset:4096
	ds_read_b128 v[202:205], v161 offset:5120
	ds_read_b128 v[206:209], v161 offset:6144
	ds_read_b128 v[210:213], v161 offset:7168
	s_add_u32 s92, s79, 0x83f80
	s_addc_u32 s93, s85, 0
	s_mov_b32 m0, s54
	s_nop 0
	global_load_lds_dwordx4 v147, s[92:93]
	s_nop 0
	s_mov_b32 m0, s55
	s_nop 0
	global_load_lds_dwordx4 v151, s[92:93]
	s_waitcnt vmcnt(8) lgkmcnt(0)
	s_setprio 1
	s_barrier
	v_mfma_f32_16x16x32_bf16 v[140:143], v[80:83], v[180:183], v[140:143]
	v_mfma_f32_16x16x32_bf16 v[136:139], v[88:91], v[180:183], v[136:139]
	v_mfma_f32_16x16x32_bf16 v[124:127], v[80:83], v[188:191], v[124:127]
	v_mfma_f32_16x16x32_bf16 v[120:123], v[88:91], v[188:191], v[120:123]
	v_mfma_f32_16x16x32_bf16 v[108:111], v[80:83], v[198:201], v[108:111]
	v_mfma_f32_16x16x32_bf16 v[104:107], v[88:91], v[198:201], v[104:107]
	v_mfma_f32_16x16x32_bf16 v[76:79], v[80:83], v[206:209], v[76:79]
	v_mfma_f32_16x16x32_bf16 v[72:75], v[88:91], v[206:209], v[72:75]
	v_mfma_f32_16x16x32_bf16 v[140:143], v[84:87], v[184:187], v[140:143]
	v_mfma_f32_16x16x32_bf16 v[136:139], v[92:95], v[184:187], v[136:139]
	v_mfma_f32_16x16x32_bf16 v[124:127], v[84:87], v[194:197], v[124:127]
	v_mfma_f32_16x16x32_bf16 v[120:123], v[92:95], v[194:197], v[120:123]
	v_mfma_f32_16x16x32_bf16 v[108:111], v[84:87], v[202:205], v[108:111]
	v_mfma_f32_16x16x32_bf16 v[104:107], v[92:95], v[202:205], v[104:107]
	v_mfma_f32_16x16x32_bf16 v[76:79], v[84:87], v[210:213], v[76:79]
	v_mfma_f32_16x16x32_bf16 v[72:75], v[92:95], v[210:213], v[72:75]
	v_mfma_f32_16x16x32_bf16 v[132:135], v[164:167], v[180:183], v[132:135]
	v_mfma_f32_16x16x32_bf16 v[128:131], v[172:175], v[180:183], v[128:131]
	v_mfma_f32_16x16x32_bf16 v[116:119], v[164:167], v[188:191], v[116:119]
	v_mfma_f32_16x16x32_bf16 v[112:115], v[172:175], v[188:191], v[112:115]
	v_mfma_f32_16x16x32_bf16 v[100:103], v[164:167], v[198:201], v[100:103]
	v_mfma_f32_16x16x32_bf16 v[96:99], v[172:175], v[198:201], v[96:99]
	v_mfma_f32_16x16x32_bf16 v[68:71], v[164:167], v[206:209], v[68:71]
	v_mfma_f32_16x16x32_bf16 v[64:67], v[172:175], v[206:209], v[64:67]
	v_mfma_f32_16x16x32_bf16 v[132:135], v[168:171], v[184:187], v[132:135]
	v_mfma_f32_16x16x32_bf16 v[128:131], v[176:179], v[184:187], v[128:131]
	v_mfma_f32_16x16x32_bf16 v[116:119], v[168:171], v[194:197], v[116:119]
	v_mfma_f32_16x16x32_bf16 v[112:115], v[176:179], v[194:197], v[112:115]
	v_mfma_f32_16x16x32_bf16 v[100:103], v[168:171], v[202:205], v[100:103]
	v_mfma_f32_16x16x32_bf16 v[96:99], v[176:179], v[202:205], v[96:99]
	v_mfma_f32_16x16x32_bf16 v[68:71], v[168:171], v[210:213], v[68:71]
	v_mfma_f32_16x16x32_bf16 v[64:67], v[176:179], v[210:213], v[64:67]
	s_setprio 0
	s_barrier
	ds_read_b128 v[180:183], v161 offset:16384
	ds_read_b128 v[184:187], v161 offset:17408
	ds_read_b128 v[188:191], v161 offset:18432
	ds_read_b128 v[194:197], v161 offset:19456
	ds_read_b128 v[198:201], v161 offset:20480
	ds_read_b128 v[202:205], v161 offset:21504
	ds_read_b128 v[206:209], v161 offset:22528
	ds_read_b128 v[210:213], v161 offset:23552
	s_mov_b32 m0, s33
	s_nop 0
	global_load_lds_dwordx4 v149, s[24:25]
	s_add_u32 s92, s24, 0x80000
	s_mov_b32 m0, s34
	s_nop 0
	global_load_lds_dwordx4 v153, s[24:25]
	s_addc_u32 s93, s25, 0
	s_mov_b32 m0, s35
	s_nop 0
	global_load_lds_dwordx4 v149, s[92:93]
	s_nop 0
	s_mov_b32 m0, s36
	s_nop 0
	global_load_lds_dwordx4 v153, s[92:93]
	s_nop 0
	s_mov_b32 m0, s31
	s_nop 0
	global_load_lds_dwordx4 v147, s[26:27]
	s_nop 0
	s_mov_b32 m0, s37
	s_nop 0
	global_load_lds_dwordx4 v151, s[26:27]
	s_waitcnt vmcnt(8) lgkmcnt(0)
	s_setprio 1
	s_barrier
	v_mfma_f32_16x16x32_bf16 v[60:63], v[80:83], v[180:183], v[60:63]
	v_mfma_f32_16x16x32_bf16 v[56:59], v[88:91], v[180:183], v[56:59]
	v_mfma_f32_16x16x32_bf16 v[44:47], v[80:83], v[188:191], v[44:47]
	v_mfma_f32_16x16x32_bf16 v[40:43], v[88:91], v[188:191], v[40:43]
	v_mfma_f32_16x16x32_bf16 v[28:31], v[80:83], v[198:201], v[28:31]
	v_mfma_f32_16x16x32_bf16 v[24:27], v[88:91], v[198:201], v[24:27]
	v_mfma_f32_16x16x32_bf16 v[12:15], v[80:83], v[206:209], v[12:15]
	v_mfma_f32_16x16x32_bf16 v[8:11], v[88:91], v[206:209], v[8:11]
	v_mfma_f32_16x16x32_bf16 v[60:63], v[84:87], v[184:187], v[60:63]
	v_mfma_f32_16x16x32_bf16 v[56:59], v[92:95], v[184:187], v[56:59]
	v_mfma_f32_16x16x32_bf16 v[44:47], v[84:87], v[194:197], v[44:47]
	v_mfma_f32_16x16x32_bf16 v[40:43], v[92:95], v[194:197], v[40:43]
	v_mfma_f32_16x16x32_bf16 v[28:31], v[84:87], v[202:205], v[28:31]
	v_mfma_f32_16x16x32_bf16 v[24:27], v[92:95], v[202:205], v[24:27]
	v_mfma_f32_16x16x32_bf16 v[12:15], v[84:87], v[210:213], v[12:15]
	v_mfma_f32_16x16x32_bf16 v[8:11], v[92:95], v[210:213], v[8:11]
	v_mfma_f32_16x16x32_bf16 v[52:55], v[164:167], v[180:183], v[52:55]
	v_mfma_f32_16x16x32_bf16 v[48:51], v[172:175], v[180:183], v[48:51]
	v_mfma_f32_16x16x32_bf16 v[36:39], v[164:167], v[188:191], v[36:39]
	v_mfma_f32_16x16x32_bf16 v[32:35], v[172:175], v[188:191], v[32:35]
	v_mfma_f32_16x16x32_bf16 v[20:23], v[164:167], v[198:201], v[20:23]
	v_mfma_f32_16x16x32_bf16 v[16:19], v[172:175], v[198:201], v[16:19]
	v_mfma_f32_16x16x32_bf16 v[4:7], v[164:167], v[206:209], v[4:7]
	v_mfma_f32_16x16x32_bf16 v[0:3], v[172:175], v[206:209], v[0:3]
	v_mfma_f32_16x16x32_bf16 v[52:55], v[168:171], v[184:187], v[52:55]
	v_mfma_f32_16x16x32_bf16 v[48:51], v[176:179], v[184:187], v[48:51]
	v_mfma_f32_16x16x32_bf16 v[36:39], v[168:171], v[194:197], v[36:39]
	v_mfma_f32_16x16x32_bf16 v[32:35], v[176:179], v[194:197], v[32:35]
	v_mfma_f32_16x16x32_bf16 v[20:23], v[168:171], v[202:205], v[20:23]
	v_mfma_f32_16x16x32_bf16 v[16:19], v[176:179], v[202:205], v[16:19]
	v_mfma_f32_16x16x32_bf16 v[4:7], v[168:171], v[210:213], v[4:7]
	v_mfma_f32_16x16x32_bf16 v[0:3], v[176:179], v[210:213], v[0:3]
	s_setprio 0
	s_barrier
; #define PG8_STAGE(bufoff, gbase, voff) do { _Pragma("unroll") for (int _i = 0; _i < 2; ++_i) \
;         asm volatile("s_mov_b32 m0, %0\n\ts_nop 0\n\tglobal_load_lds_dwordx4 %1, %2" :: "s"(ldsb + (unsigned)((bufoff) + _i * 8192)), "v"((voff)[_i]), "s"(gbase) : "m0", "memory"); } while (0)
; #define PG8_LDA(dst, b, h) do { _Pragma("unroll") for (int m = 0; m < 4; ++m) _Pragma("unroll") for (int k = 0; k < 2; ++k) dst[m][k] = *(const PG8_LAS bf16x8*)(lds + PG8_SA(b, h) + aoff + m * 2048 + k * 1024); } while (0)
; #define PG8_LDB(dst, b, h) do { _Pragma("unroll") for (int n = 0; n < 2; ++n) _Pragma("unroll") for (int k = 0; k < 2; ++k) dst[n][k] = *(const PG8_LAS bf16x8*)(lds + PG8_SB(b, h) + boff + n * 2048 + k * 1024); } while (0)
; #define PG8_MMA(ai, bj, At, Bt) do { __builtin_amdgcn_s_setprio(1); _Pragma("unroll") for (int m = 0; m < 4; ++m) _Pragma("unroll") for (int n = 0; n < 2; ++n) _Pragma("unroll") for (int k = 0; k < 2; ++k) \
;         acc[ai][bj][m][n] = __builtin_amdgcn_mfma_f32_16x16x32_bf16(Bt[n][k], At[m][k], acc[ai][bj][m][n], 0, 0, 0); __builtin_amdgcn_s_setprio(0); } while (0)
; #define PG8_WAIT_V(n) asm volatile("s_waitcnt vmcnt(" #n ")" ::: "memory")
; #define PG8_WAIT_L(n) asm volatile("s_waitcnt lgkmcnt(" #n ")" ::: "memory")
; #define PG8_BAR __builtin_amdgcn_s_barrier()
; #define PG8_SCHED __builtin_amdgcn_sched_barrier(0)
; template <class Epi, class Sched, bool ALIGN_EPI = false, bool SP2 = false>
; __device__ __forceinline__ void gemm_phase(PG8_LAS unsigned char* lds, const Gemm g, const Sched& S, const Epi& E, const int wv) {
;     ...
;             PG8_LDB(B0, 1, 0); PG8_LDB(B1, 1, 1); PG8_SCHED; PG8_LDA(At, 1, 0); PG8_STAGE(PG8_SA(0, 1), a2 + hstepA, voffA);
;             PG8_WAIT_V(8); PG8_WAIT_L(0); PG8_BAR; PG8_MMA(0, 0, At, B0); PG8_MMA(0, 1, At, B1); PG8_BAR; PG8_SCHED;
;             PG8_LDA(At, 1, 1); PG8_STAGE(PG8_SB(1, 0), b3, voffB); PG8_STAGE(PG8_SB(1, 1), b3 + hstepB, voffB); PG8_STAGE(PG8_SA(1, 0), a3, voffA);
;             PG8_WAIT_V(8); PG8_WAIT_L(0); PG8_BAR; PG8_MMA(1, 0, At, B0); PG8_MMA(1, 1, At, B1); PG8_BAR; PG8_SCHED;
	v_add_u32_e32 v92, 0x18000, v160
	v_add_u32_e32 v144, 0x1c000, v160
	ds_read_b128 v[80:83], v92
	ds_read_b128 v[84:87], v92 offset:1024
	ds_read_b128 v[88:91], v92 offset:2048
	ds_read_b128 v[92:95], v92 offset:3072
	ds_read_b128 v[164:167], v144
	ds_read_b128 v[168:171], v144 offset:1024
	ds_read_b128 v[172:175], v144 offset:2048
	ds_read_b128 v[176:179], v144 offset:3072
	ds_read_b128 v[180:183], v161 offset:32768
	ds_read_b128 v[184:187], v161 offset:33792
	ds_read_b128 v[188:191], v161 offset:34816
	ds_read_b128 v[194:197], v161 offset:35840
	ds_read_b128 v[198:201], v161 offset:36864
	ds_read_b128 v[202:205], v161 offset:37888
	ds_read_b128 v[206:209], v161 offset:38912
	ds_read_b128 v[210:213], v161 offset:39936
	s_add_u32 s26, s26, 0x84000
	s_addc_u32 s27, s27, 0
	s_mov_b32 m0, s42
	s_nop 0
	global_load_lds_dwordx4 v147, s[26:27]
	s_nop 0
	s_mov_b32 m0, s43
	s_nop 0
	global_load_lds_dwordx4 v151, s[26:27]
	s_waitcnt vmcnt(8) lgkmcnt(0)
	s_setprio 1
	s_barrier
	v_mfma_f32_16x16x32_bf16 v[140:143], v[80:83], v[180:183], v[140:143]
	v_mfma_f32_16x16x32_bf16 v[136:139], v[88:91], v[180:183], v[136:139]
	v_mfma_f32_16x16x32_bf16 v[124:127], v[80:83], v[188:191], v[124:127]
	v_mfma_f32_16x16x32_bf16 v[120:123], v[88:91], v[188:191], v[120:123]
	v_mfma_f32_16x16x32_bf16 v[108:111], v[80:83], v[198:201], v[108:111]
	v_mfma_f32_16x16x32_bf16 v[104:107], v[88:91], v[198:201], v[104:107]
	v_mfma_f32_16x16x32_bf16 v[76:79], v[80:83], v[206:209], v[76:79]
	v_mfma_f32_16x16x32_bf16 v[72:75], v[88:91], v[206:209], v[72:75]
	v_mfma_f32_16x16x32_bf16 v[140:143], v[84:87], v[184:187], v[140:143]
	v_mfma_f32_16x16x32_bf16 v[136:139], v[92:95], v[184:187], v[136:139]
	v_mfma_f32_16x16x32_bf16 v[124:127], v[84:87], v[194:197], v[124:127]
	v_mfma_f32_16x16x32_bf16 v[120:123], v[92:95], v[194:197], v[120:123]
	v_mfma_f32_16x16x32_bf16 v[108:111], v[84:87], v[202:205], v[108:111]
	v_mfma_f32_16x16x32_bf16 v[104:107], v[92:95], v[202:205], v[104:107]
	v_mfma_f32_16x16x32_bf16 v[76:79], v[84:87], v[210:213], v[76:79]
	v_mfma_f32_16x16x32_bf16 v[72:75], v[92:95], v[210:213], v[72:75]
	v_mfma_f32_16x16x32_bf16 v[132:135], v[164:167], v[180:183], v[132:135]
	v_mfma_f32_16x16x32_bf16 v[128:131], v[172:175], v[180:183], v[128:131]
	v_mfma_f32_16x16x32_bf16 v[116:119], v[164:167], v[188:191], v[116:119]
	v_mfma_f32_16x16x32_bf16 v[112:115], v[172:175], v[188:191], v[112:115]
	v_mfma_f32_16x16x32_bf16 v[100:103], v[164:167], v[198:201], v[100:103]
	v_mfma_f32_16x16x32_bf16 v[96:99], v[172:175], v[198:201], v[96:99]
	v_mfma_f32_16x16x32_bf16 v[68:71], v[164:167], v[206:209], v[68:71]
	v_mfma_f32_16x16x32_bf16 v[64:67], v[172:175], v[206:209], v[64:67]
	v_mfma_f32_16x16x32_bf16 v[132:135], v[168:171], v[184:187], v[132:135]
	v_mfma_f32_16x16x32_bf16 v[128:131], v[176:179], v[184:187], v[128:131]
	v_mfma_f32_16x16x32_bf16 v[116:119], v[168:171], v[194:197], v[116:119]
	v_mfma_f32_16x16x32_bf16 v[112:115], v[176:179], v[194:197], v[112:115]
	v_mfma_f32_16x16x32_bf16 v[100:103], v[168:171], v[202:205], v[100:103]
	v_mfma_f32_16x16x32_bf16 v[96:99], v[176:179], v[202:205], v[96:99]
	v_mfma_f32_16x16x32_bf16 v[68:71], v[168:171], v[210:213], v[68:71]
	v_mfma_f32_16x16x32_bf16 v[64:67], v[176:179], v[210:213], v[64:67]
	s_setprio 0
	s_barrier
	ds_read_b128 v[180:183], v161 offset:49152
	ds_read_b128 v[184:187], v161 offset:50176
	ds_read_b128 v[188:191], v161 offset:51200
	ds_read_b128 v[194:197], v161 offset:52224
	ds_read_b128 v[198:201], v161 offset:53248
	ds_read_b128 v[202:205], v161 offset:54272
	ds_read_b128 v[206:209], v161 offset:55296
	ds_read_b128 v[210:213], v161 offset:56320
	s_add_u32 s26, s24, 0x80
	s_addc_u32 s27, s25, 0
	s_mov_b32 m0, s48
	s_nop 0
	global_load_lds_dwordx4 v149, s[26:27]
	s_add_u32 s24, s24, 0x80080
	s_mov_b32 m0, s49
	s_nop 0
	global_load_lds_dwordx4 v153, s[26:27]
	s_addc_u32 s25, s25, 0
	s_mov_b32 m0, s52
	s_nop 0
	global_load_lds_dwordx4 v149, s[24:25]
	s_nop 0
	s_mov_b32 m0, s53
	s_nop 0
	global_load_lds_dwordx4 v153, s[24:25]
	s_nop 0
	s_mov_b32 m0, s50
	s_nop 0
	global_load_lds_dwordx4 v147, s[22:23]
	s_nop 0
	s_mov_b32 m0, s51
	s_nop 0
	global_load_lds_dwordx4 v151, s[22:23]
	s_waitcnt vmcnt(8) lgkmcnt(0)
	s_setprio 1
	s_barrier
	v_mfma_f32_16x16x32_bf16 v[60:63], v[80:83], v[180:183], v[60:63]
	v_mfma_f32_16x16x32_bf16 v[56:59], v[88:91], v[180:183], v[56:59]
	v_mfma_f32_16x16x32_bf16 v[44:47], v[80:83], v[188:191], v[44:47]
	v_mfma_f32_16x16x32_bf16 v[40:43], v[88:91], v[188:191], v[40:43]
	v_mfma_f32_16x16x32_bf16 v[28:31], v[80:83], v[198:201], v[28:31]
	v_mfma_f32_16x16x32_bf16 v[24:27], v[88:91], v[198:201], v[24:27]
	v_mfma_f32_16x16x32_bf16 v[12:15], v[80:83], v[206:209], v[12:15]
	v_mfma_f32_16x16x32_bf16 v[8:11], v[88:91], v[206:209], v[8:11]
	v_mfma_f32_16x16x32_bf16 v[60:63], v[84:87], v[184:187], v[60:63]
	v_mfma_f32_16x16x32_bf16 v[56:59], v[92:95], v[184:187], v[56:59]
	v_mfma_f32_16x16x32_bf16 v[44:47], v[84:87], v[194:197], v[44:47]
	v_mfma_f32_16x16x32_bf16 v[40:43], v[92:95], v[194:197], v[40:43]
	v_mfma_f32_16x16x32_bf16 v[28:31], v[84:87], v[202:205], v[28:31]
	v_mfma_f32_16x16x32_bf16 v[24:27], v[92:95], v[202:205], v[24:27]
	v_mfma_f32_16x16x32_bf16 v[12:15], v[84:87], v[210:213], v[12:15]
	v_mfma_f32_16x16x32_bf16 v[8:11], v[92:95], v[210:213], v[8:11]
	v_mfma_f32_16x16x32_bf16 v[52:55], v[164:167], v[180:183], v[52:55]
	v_mfma_f32_16x16x32_bf16 v[48:51], v[172:175], v[180:183], v[48:51]
	v_mfma_f32_16x16x32_bf16 v[36:39], v[164:167], v[188:191], v[36:39]
	v_mfma_f32_16x16x32_bf16 v[32:35], v[172:175], v[188:191], v[32:35]
	v_mfma_f32_16x16x32_bf16 v[20:23], v[164:167], v[198:201], v[20:23]
	v_mfma_f32_16x16x32_bf16 v[16:19], v[172:175], v[198:201], v[16:19]
	v_mfma_f32_16x16x32_bf16 v[4:7], v[164:167], v[206:209], v[4:7]
	v_mfma_f32_16x16x32_bf16 v[0:3], v[172:175], v[206:209], v[0:3]
	v_mfma_f32_16x16x32_bf16 v[52:55], v[168:171], v[184:187], v[52:55]
	v_mfma_f32_16x16x32_bf16 v[48:51], v[176:179], v[184:187], v[48:51]
	v_mfma_f32_16x16x32_bf16 v[36:39], v[168:171], v[194:197], v[36:39]
	v_mfma_f32_16x16x32_bf16 v[32:35], v[176:179], v[194:197], v[32:35]
	v_mfma_f32_16x16x32_bf16 v[20:23], v[168:171], v[202:205], v[20:23]
	v_mfma_f32_16x16x32_bf16 v[16:19], v[176:179], v[202:205], v[16:19]
	v_mfma_f32_16x16x32_bf16 v[4:7], v[168:171], v[210:213], v[4:7]
	v_mfma_f32_16x16x32_bf16 v[0:3], v[176:179], v[210:213], v[0:3]
	s_setprio 0
	s_barrier
	s_add_u32 s79, s79, 0x100
	s_addc_u32 s85, s85, 0
	s_add_u32 s86, s86, 0x100
	s_addc_u32 s87, s87, 0
	s_cmp_ge_i32 s88, s40
	s_mov_b32 s22, s88
	s_cbranch_scc0 .LBB0_1175
	v_readlane_b32 s92, v254, 49
	v_readlane_b32 s93, v254, 50
	s_mov_b32 s79, 0xc00000
	s_and_b64 vcc, exec, s[14:15]
	s_cbranch_vccz .LBB0_1178

; #define PG8_STAGE(bufoff, gbase, voff) do { _Pragma("unroll") for (int _i = 0; _i < 2; ++_i) \
;         asm volatile("s_mov_b32 m0, %0\n\ts_nop 0\n\tglobal_load_lds_dwordx4 %1, %2" :: "s"(ldsb + (unsigned)((bufoff) + _i * 8192)), "v"((voff)[_i]), "s"(gbase) : "m0", "memory"); } while (0)
; #define PG8_LDA(dst, b, h) do { _Pragma("unroll") for (int m = 0; m < 4; ++m) _Pragma("unroll") for (int k = 0; k < 2; ++k) dst[m][k] = *(const PG8_LAS bf16x8*)(lds + PG8_SA(b, h) + aoff + m * 2048 + k * 1024); } while (0)
; #define PG8_LDB(dst, b, h) do { _Pragma("unroll") for (int n = 0; n < 2; ++n) _Pragma("unroll") for (int k = 0; k < 2; ++k) dst[n][k] = *(const PG8_LAS bf16x8*)(lds + PG8_SB(b, h) + boff + n * 2048 + k * 1024); } while (0)
; #define PG8_MMA(ai, bj, At, Bt) do { __builtin_amdgcn_s_setprio(1); _Pragma("unroll") for (int m = 0; m < 4; ++m) _Pragma("unroll") for (int n = 0; n < 2; ++n) _Pragma("unroll") for (int k = 0; k < 2; ++k) \
;         acc[ai][bj][m][n] = __builtin_amdgcn_mfma_f32_16x16x32_bf16(Bt[n][k], At[m][k], acc[ai][bj][m][n], 0, 0, 0); __builtin_amdgcn_s_setprio(0); } while (0)
; #define PG8_WAIT_V(n) asm volatile("s_waitcnt vmcnt(" #n ")" ::: "memory")
; template <class Epi, class Sched, bool ALIGN_EPI = false, bool SP2 = false>
; __device__ __forceinline__ void gemm_phase(PG8_LAS unsigned char* lds, const Gemm g, const Sched& S, const Epi& E, const int wv) {
;     ...
;         for (int t = 0; t < nt; t += 2) {
;             const bool last = (t == nt - 2);
;             const char* a1 = cA + (size_t)(t + 1) * kstep;
;             const char* a2 = last ? nA : cA + (size_t)(t + 2) * kstep; const char* b2 = last ? nB : cB + (size_t)(t + 2) * kstep;
;             const char* a3 = a2 + kstep; const char* b3 = b2 + kstep;
;             if (last && has_next) S.a_ready(nxt);
;             if constexpr (SP2) {
;             PG8_LDB(B0, 0, 0); PG8_LDB(B1, 0, 1); PG8_SCHED; PG8_LDA(At, 0, 0); PG8_STAGE(PG8_SA(1, 1), a1 + hstepA, voffA);
;             PG8_WAIT_V(8); PG8_WAIT_L(0); PG8_BAR; PG8_MMA(0, 0, At, B0); PG8_MMA(0, 1, At, B1); PG8_BAR; PG8_SCHED;
;             PG8_LDA(At, 0, 1); PG8_STAGE(PG8_SB(0, 0), b2, voffB); PG8_STAGE(PG8_SB(0, 1), b2 + hstepB, voffB); PG8_STAGE(PG8_SA(0, 0), a2, voffA);
;             PG8_WAIT_V(8); PG8_WAIT_L(0); PG8_BAR; PG8_MMA(1, 0, At, B0); PG8_MMA(1, 1, At, B1); PG8_BAR; PG8_SCHED;
.LBB0_1244:
	v_add_u32_e32 v140, 0x10000, v196
	v_add_u32_e32 v156, 0x14000, v196
	ds_read_b128 v[128:131], v140
	ds_read_b128 v[132:135], v140 offset:1024
	ds_read_b128 v[136:139], v140 offset:2048
	ds_read_b128 v[140:143], v140 offset:3072
	ds_read_b128 v[144:147], v156
	ds_read_b128 v[148:151], v156 offset:1024
	ds_read_b128 v[152:155], v156 offset:2048
	ds_read_b128 v[156:159], v156 offset:3072
	s_add_i32 s85, s20, 2
	s_cmp_eq_u32 s62, s20
	s_cselect_b32 s24, s14, s77
	s_cselect_b32 s25, s15, s79
	s_cselect_b32 s22, s72, s83
	s_cselect_b32 s23, s71, s84
	s_add_u32 s20, s24, 0x80
	s_addc_u32 s21, s25, 0
	ds_read_b128 v[160:163], v197
	ds_read_b128 v[164:167], v197 offset:1024
	ds_read_b128 v[168:171], v197 offset:2048
	ds_read_b128 v[172:175], v197 offset:3072
	ds_read_b128 v[176:179], v197 offset:4096
	ds_read_b128 v[198:201], v197 offset:5120
	ds_read_b128 v[202:205], v197 offset:6144
	ds_read_b128 v[206:209], v197 offset:7168
	s_add_u32 s86, s77, 0x15ff80
	s_addc_u32 s87, s79, 0
	s_mov_b32 m0, s50
	s_nop 0
	global_load_lds_dwordx4 v182, s[86:87]
	s_nop 0
	s_mov_b32 m0, s52
	s_nop 0
	global_load_lds_dwordx4 v184, s[86:87]
	s_waitcnt vmcnt(8) lgkmcnt(0)
	s_setprio 1
	s_barrier
	v_mfma_f32_16x16x32_bf16 v[124:127], v[128:131], v[160:163], v[124:127]
	v_mfma_f32_16x16x32_bf16 v[120:123], v[136:139], v[160:163], v[120:123]
	v_mfma_f32_16x16x32_bf16 v[108:111], v[128:131], v[168:171], v[108:111]
	v_mfma_f32_16x16x32_bf16 v[104:107], v[136:139], v[168:171], v[104:107]
	v_mfma_f32_16x16x32_bf16 v[92:95], v[128:131], v[176:179], v[92:95]
	v_mfma_f32_16x16x32_bf16 v[88:91], v[136:139], v[176:179], v[88:91]
	v_mfma_f32_16x16x32_bf16 v[76:79], v[128:131], v[202:205], v[76:79]
	v_mfma_f32_16x16x32_bf16 v[72:75], v[136:139], v[202:205], v[72:75]
	v_mfma_f32_16x16x32_bf16 v[124:127], v[132:135], v[164:167], v[124:127]
	v_mfma_f32_16x16x32_bf16 v[120:123], v[140:143], v[164:167], v[120:123]
	v_mfma_f32_16x16x32_bf16 v[108:111], v[132:135], v[172:175], v[108:111]
	v_mfma_f32_16x16x32_bf16 v[104:107], v[140:143], v[172:175], v[104:107]
	v_mfma_f32_16x16x32_bf16 v[92:95], v[132:135], v[198:201], v[92:95]
	v_mfma_f32_16x16x32_bf16 v[88:91], v[140:143], v[198:201], v[88:91]
	v_mfma_f32_16x16x32_bf16 v[76:79], v[132:135], v[206:209], v[76:79]
	v_mfma_f32_16x16x32_bf16 v[72:75], v[140:143], v[206:209], v[72:75]
	v_mfma_f32_16x16x32_bf16 v[116:119], v[144:147], v[160:163], v[116:119]
	v_mfma_f32_16x16x32_bf16 v[112:115], v[152:155], v[160:163], v[112:115]
	v_mfma_f32_16x16x32_bf16 v[100:103], v[144:147], v[168:171], v[100:103]
	v_mfma_f32_16x16x32_bf16 v[96:99], v[152:155], v[168:171], v[96:99]
	v_mfma_f32_16x16x32_bf16 v[84:87], v[144:147], v[176:179], v[84:87]
	v_mfma_f32_16x16x32_bf16 v[80:83], v[152:155], v[176:179], v[80:83]
	v_mfma_f32_16x16x32_bf16 v[68:71], v[144:147], v[202:205], v[68:71]
	v_mfma_f32_16x16x32_bf16 v[64:67], v[152:155], v[202:205], v[64:67]
	v_mfma_f32_16x16x32_bf16 v[116:119], v[148:151], v[164:167], v[116:119]
	v_mfma_f32_16x16x32_bf16 v[112:115], v[156:159], v[164:167], v[112:115]
	v_mfma_f32_16x16x32_bf16 v[100:103], v[148:151], v[172:175], v[100:103]
	v_mfma_f32_16x16x32_bf16 v[96:99], v[156:159], v[172:175], v[96:99]
	v_mfma_f32_16x16x32_bf16 v[84:87], v[148:151], v[198:201], v[84:87]
	v_mfma_f32_16x16x32_bf16 v[80:83], v[156:159], v[198:201], v[80:83]
	v_mfma_f32_16x16x32_bf16 v[68:71], v[148:151], v[206:209], v[68:71]
	v_mfma_f32_16x16x32_bf16 v[64:67], v[156:159], v[206:209], v[64:67]
	s_setprio 0
	s_barrier
	ds_read_b128 v[160:163], v197 offset:16384
	ds_read_b128 v[164:167], v197 offset:17408
	ds_read_b128 v[168:171], v197 offset:18432
	ds_read_b128 v[172:175], v197 offset:19456
	ds_read_b128 v[176:179], v197 offset:20480
	ds_read_b128 v[198:201], v197 offset:21504
	ds_read_b128 v[202:205], v197 offset:22528
	ds_read_b128 v[206:209], v197 offset:23552
	s_mov_b32 m0, s29
	s_nop 0
	global_load_lds_dwordx4 v183, s[22:23]
	s_add_u32 s86, s22, 0x160000
	s_mov_b32 m0, s30
	s_nop 0
	global_load_lds_dwordx4 v185, s[22:23]
	s_addc_u32 s87, s23, 0
	s_mov_b32 m0, s31
	s_nop 0
	global_load_lds_dwordx4 v183, s[86:87]
	s_nop 0
	s_mov_b32 m0, s33
	s_nop 0
	global_load_lds_dwordx4 v185, s[86:87]
	s_nop 0
	s_mov_b32 m0, s28
	s_nop 0
	global_load_lds_dwordx4 v182, s[24:25]
	s_nop 0
	s_mov_b32 m0, s34
	s_nop 0
	global_load_lds_dwordx4 v184, s[24:25]
	s_waitcnt vmcnt(8) lgkmcnt(0)
	s_setprio 1
	s_barrier
	v_mfma_f32_16x16x32_bf16 v[60:63], v[128:131], v[160:163], v[60:63]
	v_mfma_f32_16x16x32_bf16 v[56:59], v[136:139], v[160:163], v[56:59]
	v_mfma_f32_16x16x32_bf16 v[44:47], v[128:131], v[168:171], v[44:47]
	v_mfma_f32_16x16x32_bf16 v[40:43], v[136:139], v[168:171], v[40:43]
	v_mfma_f32_16x16x32_bf16 v[28:31], v[128:131], v[176:179], v[28:31]
	v_mfma_f32_16x16x32_bf16 v[24:27], v[136:139], v[176:179], v[24:27]
	v_mfma_f32_16x16x32_bf16 v[12:15], v[128:131], v[202:205], v[12:15]
	v_mfma_f32_16x16x32_bf16 v[8:11], v[136:139], v[202:205], v[8:11]
	v_mfma_f32_16x16x32_bf16 v[60:63], v[132:135], v[164:167], v[60:63]
	v_mfma_f32_16x16x32_bf16 v[56:59], v[140:143], v[164:167], v[56:59]
	v_mfma_f32_16x16x32_bf16 v[44:47], v[132:135], v[172:175], v[44:47]
	v_mfma_f32_16x16x32_bf16 v[40:43], v[140:143], v[172:175], v[40:43]
	v_mfma_f32_16x16x32_bf16 v[28:31], v[132:135], v[198:201], v[28:31]
	v_mfma_f32_16x16x32_bf16 v[24:27], v[140:143], v[198:201], v[24:27]
	v_mfma_f32_16x16x32_bf16 v[12:15], v[132:135], v[206:209], v[12:15]
	v_mfma_f32_16x16x32_bf16 v[8:11], v[140:143], v[206:209], v[8:11]
	v_mfma_f32_16x16x32_bf16 v[52:55], v[144:147], v[160:163], v[52:55]
	v_mfma_f32_16x16x32_bf16 v[48:51], v[152:155], v[160:163], v[48:51]
	v_mfma_f32_16x16x32_bf16 v[36:39], v[144:147], v[168:171], v[36:39]
	v_mfma_f32_16x16x32_bf16 v[32:35], v[152:155], v[168:171], v[32:35]
	v_mfma_f32_16x16x32_bf16 v[20:23], v[144:147], v[176:179], v[20:23]
	v_mfma_f32_16x16x32_bf16 v[16:19], v[152:155], v[176:179], v[16:19]
	v_mfma_f32_16x16x32_bf16 v[4:7], v[144:147], v[202:205], v[4:7]
	v_mfma_f32_16x16x32_bf16 v[0:3], v[152:155], v[202:205], v[0:3]
	v_mfma_f32_16x16x32_bf16 v[52:55], v[148:151], v[164:167], v[52:55]
	v_mfma_f32_16x16x32_bf16 v[48:51], v[156:159], v[164:167], v[48:51]
	v_mfma_f32_16x16x32_bf16 v[36:39], v[148:151], v[172:175], v[36:39]
	v_mfma_f32_16x16x32_bf16 v[32:35], v[156:159], v[172:175], v[32:35]
	v_mfma_f32_16x16x32_bf16 v[20:23], v[148:151], v[198:201], v[20:23]
	v_mfma_f32_16x16x32_bf16 v[16:19], v[156:159], v[198:201], v[16:19]
	v_mfma_f32_16x16x32_bf16 v[4:7], v[148:151], v[206:209], v[4:7]
	v_mfma_f32_16x16x32_bf16 v[0:3], v[156:159], v[206:209], v[0:3]
	s_setprio 0
	s_barrier
; #define PG8_STAGE(bufoff, gbase, voff) do { _Pragma("unroll") for (int _i = 0; _i < 2; ++_i) \
;         asm volatile("s_mov_b32 m0, %0\n\ts_nop 0\n\tglobal_load_lds_dwordx4 %1, %2" :: "s"(ldsb + (unsigned)((bufoff) + _i * 8192)), "v"((voff)[_i]), "s"(gbase) : "m0", "memory"); } while (0)
; #define PG8_LDA(dst, b, h) do { _Pragma("unroll") for (int m = 0; m < 4; ++m) _Pragma("unroll") for (int k = 0; k < 2; ++k) dst[m][k] = *(const PG8_LAS bf16x8*)(lds + PG8_SA(b, h) + aoff + m * 2048 + k * 1024); } while (0)
; #define PG8_LDB(dst, b, h) do { _Pragma("unroll") for (int n = 0; n < 2; ++n) _Pragma("unroll") for (int k = 0; k < 2; ++k) dst[n][k] = *(const PG8_LAS bf16x8*)(lds + PG8_SB(b, h) + boff + n * 2048 + k * 1024); } while (0)
; #define PG8_MMA(ai, bj, At, Bt) do { __builtin_amdgcn_s_setprio(1); _Pragma("unroll") for (int m = 0; m < 4; ++m) _Pragma("unroll") for (int n = 0; n < 2; ++n) _Pragma("unroll") for (int k = 0; k < 2; ++k) \
;         acc[ai][bj][m][n] = __builtin_amdgcn_mfma_f32_16x16x32_bf16(Bt[n][k], At[m][k], acc[ai][bj][m][n], 0, 0, 0); __builtin_amdgcn_s_setprio(0); } while (0)
; #define PG8_WAIT_V(n) asm volatile("s_waitcnt vmcnt(" #n ")" ::: "memory")
; #define PG8_WAIT_L(n) asm volatile("s_waitcnt lgkmcnt(" #n ")" ::: "memory")
; #define PG8_BAR __builtin_amdgcn_s_barrier()
; #define PG8_SCHED __builtin_amdgcn_sched_barrier(0)
; template <class Epi, class Sched, bool ALIGN_EPI = false, bool SP2 = false>
; __device__ __forceinline__ void gemm_phase(PG8_LAS unsigned char* lds, const Gemm g, const Sched& S, const Epi& E, const int wv) {
;     ...
;             PG8_LDB(B0, 1, 0); PG8_LDB(B1, 1, 1); PG8_SCHED; PG8_LDA(At, 1, 0); PG8_STAGE(PG8_SA(0, 1), a2 + hstepA, voffA);
;             PG8_WAIT_V(8); PG8_WAIT_L(0); PG8_BAR; PG8_MMA(0, 0, At, B0); PG8_MMA(0, 1, At, B1); PG8_BAR; PG8_SCHED;
;             PG8_LDA(At, 1, 1); PG8_STAGE(PG8_SB(1, 0), b3, voffB); PG8_STAGE(PG8_SB(1, 1), b3 + hstepB, voffB); PG8_STAGE(PG8_SA(1, 0), a3, voffA);
;             PG8_WAIT_V(8); PG8_WAIT_L(0); PG8_BAR; PG8_MMA(1, 0, At, B0); PG8_MMA(1, 1, At, B1); PG8_BAR; PG8_SCHED;
	v_add_u32_e32 v140, 0x18000, v196
	v_add_u32_e32 v156, 0x1c000, v196
	ds_read_b128 v[128:131], v140
	ds_read_b128 v[132:135], v140 offset:1024
	ds_read_b128 v[136:139], v140 offset:2048
	ds_read_b128 v[140:143], v140 offset:3072
	ds_read_b128 v[144:147], v156
	ds_read_b128 v[148:151], v156 offset:1024
	ds_read_b128 v[152:155], v156 offset:2048
	ds_read_b128 v[156:159], v156 offset:3072
	ds_read_b128 v[160:163], v197 offset:32768
	ds_read_b128 v[164:167], v197 offset:33792
	ds_read_b128 v[168:171], v197 offset:34816
	ds_read_b128 v[172:175], v197 offset:35840
	ds_read_b128 v[176:179], v197 offset:36864
	ds_read_b128 v[198:201], v197 offset:37888
	ds_read_b128 v[202:205], v197 offset:38912
	ds_read_b128 v[206:209], v197 offset:39936
	s_add_u32 s24, s24, 0x160000
	s_addc_u32 s25, s25, 0
	s_mov_b32 m0, s35
	s_nop 0
	global_load_lds_dwordx4 v182, s[24:25]
	s_nop 0
	s_mov_b32 m0, s36
	s_nop 0
	global_load_lds_dwordx4 v184, s[24:25]
	s_waitcnt vmcnt(8) lgkmcnt(0)
	s_setprio 1
	s_barrier
	v_mfma_f32_16x16x32_bf16 v[124:127], v[128:131], v[160:163], v[124:127]
	v_mfma_f32_16x16x32_bf16 v[120:123], v[136:139], v[160:163], v[120:123]
	v_mfma_f32_16x16x32_bf16 v[108:111], v[128:131], v[168:171], v[108:111]
	v_mfma_f32_16x16x32_bf16 v[104:107], v[136:139], v[168:171], v[104:107]
	v_mfma_f32_16x16x32_bf16 v[92:95], v[128:131], v[176:179], v[92:95]
	v_mfma_f32_16x16x32_bf16 v[88:91], v[136:139], v[176:179], v[88:91]
	v_mfma_f32_16x16x32_bf16 v[76:79], v[128:131], v[202:205], v[76:79]
	v_mfma_f32_16x16x32_bf16 v[72:75], v[136:139], v[202:205], v[72:75]
	v_mfma_f32_16x16x32_bf16 v[124:127], v[132:135], v[164:167], v[124:127]
	v_mfma_f32_16x16x32_bf16 v[120:123], v[140:143], v[164:167], v[120:123]
	v_mfma_f32_16x16x32_bf16 v[108:111], v[132:135], v[172:175], v[108:111]
	v_mfma_f32_16x16x32_bf16 v[104:107], v[140:143], v[172:175], v[104:107]
	v_mfma_f32_16x16x32_bf16 v[92:95], v[132:135], v[198:201], v[92:95]
	v_mfma_f32_16x16x32_bf16 v[88:91], v[140:143], v[198:201], v[88:91]
	v_mfma_f32_16x16x32_bf16 v[76:79], v[132:135], v[206:209], v[76:79]
	v_mfma_f32_16x16x32_bf16 v[72:75], v[140:143], v[206:209], v[72:75]
	v_mfma_f32_16x16x32_bf16 v[116:119], v[144:147], v[160:163], v[116:119]
	v_mfma_f32_16x16x32_bf16 v[112:115], v[152:155], v[160:163], v[112:115]
	v_mfma_f32_16x16x32_bf16 v[100:103], v[144:147], v[168:171], v[100:103]
	v_mfma_f32_16x16x32_bf16 v[96:99], v[152:155], v[168:171], v[96:99]
	v_mfma_f32_16x16x32_bf16 v[84:87], v[144:147], v[176:179], v[84:87]
	v_mfma_f32_16x16x32_bf16 v[80:83], v[152:155], v[176:179], v[80:83]
	v_mfma_f32_16x16x32_bf16 v[68:71], v[144:147], v[202:205], v[68:71]
	v_mfma_f32_16x16x32_bf16 v[64:67], v[152:155], v[202:205], v[64:67]
	v_mfma_f32_16x16x32_bf16 v[116:119], v[148:151], v[164:167], v[116:119]
	v_mfma_f32_16x16x32_bf16 v[112:115], v[156:159], v[164:167], v[112:115]
	v_mfma_f32_16x16x32_bf16 v[100:103], v[148:151], v[172:175], v[100:103]
	v_mfma_f32_16x16x32_bf16 v[96:99], v[156:159], v[172:175], v[96:99]
	v_mfma_f32_16x16x32_bf16 v[84:87], v[148:151], v[198:201], v[84:87]
	v_mfma_f32_16x16x32_bf16 v[80:83], v[156:159], v[198:201], v[80:83]
	v_mfma_f32_16x16x32_bf16 v[68:71], v[148:151], v[206:209], v[68:71]
	v_mfma_f32_16x16x32_bf16 v[64:67], v[156:159], v[206:209], v[64:67]
	s_setprio 0
	s_barrier
	ds_read_b128 v[160:163], v197 offset:49152
	ds_read_b128 v[164:167], v197 offset:50176
	ds_read_b128 v[168:171], v197 offset:51200
	ds_read_b128 v[172:175], v197 offset:52224
	ds_read_b128 v[176:179], v197 offset:53248
	ds_read_b128 v[198:201], v197 offset:54272
	ds_read_b128 v[202:205], v197 offset:55296
	ds_read_b128 v[206:209], v197 offset:56320
	s_add_u32 s24, s22, 0x80
	s_addc_u32 s25, s23, 0
	s_mov_b32 m0, s44
	s_nop 0
	global_load_lds_dwordx4 v183, s[24:25]
	s_add_u32 s22, s22, 0x160080
	s_mov_b32 m0, s45
	s_nop 0
	global_load_lds_dwordx4 v185, s[24:25]
	s_addc_u32 s23, s23, 0
	s_mov_b32 m0, s48
	s_nop 0
	global_load_lds_dwordx4 v183, s[22:23]
	s_nop 0
	s_mov_b32 m0, s49
	s_nop 0
	global_load_lds_dwordx4 v185, s[22:23]
	s_nop 0
	s_mov_b32 m0, s46
	s_nop 0
	global_load_lds_dwordx4 v182, s[20:21]
	s_nop 0
	s_mov_b32 m0, s47
	s_nop 0
	global_load_lds_dwordx4 v184, s[20:21]
	s_waitcnt vmcnt(8) lgkmcnt(0)
	s_setprio 1
	s_barrier
	v_mfma_f32_16x16x32_bf16 v[60:63], v[128:131], v[160:163], v[60:63]
	v_mfma_f32_16x16x32_bf16 v[56:59], v[136:139], v[160:163], v[56:59]
	v_mfma_f32_16x16x32_bf16 v[44:47], v[128:131], v[168:171], v[44:47]
	v_mfma_f32_16x16x32_bf16 v[40:43], v[136:139], v[168:171], v[40:43]
	v_mfma_f32_16x16x32_bf16 v[28:31], v[128:131], v[176:179], v[28:31]
	v_mfma_f32_16x16x32_bf16 v[24:27], v[136:139], v[176:179], v[24:27]
	v_mfma_f32_16x16x32_bf16 v[12:15], v[128:131], v[202:205], v[12:15]
	v_mfma_f32_16x16x32_bf16 v[8:11], v[136:139], v[202:205], v[8:11]
	v_mfma_f32_16x16x32_bf16 v[60:63], v[132:135], v[164:167], v[60:63]
	v_mfma_f32_16x16x32_bf16 v[56:59], v[140:143], v[164:167], v[56:59]
	v_mfma_f32_16x16x32_bf16 v[44:47], v[132:135], v[172:175], v[44:47]
	v_mfma_f32_16x16x32_bf16 v[40:43], v[140:143], v[172:175], v[40:43]
	v_mfma_f32_16x16x32_bf16 v[28:31], v[132:135], v[198:201], v[28:31]
	v_mfma_f32_16x16x32_bf16 v[24:27], v[140:143], v[198:201], v[24:27]
	v_mfma_f32_16x16x32_bf16 v[12:15], v[132:135], v[206:209], v[12:15]
	v_mfma_f32_16x16x32_bf16 v[8:11], v[140:143], v[206:209], v[8:11]
	v_mfma_f32_16x16x32_bf16 v[52:55], v[144:147], v[160:163], v[52:55]
	v_mfma_f32_16x16x32_bf16 v[48:51], v[152:155], v[160:163], v[48:51]
	v_mfma_f32_16x16x32_bf16 v[36:39], v[144:147], v[168:171], v[36:39]
	v_mfma_f32_16x16x32_bf16 v[32:35], v[152:155], v[168:171], v[32:35]
	v_mfma_f32_16x16x32_bf16 v[20:23], v[144:147], v[176:179], v[20:23]
	v_mfma_f32_16x16x32_bf16 v[16:19], v[152:155], v[176:179], v[16:19]
	v_mfma_f32_16x16x32_bf16 v[4:7], v[144:147], v[202:205], v[4:7]
	v_mfma_f32_16x16x32_bf16 v[0:3], v[152:155], v[202:205], v[0:3]
	v_mfma_f32_16x16x32_bf16 v[52:55], v[148:151], v[164:167], v[52:55]
	v_mfma_f32_16x16x32_bf16 v[48:51], v[156:159], v[164:167], v[48:51]
	v_mfma_f32_16x16x32_bf16 v[36:39], v[148:151], v[172:175], v[36:39]
	v_mfma_f32_16x16x32_bf16 v[32:35], v[156:159], v[172:175], v[32:35]
	v_mfma_f32_16x16x32_bf16 v[20:23], v[148:151], v[198:201], v[20:23]
	v_mfma_f32_16x16x32_bf16 v[16:19], v[156:159], v[198:201], v[16:19]
	v_mfma_f32_16x16x32_bf16 v[4:7], v[148:151], v[206:209], v[4:7]
	v_mfma_f32_16x16x32_bf16 v[0:3], v[156:159], v[206:209], v[0:3]
	s_setprio 0
	s_barrier
	s_add_u32 s77, s77, 0x100
	s_addc_u32 s79, s79, 0
	s_add_u32 s83, s83, 0x100
	s_addc_u32 s84, s84, 0
	s_cmp_ge_i32 s85, s65
	s_mov_b32 s20, s85
	s_cbranch_scc0 .LBB0_1244
	s_mov_b32 s79, 0xc00000
	s_and_b64 vcc, exec, s[12:13]
	s_cbranch_vccz .LBB0_1247

; #define PG8_STAGE(bufoff, gbase, voff) do { _Pragma("unroll") for (int _i = 0; _i < 2; ++_i) \
;         asm volatile("s_mov_b32 m0, %0\n\ts_nop 0\n\tglobal_load_lds_dwordx4 %1, %2" :: "s"(ldsb + (unsigned)((bufoff) + _i * 8192)), "v"((voff)[_i]), "s"(gbase) : "m0", "memory"); } while (0)
; #define PG8_LDA(dst, b, h) do { _Pragma("unroll") for (int m = 0; m < 4; ++m) _Pragma("unroll") for (int k = 0; k < 2; ++k) dst[m][k] = *(const PG8_LAS bf16x8*)(lds + PG8_SA(b, h) + aoff + m * 2048 + k * 1024); } while (0)
; #define PG8_LDB(dst, b, h) do { _Pragma("unroll") for (int n = 0; n < 2; ++n) _Pragma("unroll") for (int k = 0; k < 2; ++k) dst[n][k] = *(const PG8_LAS bf16x8*)(lds + PG8_SB(b, h) + boff + n * 2048 + k * 1024); } while (0)
; #define PG8_MMA(ai, bj, At, Bt) do { __builtin_amdgcn_s_setprio(1); _Pragma("unroll") for (int m = 0; m < 4; ++m) _Pragma("unroll") for (int n = 0; n < 2; ++n) _Pragma("unroll") for (int k = 0; k < 2; ++k) \
;         acc[ai][bj][m][n] = __builtin_amdgcn_mfma_f32_16x16x32_bf16(Bt[n][k], At[m][k], acc[ai][bj][m][n], 0, 0, 0); __builtin_amdgcn_s_setprio(0); } while (0)
; #define PG8_WAIT_V(n) asm volatile("s_waitcnt vmcnt(" #n ")" ::: "memory")
; #define PG8_WAIT_L(n) asm volatile("s_waitcnt lgkmcnt(" #n ")" ::: "memory")
; #define PG8_BAR __builtin_amdgcn_s_barrier()
; #define PG8_SCHED __builtin_amdgcn_sched_barrier(0)
; template <class Epi, class Sched, bool ALIGN_EPI = false, bool SP2 = false>
; __device__ __forceinline__ void gemm_phase(PG8_LAS unsigned char* lds, const Gemm g, const Sched& S, const Epi& E, const int wv) {
;     ...
;             PG8_LDB(B0, 0, 0); PG8_LDB(B1, 0, 1); PG8_SCHED; PG8_LDA(At, 0, 0); PG8_STAGE(PG8_SA(1, 1), a1 + hstepA, voffA);
;             PG8_WAIT_V(8); PG8_WAIT_L(0); PG8_BAR; PG8_MMA(0, 0, At, B0); PG8_MMA(0, 1, At, B1); PG8_BAR; PG8_SCHED;
;             PG8_LDA(At, 0, 1); PG8_STAGE(PG8_SB(0, 0), b2, voffB); PG8_STAGE(PG8_SB(0, 1), b2 + hstepB, voffB); PG8_STAGE(PG8_SA(0, 0), a2, voffA);
;             PG8_WAIT_V(8); PG8_WAIT_L(0); PG8_BAR; PG8_MMA(1, 0, At, B0); PG8_MMA(1, 1, At, B1); PG8_BAR; PG8_SCHED;
.LBB0_1336:
	v_add_u32_e32 v140, 0x10000, v220
	v_add_u32_e32 v159, 0x14000, v220
	ds_read_b128 v[128:131], v140
	ds_read_b128 v[132:135], v140 offset:1024
	ds_read_b128 v[136:139], v140 offset:2048
	ds_read_b128 v[140:143], v140 offset:3072
	ds_read_b128 v[144:147], v159
	ds_read_b128 v[148:151], v159 offset:1024
	ds_read_b128 v[152:155], v159 offset:2048
	ds_read_b128 v[160:163], v159 offset:3072
	s_add_i32 vcc_hi, s34, 2
	s_cmp_eq_u32 s25, s34
	s_cselect_b32 s42, s26, s85
	s_cselect_b32 s43, s27, vcc_lo
	s_cselect_b32 s36, s28, s79
	s_cselect_b32 s37, s29, s62
	s_add_u32 s34, s42, 0x80
	s_addc_u32 s35, s43, 0
	ds_read_b128 v[164:167], v221
	ds_read_b128 v[168:171], v221 offset:1024
	ds_read_b128 v[172:175], v221 offset:2048
	ds_read_b128 v[176:179], v221 offset:3072
	ds_read_b128 v[180:183], v221 offset:4096
	ds_read_b128 v[184:187], v221 offset:5120
	ds_read_b128 v[188:191], v221 offset:6144
	ds_read_b128 v[194:197], v221 offset:7168
	s_mov_b32 m0, s71
	s_nop 0
	global_load_lds_dwordx4 v208, s[30:31]
	s_nop 0
	s_mov_b32 m0, s88
	s_nop 0
	global_load_lds_dwordx4 v210, s[30:31]
	s_waitcnt vmcnt(8) lgkmcnt(0)
	s_setprio 1
	s_barrier
	v_mfma_f32_16x16x32_bf16 v[124:127], v[128:131], v[164:167], v[124:127]
	v_mfma_f32_16x16x32_bf16 v[120:123], v[136:139], v[164:167], v[120:123]
	v_mfma_f32_16x16x32_bf16 v[108:111], v[128:131], v[172:175], v[108:111]
	v_mfma_f32_16x16x32_bf16 v[104:107], v[136:139], v[172:175], v[104:107]
	v_mfma_f32_16x16x32_bf16 v[92:95], v[128:131], v[180:183], v[92:95]
	v_mfma_f32_16x16x32_bf16 v[88:91], v[136:139], v[180:183], v[88:91]
	v_mfma_f32_16x16x32_bf16 v[76:79], v[128:131], v[188:191], v[76:79]
	v_mfma_f32_16x16x32_bf16 v[72:75], v[136:139], v[188:191], v[72:75]
	v_mfma_f32_16x16x32_bf16 v[124:127], v[132:135], v[168:171], v[124:127]
	v_mfma_f32_16x16x32_bf16 v[120:123], v[140:143], v[168:171], v[120:123]
	v_mfma_f32_16x16x32_bf16 v[108:111], v[132:135], v[176:179], v[108:111]
	v_mfma_f32_16x16x32_bf16 v[104:107], v[140:143], v[176:179], v[104:107]
	v_mfma_f32_16x16x32_bf16 v[92:95], v[132:135], v[184:187], v[92:95]
	v_mfma_f32_16x16x32_bf16 v[88:91], v[140:143], v[184:187], v[88:91]
	v_mfma_f32_16x16x32_bf16 v[76:79], v[132:135], v[194:197], v[76:79]
	v_mfma_f32_16x16x32_bf16 v[72:75], v[140:143], v[194:197], v[72:75]
	v_mfma_f32_16x16x32_bf16 v[116:119], v[144:147], v[164:167], v[116:119]
	v_mfma_f32_16x16x32_bf16 v[112:115], v[152:155], v[164:167], v[112:115]
	v_mfma_f32_16x16x32_bf16 v[100:103], v[144:147], v[172:175], v[100:103]
	v_mfma_f32_16x16x32_bf16 v[96:99], v[152:155], v[172:175], v[96:99]
	v_mfma_f32_16x16x32_bf16 v[84:87], v[144:147], v[180:183], v[84:87]
	v_mfma_f32_16x16x32_bf16 v[80:83], v[152:155], v[180:183], v[80:83]
	v_mfma_f32_16x16x32_bf16 v[68:71], v[144:147], v[188:191], v[68:71]
	v_mfma_f32_16x16x32_bf16 v[64:67], v[152:155], v[188:191], v[64:67]
	v_mfma_f32_16x16x32_bf16 v[116:119], v[148:151], v[168:171], v[116:119]
	v_mfma_f32_16x16x32_bf16 v[112:115], v[160:163], v[168:171], v[112:115]
	v_mfma_f32_16x16x32_bf16 v[100:103], v[148:151], v[176:179], v[100:103]
	v_mfma_f32_16x16x32_bf16 v[96:99], v[160:163], v[176:179], v[96:99]
	v_mfma_f32_16x16x32_bf16 v[84:87], v[148:151], v[184:187], v[84:87]
	v_mfma_f32_16x16x32_bf16 v[80:83], v[160:163], v[184:187], v[80:83]
	v_mfma_f32_16x16x32_bf16 v[68:71], v[148:151], v[194:197], v[68:71]
	v_mfma_f32_16x16x32_bf16 v[64:67], v[160:163], v[194:197], v[64:67]
	s_setprio 0
	s_barrier
	ds_read_b128 v[164:167], v221 offset:16384
	ds_read_b128 v[168:171], v221 offset:17408
	ds_read_b128 v[172:175], v221 offset:18432
	ds_read_b128 v[176:179], v221 offset:19456
	ds_read_b128 v[180:183], v221 offset:20480
	ds_read_b128 v[184:187], v221 offset:21504
	ds_read_b128 v[188:191], v221 offset:22528
	ds_read_b128 v[194:197], v221 offset:23552
	s_mov_b32 m0, s47
	s_nop 0
	global_load_lds_dwordx4 v209, s[36:37]
	s_add_u32 s10, s36, 0x160000
	s_mov_b32 m0, s48
	s_nop 0
	global_load_lds_dwordx4 v211, s[36:37]
	s_addc_u32 s11, s37, 0
	s_mov_b32 m0, s49
	s_nop 0
	global_load_lds_dwordx4 v209, s[10:11]
	s_nop 0
	s_mov_b32 m0, s50
	s_nop 0
	global_load_lds_dwordx4 v211, s[10:11]
	s_nop 0
	s_mov_b32 m0, s46
	s_nop 0
	global_load_lds_dwordx4 v208, s[42:43]
	s_nop 0
	s_mov_b32 m0, s51
	s_nop 0
	global_load_lds_dwordx4 v210, s[42:43]
	s_waitcnt vmcnt(8) lgkmcnt(0)
	s_setprio 1
	s_barrier
	v_mfma_f32_16x16x32_bf16 v[60:63], v[128:131], v[164:167], v[60:63]
	v_mfma_f32_16x16x32_bf16 v[56:59], v[136:139], v[164:167], v[56:59]
	v_mfma_f32_16x16x32_bf16 v[44:47], v[128:131], v[172:175], v[44:47]
	v_mfma_f32_16x16x32_bf16 v[40:43], v[136:139], v[172:175], v[40:43]
	v_mfma_f32_16x16x32_bf16 v[28:31], v[128:131], v[180:183], v[28:31]
	v_mfma_f32_16x16x32_bf16 v[24:27], v[136:139], v[180:183], v[24:27]
	v_mfma_f32_16x16x32_bf16 v[12:15], v[128:131], v[188:191], v[12:15]
	v_mfma_f32_16x16x32_bf16 v[8:11], v[136:139], v[188:191], v[8:11]
	v_mfma_f32_16x16x32_bf16 v[60:63], v[132:135], v[168:171], v[60:63]
	v_mfma_f32_16x16x32_bf16 v[56:59], v[140:143], v[168:171], v[56:59]
	v_mfma_f32_16x16x32_bf16 v[44:47], v[132:135], v[176:179], v[44:47]
	v_mfma_f32_16x16x32_bf16 v[40:43], v[140:143], v[176:179], v[40:43]
	v_mfma_f32_16x16x32_bf16 v[28:31], v[132:135], v[184:187], v[28:31]
	v_mfma_f32_16x16x32_bf16 v[24:27], v[140:143], v[184:187], v[24:27]
	v_mfma_f32_16x16x32_bf16 v[12:15], v[132:135], v[194:197], v[12:15]
	v_mfma_f32_16x16x32_bf16 v[8:11], v[140:143], v[194:197], v[8:11]
	v_mfma_f32_16x16x32_bf16 v[52:55], v[144:147], v[164:167], v[52:55]
	v_mfma_f32_16x16x32_bf16 v[48:51], v[152:155], v[164:167], v[48:51]
	v_mfma_f32_16x16x32_bf16 v[36:39], v[144:147], v[172:175], v[36:39]
	v_mfma_f32_16x16x32_bf16 v[32:35], v[152:155], v[172:175], v[32:35]
	v_mfma_f32_16x16x32_bf16 v[20:23], v[144:147], v[180:183], v[20:23]
	v_mfma_f32_16x16x32_bf16 v[16:19], v[152:155], v[180:183], v[16:19]
	v_mfma_f32_16x16x32_bf16 v[4:7], v[144:147], v[188:191], v[4:7]
	v_mfma_f32_16x16x32_bf16 v[0:3], v[152:155], v[188:191], v[0:3]
	v_mfma_f32_16x16x32_bf16 v[52:55], v[148:151], v[168:171], v[52:55]
	v_mfma_f32_16x16x32_bf16 v[48:51], v[160:163], v[168:171], v[48:51]
	v_mfma_f32_16x16x32_bf16 v[36:39], v[148:151], v[176:179], v[36:39]
	v_mfma_f32_16x16x32_bf16 v[32:35], v[160:163], v[176:179], v[32:35]
	v_mfma_f32_16x16x32_bf16 v[20:23], v[148:151], v[184:187], v[20:23]
	v_mfma_f32_16x16x32_bf16 v[16:19], v[160:163], v[184:187], v[16:19]
	v_mfma_f32_16x16x32_bf16 v[4:7], v[148:151], v[194:197], v[4:7]
	v_mfma_f32_16x16x32_bf16 v[0:3], v[160:163], v[194:197], v[0:3]
	s_setprio 0
	s_barrier
; #define PG8_STAGE(bufoff, gbase, voff) do { _Pragma("unroll") for (int _i = 0; _i < 2; ++_i) \
;         asm volatile("s_mov_b32 m0, %0\n\ts_nop 0\n\tglobal_load_lds_dwordx4 %1, %2" :: "s"(ldsb + (unsigned)((bufoff) + _i * 8192)), "v"((voff)[_i]), "s"(gbase) : "m0", "memory"); } while (0)
; #define PG8_LDA(dst, b, h) do { _Pragma("unroll") for (int m = 0; m < 4; ++m) _Pragma("unroll") for (int k = 0; k < 2; ++k) dst[m][k] = *(const PG8_LAS bf16x8*)(lds + PG8_SA(b, h) + aoff + m * 2048 + k * 1024); } while (0)
; #define PG8_LDB(dst, b, h) do { _Pragma("unroll") for (int n = 0; n < 2; ++n) _Pragma("unroll") for (int k = 0; k < 2; ++k) dst[n][k] = *(const PG8_LAS bf16x8*)(lds + PG8_SB(b, h) + boff + n * 2048 + k * 1024); } while (0)
; #define PG8_MMA(ai, bj, At, Bt) do { __builtin_amdgcn_s_setprio(1); _Pragma("unroll") for (int m = 0; m < 4; ++m) _Pragma("unroll") for (int n = 0; n < 2; ++n) _Pragma("unroll") for (int k = 0; k < 2; ++k) \
;         acc[ai][bj][m][n] = __builtin_amdgcn_mfma_f32_16x16x32_bf16(Bt[n][k], At[m][k], acc[ai][bj][m][n], 0, 0, 0); __builtin_amdgcn_s_setprio(0); } while (0)
; #define PG8_WAIT_V(n) asm volatile("s_waitcnt vmcnt(" #n ")" ::: "memory")
; #define PG8_WAIT_L(n) asm volatile("s_waitcnt lgkmcnt(" #n ")" ::: "memory")
; #define PG8_BAR __builtin_amdgcn_s_barrier()
; template <class Epi, class Sched, bool ALIGN_EPI = false, bool SP2 = false>
; __device__ __forceinline__ void gemm_phase(PG8_LAS unsigned char* lds, const Gemm g, const Sched& S, const Epi& E, const int wv) {
;     ...
;         for (int t = 0; t < nt; t += 2) {
;             const bool last = (t == nt - 2);
;             const char* a1 = cA + (size_t)(t + 1) * kstep;
;             const char* a2 = last ? nA : cA + (size_t)(t + 2) * kstep; const char* b2 = last ? nB : cB + (size_t)(t + 2) * kstep;
;             const char* a3 = a2 + kstep; const char* b3 = b2 + kstep;
;     ...
;             PG8_LDB(B0, 1, 0); PG8_LDB(B1, 1, 1); PG8_SCHED; PG8_LDA(At, 1, 0); PG8_STAGE(PG8_SA(0, 1), a2 + hstepA, voffA);
;             PG8_WAIT_V(8); PG8_WAIT_L(0); PG8_BAR; PG8_MMA(0, 0, At, B0); PG8_MMA(0, 1, At, B1); PG8_BAR; PG8_SCHED;
;             PG8_LDA(At, 1, 1); PG8_STAGE(PG8_SB(1, 0), b3, voffB); PG8_STAGE(PG8_SB(1, 1), b3 + hstepB, voffB); PG8_STAGE(PG8_SA(1, 0), a3, voffA);
;             PG8_WAIT_V(8); PG8_WAIT_L(0); PG8_BAR; PG8_MMA(1, 0, At, B0); PG8_MMA(1, 1, At, B1); PG8_BAR; PG8_SCHED;
	v_add_u32_e32 v140, 0x18000, v220
	v_add_u32_e32 v159, 0x1c000, v220
	ds_read_b128 v[128:131], v140
	ds_read_b128 v[132:135], v140 offset:1024
	ds_read_b128 v[136:139], v140 offset:2048
	ds_read_b128 v[140:143], v140 offset:3072
	ds_read_b128 v[144:147], v159
	ds_read_b128 v[148:151], v159 offset:1024
	ds_read_b128 v[152:155], v159 offset:2048
	ds_read_b128 v[160:163], v159 offset:3072
	ds_read_b128 v[164:167], v221 offset:32768
	ds_read_b128 v[168:171], v221 offset:33792
	ds_read_b128 v[172:175], v221 offset:34816
	ds_read_b128 v[176:179], v221 offset:35840
	ds_read_b128 v[180:183], v221 offset:36864
	ds_read_b128 v[184:187], v221 offset:37888
	ds_read_b128 v[188:191], v221 offset:38912
	ds_read_b128 v[194:197], v221 offset:39936
	s_add_u32 s10, s42, 0x160000
	s_addc_u32 s11, s43, 0
	s_mov_b32 m0, s52
	s_nop 0
	global_load_lds_dwordx4 v208, s[10:11]
	s_nop 0
	s_mov_b32 m0, s53
	s_nop 0
	global_load_lds_dwordx4 v210, s[10:11]
	s_waitcnt vmcnt(8) lgkmcnt(0)
	s_setprio 1
	s_barrier
	v_mfma_f32_16x16x32_bf16 v[124:127], v[128:131], v[164:167], v[124:127]
	v_mfma_f32_16x16x32_bf16 v[120:123], v[136:139], v[164:167], v[120:123]
	v_mfma_f32_16x16x32_bf16 v[108:111], v[128:131], v[172:175], v[108:111]
	v_mfma_f32_16x16x32_bf16 v[104:107], v[136:139], v[172:175], v[104:107]
	v_mfma_f32_16x16x32_bf16 v[92:95], v[128:131], v[180:183], v[92:95]
	v_mfma_f32_16x16x32_bf16 v[88:91], v[136:139], v[180:183], v[88:91]
	v_mfma_f32_16x16x32_bf16 v[76:79], v[128:131], v[188:191], v[76:79]
	v_mfma_f32_16x16x32_bf16 v[72:75], v[136:139], v[188:191], v[72:75]
	v_mfma_f32_16x16x32_bf16 v[124:127], v[132:135], v[168:171], v[124:127]
	v_mfma_f32_16x16x32_bf16 v[120:123], v[140:143], v[168:171], v[120:123]
	v_mfma_f32_16x16x32_bf16 v[108:111], v[132:135], v[176:179], v[108:111]
	v_mfma_f32_16x16x32_bf16 v[104:107], v[140:143], v[176:179], v[104:107]
	v_mfma_f32_16x16x32_bf16 v[92:95], v[132:135], v[184:187], v[92:95]
	v_mfma_f32_16x16x32_bf16 v[88:91], v[140:143], v[184:187], v[88:91]
	v_mfma_f32_16x16x32_bf16 v[76:79], v[132:135], v[194:197], v[76:79]
	v_mfma_f32_16x16x32_bf16 v[72:75], v[140:143], v[194:197], v[72:75]
	v_mfma_f32_16x16x32_bf16 v[116:119], v[144:147], v[164:167], v[116:119]
	v_mfma_f32_16x16x32_bf16 v[112:115], v[152:155], v[164:167], v[112:115]
	v_mfma_f32_16x16x32_bf16 v[100:103], v[144:147], v[172:175], v[100:103]
	v_mfma_f32_16x16x32_bf16 v[96:99], v[152:155], v[172:175], v[96:99]
	v_mfma_f32_16x16x32_bf16 v[84:87], v[144:147], v[180:183], v[84:87]
	v_mfma_f32_16x16x32_bf16 v[80:83], v[152:155], v[180:183], v[80:83]
	v_mfma_f32_16x16x32_bf16 v[68:71], v[144:147], v[188:191], v[68:71]
	v_mfma_f32_16x16x32_bf16 v[64:67], v[152:155], v[188:191], v[64:67]
	v_mfma_f32_16x16x32_bf16 v[116:119], v[148:151], v[168:171], v[116:119]
	v_mfma_f32_16x16x32_bf16 v[112:115], v[160:163], v[168:171], v[112:115]
	v_mfma_f32_16x16x32_bf16 v[100:103], v[148:151], v[176:179], v[100:103]
	v_mfma_f32_16x16x32_bf16 v[96:99], v[160:163], v[176:179], v[96:99]
	v_mfma_f32_16x16x32_bf16 v[84:87], v[148:151], v[184:187], v[84:87]
	v_mfma_f32_16x16x32_bf16 v[80:83], v[160:163], v[184:187], v[80:83]
	v_mfma_f32_16x16x32_bf16 v[68:71], v[148:151], v[194:197], v[68:71]
	v_mfma_f32_16x16x32_bf16 v[64:67], v[160:163], v[194:197], v[64:67]
	s_setprio 0
	s_barrier
	ds_read_b128 v[164:167], v221 offset:49152
	ds_read_b128 v[168:171], v221 offset:50176
	ds_read_b128 v[172:175], v221 offset:51200
	ds_read_b128 v[176:179], v221 offset:52224
	ds_read_b128 v[180:183], v221 offset:53248
	ds_read_b128 v[184:187], v221 offset:54272
	ds_read_b128 v[188:191], v221 offset:55296
	ds_read_b128 v[194:197], v221 offset:56320
	s_add_u32 s10, s36, 0x80
	s_addc_u32 s11, s37, 0
	s_mov_b32 m0, s87
	s_nop 0
	global_load_lds_dwordx4 v209, s[10:11]
	s_nop 0
	s_mov_b32 m0, s83
	s_nop 0
	global_load_lds_dwordx4 v211, s[10:11]
	s_add_u32 s10, s36, 0x160080
	s_addc_u32 s11, s37, 0
	s_mov_b32 m0, s92
	s_nop 0
	global_load_lds_dwordx4 v209, s[10:11]
	s_nop 0
	s_mov_b32 m0, s93
	s_nop 0
	global_load_lds_dwordx4 v211, s[10:11]
	s_nop 0
	s_mov_b32 m0, s60
	s_nop 0
	global_load_lds_dwordx4 v208, s[34:35]
	s_nop 0
	s_mov_b32 m0, s89
	s_nop 0
	global_load_lds_dwordx4 v210, s[34:35]
	s_waitcnt vmcnt(8) lgkmcnt(0)
	s_setprio 1
	s_barrier
	v_mfma_f32_16x16x32_bf16 v[60:63], v[128:131], v[164:167], v[60:63]
	v_mfma_f32_16x16x32_bf16 v[56:59], v[136:139], v[164:167], v[56:59]
	v_mfma_f32_16x16x32_bf16 v[44:47], v[128:131], v[172:175], v[44:47]
	v_mfma_f32_16x16x32_bf16 v[40:43], v[136:139], v[172:175], v[40:43]
	v_mfma_f32_16x16x32_bf16 v[28:31], v[128:131], v[180:183], v[28:31]
	v_mfma_f32_16x16x32_bf16 v[24:27], v[136:139], v[180:183], v[24:27]
	v_mfma_f32_16x16x32_bf16 v[12:15], v[128:131], v[188:191], v[12:15]
	v_mfma_f32_16x16x32_bf16 v[8:11], v[136:139], v[188:191], v[8:11]
	v_mfma_f32_16x16x32_bf16 v[60:63], v[132:135], v[168:171], v[60:63]
	v_mfma_f32_16x16x32_bf16 v[56:59], v[140:143], v[168:171], v[56:59]
	v_mfma_f32_16x16x32_bf16 v[44:47], v[132:135], v[176:179], v[44:47]
	v_mfma_f32_16x16x32_bf16 v[40:43], v[140:143], v[176:179], v[40:43]
	v_mfma_f32_16x16x32_bf16 v[28:31], v[132:135], v[184:187], v[28:31]
	v_mfma_f32_16x16x32_bf16 v[24:27], v[140:143], v[184:187], v[24:27]
	v_mfma_f32_16x16x32_bf16 v[12:15], v[132:135], v[194:197], v[12:15]
	v_mfma_f32_16x16x32_bf16 v[8:11], v[140:143], v[194:197], v[8:11]
	v_mfma_f32_16x16x32_bf16 v[52:55], v[144:147], v[164:167], v[52:55]
	v_mfma_f32_16x16x32_bf16 v[48:51], v[152:155], v[164:167], v[48:51]
	v_mfma_f32_16x16x32_bf16 v[36:39], v[144:147], v[172:175], v[36:39]
	v_mfma_f32_16x16x32_bf16 v[32:35], v[152:155], v[172:175], v[32:35]
	v_mfma_f32_16x16x32_bf16 v[20:23], v[144:147], v[180:183], v[20:23]
	v_mfma_f32_16x16x32_bf16 v[16:19], v[152:155], v[180:183], v[16:19]
	v_mfma_f32_16x16x32_bf16 v[4:7], v[144:147], v[188:191], v[4:7]
	v_mfma_f32_16x16x32_bf16 v[0:3], v[152:155], v[188:191], v[0:3]
	v_mfma_f32_16x16x32_bf16 v[52:55], v[148:151], v[168:171], v[52:55]
	v_mfma_f32_16x16x32_bf16 v[48:51], v[160:163], v[168:171], v[48:51]
	v_mfma_f32_16x16x32_bf16 v[36:39], v[148:151], v[176:179], v[36:39]
	v_mfma_f32_16x16x32_bf16 v[32:35], v[160:163], v[176:179], v[32:35]
	v_mfma_f32_16x16x32_bf16 v[20:23], v[148:151], v[184:187], v[20:23]
	v_mfma_f32_16x16x32_bf16 v[16:19], v[160:163], v[184:187], v[16:19]
	v_mfma_f32_16x16x32_bf16 v[4:7], v[148:151], v[194:197], v[4:7]
	v_mfma_f32_16x16x32_bf16 v[0:3], v[160:163], v[194:197], v[0:3]
	s_setprio 0
	s_barrier
	s_add_u32 s85, s85, 0x100
	s_addc_u32 vcc_lo, vcc_lo, 0
	s_add_u32 s79, s79, 0x100
	s_addc_u32 s62, s62, 0
	s_add_u32 s30, s30, 0x100
	s_addc_u32 s31, s31, 0
	s_cmp_ge_i32 vcc_hi, s40
	s_mov_b32 s34, vcc_hi
	s_cbranch_scc0 .LBB0_1336
	s_mov_b32 s79, 0xc00000
	s_and_b64 vcc, exec, s[20:21]
	s_cbranch_vccz .LBB0_1339

; __device__ __forceinline__ float wave_sum(float v, int lane) {
; #pragma unroll
;     for (int o = 1; o < 64; o <<= 1) v += __uint_as_float(__builtin_amdgcn_ds_bpermute((lane ^ o) << 2, __float_as_uint(v)));
;     return v;
; __device__ __forceinline__ void final_phase(const hf_t* H, const float* SSQ, float* out, const float* g, const int wv) {
;     ...
;         const float rinv = rsqrtf(wave_sum(cs, lane) * (1.f / D) + EPS);
;         f32x4* op = (f32x4*)(out + (size_t)row * D) + lane;
; #pragma unroll
;         for (int j = 0; j < 8; ++j) op[64 * j] = __builtin_convertvector(cur[j], f32x4) * rinv * gp[64 * j];
; #pragma unroll
;         for (int j = 0; j < 8; ++j) cur[j] = nxt[j];
;         cs = ns;
.LBB0_1469:
	s_or_b64 exec, exec, s[10:11]
	global_load_dwordx4 v[58:61], v[4:5], off
	v_cvt_f32_f16_sdwa v63, v49 dst_sel:DWORD dst_unused:UNUSED_PAD src0_sel:WORD_1
	v_cvt_f32_f16_sdwa v65, v48 dst_sel:DWORD dst_unused:UNUSED_PAD src0_sel:WORD_1
	v_cvt_f32_f16_e32 v64, v48
	s_and_b64 s[0:1], exec, s[0:1]
	s_waitcnt lgkmcnt(0)
	s_nop 1
	v_add_f32_dpp v57, v57, v57 quad_perm:[1,0,3,2] row_mask:0xf bank_mask:0xf bound_ctrl:1
	s_or_b64 s[6:7], s[0:1], s[6:7]
	s_waitcnt lgkmcnt(0)
	s_nop 1
	v_add_f32_dpp v57, v57, v57 quad_perm:[2,3,0,1] row_mask:0xf bank_mask:0xf bound_ctrl:1
	s_waitcnt lgkmcnt(0)
	s_nop 1
	v_add_f32_dpp v57, v57, v57 row_half_mirror row_mask:0xf bank_mask:0xf bound_ctrl:1
	s_waitcnt lgkmcnt(0)
	s_nop 1
	v_add_f32_dpp v57, v57, v57 row_mirror row_mask:0xf bank_mask:0xf bound_ctrl:1
	v_mov_b32_e32 v62, v57
	s_waitcnt lgkmcnt(0)
	s_nop 1
	v_permlane16_swap_b32_e32 v57, v62
	v_add_f32_e32 v57, v57, v62
	v_mov_b32_e32 v62, v57
	s_waitcnt lgkmcnt(0)
	s_nop 1
	v_permlane32_swap_b32_e32 v57, v62
	v_add_f32_e32 v57, v57, v62
	v_fmamk_f32 v57, v57, 0x3a000000, v56
	v_mul_f32_e32 v62, 0x4b800000, v57
	v_cmp_gt_f32_e64 s[2:3], s14, v57
	s_nop 1
	v_cndmask_b32_e64 v57, v57, v62, s[2:3]
	v_rsq_f32_e32 v57, v57
	v_cvt_f32_f16_e32 v62, v49
	v_mul_f32_e32 v48, 0x45800000, v57
	v_cndmask_b32_e64 v66, v57, v48, s[2:3]
	v_pk_mul_f32 v[48:49], v[66:67], v[64:65] op_sel_hi:[0,1]
	v_pk_mul_f32 v[62:63], v[66:67], v[62:63] op_sel_hi:[0,1]
	v_cvt_f32_f16_sdwa v65, v3 dst_sel:DWORD dst_unused:UNUSED_PAD src0_sel:WORD_1
	v_cvt_f32_f16_e32 v64, v3
	s_waitcnt vmcnt(1)
	v_mov_b32_e32 v57, v1
	v_mov_b32_e32 v3, v33
	s_waitcnt vmcnt(0)
	v_pk_mul_f32 v[60:61], v[60:61], v[62:63]
	v_pk_mul_f32 v[58:59], v[58:59], v[48:49]
	global_store_dwordx4 v[22:23], v[58:61], off offset:-4096
	global_load_dwordx4 v[58:61], v[4:5], off offset:1024
	v_cvt_f32_f16_sdwa v49, v30 dst_sel:DWORD dst_unused:UNUSED_PAD src0_sel:WORD_1
	v_cvt_f32_f16_sdwa v63, v31 dst_sel:DWORD dst_unused:UNUSED_PAD src0_sel:WORD_1
	v_cvt_f32_f16_e32 v62, v31
	v_cvt_f32_f16_e32 v48, v30
	v_pk_mul_f32 v[30:31], v[66:67], v[62:63] op_sel_hi:[0,1]
	v_pk_mul_f32 v[48:49], v[66:67], v[48:49] op_sel_hi:[0,1]
	v_cvt_f32_f16_sdwa v63, v2 dst_sel:DWORD dst_unused:UNUSED_PAD src0_sel:WORD_1
	v_cvt_f32_f16_e32 v62, v2
	v_mov_b32_e32 v2, v32
	s_waitcnt vmcnt(0)
	v_pk_mul_f32 v[58:59], v[58:59], v[48:49]
	v_pk_mul_f32 v[60:61], v[60:61], v[30:31]
	global_store_dwordx4 v[22:23], v[58:61], off offset:-3072
	global_load_dwordx4 v[58:61], v[4:5], off offset:2048
	v_cvt_f32_f16_sdwa v31, v28 dst_sel:DWORD dst_unused:UNUSED_PAD src0_sel:WORD_1
	v_cvt_f32_f16_sdwa v49, v29 dst_sel:DWORD dst_unused:UNUSED_PAD src0_sel:WORD_1
	v_cvt_f32_f16_e32 v48, v29
	v_cvt_f32_f16_e32 v30, v28
	v_pk_mul_f32 v[48:49], v[66:67], v[48:49] op_sel_hi:[0,1]
	v_pk_mul_f32 v[28:29], v[66:67], v[30:31] op_sel_hi:[0,1]
	s_waitcnt vmcnt(0)
	v_pk_mul_f32 v[28:29], v[58:59], v[28:29]
	v_pk_mul_f32 v[30:31], v[60:61], v[48:49]
	global_store_dwordx4 v[22:23], v[28:31], off offset:-2048
	global_load_dwordx4 v[28:31], v[4:5], off offset:3072
	v_cvt_f32_f16_sdwa v49, v26 dst_sel:DWORD dst_unused:UNUSED_PAD src0_sel:WORD_1
	v_cvt_f32_f16_sdwa v59, v27 dst_sel:DWORD dst_unused:UNUSED_PAD src0_sel:WORD_1
	v_cvt_f32_f16_e32 v58, v27
	v_cvt_f32_f16_e32 v48, v26
	v_pk_mul_f32 v[58:59], v[66:67], v[58:59] op_sel_hi:[0,1]
	v_pk_mul_f32 v[26:27], v[66:67], v[48:49] op_sel_hi:[0,1]
	v_cvt_f32_f16_sdwa v49, v25 dst_sel:DWORD dst_unused:UNUSED_PAD src0_sel:WORD_1
	v_cvt_f32_f16_e32 v48, v25
	v_pk_mul_f32 v[48:49], v[66:67], v[48:49] op_sel_hi:[0,1]
	s_waitcnt vmcnt(0)
	v_pk_mul_f32 v[26:27], v[28:29], v[26:27]
	v_pk_mul_f32 v[28:29], v[30:31], v[58:59]
	global_store_dwordx4 v[22:23], v[26:29], off offset:-1024
	global_load_dwordx4 v[26:29], v[10:11], off
	v_cvt_f32_f16_sdwa v31, v24 dst_sel:DWORD dst_unused:UNUSED_PAD src0_sel:WORD_1
	v_cvt_f32_f16_e32 v30, v24
	v_pk_mul_f32 v[24:25], v[66:67], v[30:31] op_sel_hi:[0,1]
	v_cvt_f32_f16_sdwa v31, v21 dst_sel:DWORD dst_unused:UNUSED_PAD src0_sel:WORD_1
	v_cvt_f32_f16_e32 v30, v21
	s_waitcnt vmcnt(0)
	v_pk_mul_f32 v[24:25], v[26:27], v[24:25]
	v_pk_mul_f32 v[26:27], v[28:29], v[48:49]
	global_store_dwordx4 v[22:23], v[24:27], off
	global_load_dwordx4 v[24:27], v[12:13], off
	v_cvt_f32_f16_sdwa v29, v20 dst_sel:DWORD dst_unused:UNUSED_PAD src0_sel:WORD_1
	v_cvt_f32_f16_e32 v28, v20
	v_pk_mul_f32 v[20:21], v[66:67], v[30:31] op_sel_hi:[0,1]
	v_mov_b32_e32 v48, v34
	v_mov_b32_e32 v49, v35
	v_pk_mul_f32 v[28:29], v[66:67], v[28:29] op_sel_hi:[0,1]
	v_mov_b32_e32 v30, v36
	v_mov_b32_e32 v31, v37
	v_pk_mul_f32 v[36:37], v[66:67], v[64:65] op_sel_hi:[0,1]
	v_pk_mul_f32 v[34:35], v[66:67], v[62:63] op_sel_hi:[0,1]
	s_waitcnt vmcnt(0)
	v_pk_mul_f32 v[24:25], v[24:25], v[28:29]
	v_pk_mul_f32 v[26:27], v[26:27], v[20:21]
	global_store_dwordx4 v[22:23], v[24:27], off offset:1024
	global_load_dwordx4 v[24:27], v[16:17], off
	v_cvt_f32_f16_sdwa v21, v14 dst_sel:DWORD dst_unused:UNUSED_PAD src0_sel:WORD_1
	v_cvt_f32_f16_sdwa v29, v15 dst_sel:DWORD dst_unused:UNUSED_PAD src0_sel:WORD_1
	v_cvt_f32_f16_e32 v28, v15
	v_cvt_f32_f16_e32 v20, v14
	v_pk_mul_f32 v[14:15], v[66:67], v[28:29] op_sel_hi:[0,1]
	v_pk_mul_f32 v[20:21], v[66:67], v[20:21] op_sel_hi:[0,1]
	v_mov_b32_e32 v28, v38
	v_mov_b32_e32 v29, v39
	s_waitcnt vmcnt(0)
	v_pk_mul_f32 v[24:25], v[20:21], v[24:25]
	v_pk_mul_f32 v[26:27], v[14:15], v[26:27]
	global_store_dwordx4 v[22:23], v[24:27], off offset:2048
	global_load_dwordx4 v[58:61], v[18:19], off
	v_mov_b32_e32 v20, v44
	v_mov_b32_e32 v26, v40
	v_mov_b32_e32 v27, v41
	v_mov_b32_e32 v24, v42
	v_mov_b32_e32 v25, v43
	v_mov_b32_e32 v21, v45
	v_mov_b32_e32 v14, v46
	v_mov_b32_e32 v15, v47
	s_waitcnt vmcnt(0)
	v_pk_mul_f32 v[34:35], v[34:35], v[58:59]
	v_pk_mul_f32 v[36:37], v[36:37], v[60:61]
	global_store_dwordx4 v[22:23], v[34:37], off offset:3072
	v_lshl_add_u64 v[22:23], v[22:23], 0, s[4:5]
	s_andn2_b64 exec, exec, s[6:7]
	s_cbranch_execz .LBB0_1473
